# k24 + three small seam trims stacked: lead-half epilogue alignment barrier after the residual loads, no vmcnt drain at quad-seam final barriers, XCC-barrier acquire invalidate dropped at 3 sites
# speedup vs baseline: 1.0015x; 1.0015x over previous
.LBB0_375:
	s_or_b64 exec, exec, s[22:23]
	s_waitcnt lgkmcnt(0)
	s_barrier
	s_branch .LBB0_432

.LBB0_675:
	s_or_b64 exec, exec, s[24:25]
	s_waitcnt lgkmcnt(0)
	s_barrier
	s_branch .LBB0_732

.LBB0_793:
	s_or_b64 exec, exec, s[40:41]
	s_waitcnt vmcnt(0)
	s_waitcnt vmcnt(0)

.LBB0_821:
	s_add_u32 s4, s79, s50
	s_addc_u32 s5, s82, s51
	s_add_u32 s46, s4, 0x9800100
	s_addc_u32 s47, s5, 0
	s_add_u32 s58, s64, s50
	s_addc_u32 s59, s83, s51
	s_add_i32 s85, 0, 0x10000
	s_cmpk_eq_i32 s50, 0x1500
	s_cselect_b32 s47, s49, s47
	s_cselect_b32 s46, s48, s46
	v_add_u32_e32 v0, s85, v134
	s_cselect_b32 s59, s71, s59
	s_cselect_b32 s58, s70, s58
	s_add_i32 s86, 0, 0x14000
	ds_read_b128 v[136:139], v0
	ds_read_b128 v[140:143], v0 offset:1024
	ds_read_b128 v[144:147], v0 offset:2048
	ds_read_b128 v[148:151], v0 offset:3072
	ds_read_b128 v[152:155], v0 offset:16384
	ds_read_b128 v[156:159], v0 offset:17408
	ds_read_b128 v[160:163], v0 offset:18432
	ds_read_b128 v[164:167], v0 offset:19456
	ds_read_b128 v[168:171], v135
	ds_read_b128 v[172:175], v135 offset:1024
	ds_read_b128 v[176:179], v135 offset:2048
	ds_read_b128 v[180:183], v135 offset:3072
	ds_read_b128 v[184:187], v135 offset:4096
	ds_read_b128 v[188:191], v135 offset:5120
	ds_read_b128 v[192:195], v135 offset:6144
	ds_read_b128 v[198:201], v135 offset:7168
	s_add_i32 m0, s60, 0xc000
	s_add_u32 s100, s4, s88
	s_addc_u32 s101, s5, s89
	global_load_lds_dwordx4 v130, s[100:101]
	s_add_i32 m0, s60, 0xe000
	s_nop 0
	global_load_lds_dwordx4 v131, s[100:101]
	s_waitcnt vmcnt(8)
	s_waitcnt lgkmcnt(0)
	s_barrier
	s_setprio 1
	s_waitcnt lgkmcnt(0)
	v_mfma_f32_16x16x32_bf16 v[126:129], v[136:139], v[168:171], v[126:129]
	v_mfma_f32_16x16x32_bf16 v[122:125], v[144:147], v[168:171], v[122:125]
	v_mfma_f32_16x16x32_bf16 v[110:113], v[136:139], v[176:179], v[110:113]
	v_mfma_f32_16x16x32_bf16 v[106:109], v[144:147], v[176:179], v[106:109]
	v_mfma_f32_16x16x32_bf16 v[94:97], v[136:139], v[184:187], v[94:97]
	v_mfma_f32_16x16x32_bf16 v[90:93], v[144:147], v[184:187], v[90:93]
	v_mfma_f32_16x16x32_bf16 v[78:81], v[136:139], v[192:195], v[78:81]
	v_mfma_f32_16x16x32_bf16 v[74:77], v[144:147], v[192:195], v[74:77]
	v_mfma_f32_16x16x32_bf16 v[126:129], v[140:143], v[172:175], v[126:129]
	v_mfma_f32_16x16x32_bf16 v[122:125], v[148:151], v[172:175], v[122:125]
	v_mfma_f32_16x16x32_bf16 v[110:113], v[140:143], v[180:183], v[110:113]
	v_mfma_f32_16x16x32_bf16 v[106:109], v[148:151], v[180:183], v[106:109]
	v_mfma_f32_16x16x32_bf16 v[94:97], v[140:143], v[188:191], v[94:97]
	v_mfma_f32_16x16x32_bf16 v[90:93], v[148:151], v[188:191], v[90:93]
	v_mfma_f32_16x16x32_bf16 v[78:81], v[140:143], v[198:201], v[78:81]
	v_mfma_f32_16x16x32_bf16 v[74:77], v[148:151], v[198:201], v[74:77]
	s_setprio 0
	s_setprio 1
	v_mfma_f32_16x16x32_bf16 v[118:121], v[152:155], v[168:171], v[118:121]
	v_mfma_f32_16x16x32_bf16 v[114:117], v[160:163], v[168:171], v[114:117]
	v_mfma_f32_16x16x32_bf16 v[102:105], v[152:155], v[176:179], v[102:105]
	v_mfma_f32_16x16x32_bf16 v[98:101], v[160:163], v[176:179], v[98:101]
	v_mfma_f32_16x16x32_bf16 v[86:89], v[152:155], v[184:187], v[86:89]
	v_mfma_f32_16x16x32_bf16 v[82:85], v[160:163], v[184:187], v[82:85]
	v_mfma_f32_16x16x32_bf16 v[70:73], v[152:155], v[192:195], v[70:73]
	v_mfma_f32_16x16x32_bf16 v[66:69], v[160:163], v[192:195], v[66:69]
	v_mfma_f32_16x16x32_bf16 v[118:121], v[156:159], v[172:175], v[118:121]
	v_mfma_f32_16x16x32_bf16 v[114:117], v[164:167], v[172:175], v[114:117]
	v_mfma_f32_16x16x32_bf16 v[102:105], v[156:159], v[180:183], v[102:105]
	v_mfma_f32_16x16x32_bf16 v[98:101], v[164:167], v[180:183], v[98:101]
	v_mfma_f32_16x16x32_bf16 v[86:89], v[156:159], v[188:191], v[86:89]
	v_mfma_f32_16x16x32_bf16 v[82:85], v[164:167], v[188:191], v[82:85]
	v_mfma_f32_16x16x32_bf16 v[70:73], v[156:159], v[198:201], v[70:73]
	v_mfma_f32_16x16x32_bf16 v[66:69], v[164:167], v[198:201], v[66:69]
	s_setprio 0
	s_barrier
	s_add_i32 s4, s85, s26
	ds_read_b128 v[168:171], v135 offset:16384
	ds_read_b128 v[172:175], v135 offset:17408
	ds_read_b128 v[176:179], v135 offset:18432
	ds_read_b128 v[180:183], v135 offset:19456
	ds_read_b128 v[184:187], v135 offset:20480
	ds_read_b128 v[188:191], v135 offset:21504
	ds_read_b128 v[192:195], v135 offset:22528
	ds_read_b128 v[198:201], v135 offset:23552
	s_mov_b32 m0, s4
	s_nop 0
	global_load_lds_dwordx4 v132, s[58:59]
	s_add_i32 m0, s4, 0x2000
	s_add_u32 s4, s58, 0xb0000
	global_load_lds_dwordx4 v133, s[58:59]
	s_addc_u32 s5, s59, 0
	s_add_i32 s85, s86, s26
	s_mov_b32 m0, s85
	s_nop 0
	global_load_lds_dwordx4 v132, s[4:5]
	s_add_i32 m0, s85, 0x2000
	s_nop 0
	global_load_lds_dwordx4 v133, s[4:5]
	s_mov_b32 m0, s60
	s_nop 0
	global_load_lds_dwordx4 v130, s[46:47]
	s_mov_b32 m0, s65
	s_nop 0
	global_load_lds_dwordx4 v131, s[46:47]
	s_waitcnt vmcnt(8)
	s_waitcnt lgkmcnt(0)
	s_barrier
	s_setprio 1
	s_waitcnt lgkmcnt(0)
	v_mfma_f32_16x16x32_bf16 v[62:65], v[136:139], v[168:171], v[62:65]
	v_mfma_f32_16x16x32_bf16 v[58:61], v[144:147], v[168:171], v[58:61]
	v_mfma_f32_16x16x32_bf16 v[46:49], v[136:139], v[176:179], v[46:49]
	v_mfma_f32_16x16x32_bf16 v[42:45], v[144:147], v[176:179], v[42:45]
	v_mfma_f32_16x16x32_bf16 v[30:33], v[136:139], v[184:187], v[30:33]
	v_mfma_f32_16x16x32_bf16 v[26:29], v[144:147], v[184:187], v[26:29]
	v_mfma_f32_16x16x32_bf16 v[14:17], v[136:139], v[192:195], v[14:17]
	v_mfma_f32_16x16x32_bf16 v[10:13], v[144:147], v[192:195], v[10:13]
	v_mfma_f32_16x16x32_bf16 v[62:65], v[140:143], v[172:175], v[62:65]
	v_mfma_f32_16x16x32_bf16 v[58:61], v[148:151], v[172:175], v[58:61]
	v_mfma_f32_16x16x32_bf16 v[46:49], v[140:143], v[180:183], v[46:49]
	v_mfma_f32_16x16x32_bf16 v[42:45], v[148:151], v[180:183], v[42:45]
	v_mfma_f32_16x16x32_bf16 v[30:33], v[140:143], v[188:191], v[30:33]
	v_mfma_f32_16x16x32_bf16 v[26:29], v[148:151], v[188:191], v[26:29]
	v_mfma_f32_16x16x32_bf16 v[14:17], v[140:143], v[198:201], v[14:17]
	v_mfma_f32_16x16x32_bf16 v[10:13], v[148:151], v[198:201], v[10:13]
	s_setprio 0
	s_setprio 1
	v_mfma_f32_16x16x32_bf16 v[54:57], v[152:155], v[168:171], v[54:57]
	v_mfma_f32_16x16x32_bf16 v[50:53], v[160:163], v[168:171], v[50:53]
	v_mfma_f32_16x16x32_bf16 v[38:41], v[152:155], v[176:179], v[38:41]
	v_mfma_f32_16x16x32_bf16 v[34:37], v[160:163], v[176:179], v[34:37]
	v_mfma_f32_16x16x32_bf16 v[22:25], v[152:155], v[184:187], v[22:25]
	v_mfma_f32_16x16x32_bf16 v[18:21], v[160:163], v[184:187], v[18:21]
	v_mfma_f32_16x16x32_bf16 v[6:9], v[152:155], v[192:195], v[6:9]
	v_mfma_f32_16x16x32_bf16 v[2:5], v[160:163], v[192:195], v[2:5]
	v_mfma_f32_16x16x32_bf16 v[54:57], v[156:159], v[172:175], v[54:57]
	v_mfma_f32_16x16x32_bf16 v[50:53], v[164:167], v[172:175], v[50:53]
	v_mfma_f32_16x16x32_bf16 v[38:41], v[156:159], v[180:183], v[38:41]
	v_mfma_f32_16x16x32_bf16 v[34:37], v[164:167], v[180:183], v[34:37]
	v_mfma_f32_16x16x32_bf16 v[22:25], v[156:159], v[188:191], v[22:25]
	v_mfma_f32_16x16x32_bf16 v[18:21], v[164:167], v[188:191], v[18:21]
	v_mfma_f32_16x16x32_bf16 v[6:9], v[156:159], v[198:201], v[6:9]
	v_mfma_f32_16x16x32_bf16 v[2:5], v[164:167], v[198:201], v[2:5]
	s_setprio 0
	s_barrier
	s_add_i32 s85, 0, 0x18000
	s_add_i32 s86, 0, 0x1c000
	ds_read_b128 v[136:139], v0 offset:32768
	ds_read_b128 v[140:143], v0 offset:33792
	ds_read_b128 v[144:147], v0 offset:34816
	ds_read_b128 v[148:151], v0 offset:35840
	ds_read_b128 v[152:155], v0 offset:49152
	ds_read_b128 v[156:159], v0 offset:50176
	ds_read_b128 v[160:163], v0 offset:51200
	ds_read_b128 v[164:167], v0 offset:52224
	s_add_u32 s4, s46, 0xb0000
	s_mov_b32 m0, s68
	ds_read_b128 v[168:171], v135 offset:32768
	ds_read_b128 v[172:175], v135 offset:33792
	ds_read_b128 v[176:179], v135 offset:34816
	ds_read_b128 v[180:183], v135 offset:35840
	ds_read_b128 v[184:187], v135 offset:36864
	ds_read_b128 v[188:191], v135 offset:37888
	ds_read_b128 v[192:195], v135 offset:38912
	ds_read_b128 v[198:201], v135 offset:39936
	s_addc_u32 s5, s47, 0
	s_nop 0
	global_load_lds_dwordx4 v130, s[4:5]
	s_mov_b32 m0, s69
	s_nop 0
	global_load_lds_dwordx4 v131, s[4:5]
	s_waitcnt vmcnt(8)
	s_waitcnt lgkmcnt(0)
	s_barrier
	s_setprio 1
	s_waitcnt lgkmcnt(0)
	v_mfma_f32_16x16x32_bf16 v[126:129], v[136:139], v[168:171], v[126:129]
	v_mfma_f32_16x16x32_bf16 v[122:125], v[144:147], v[168:171], v[122:125]
	v_mfma_f32_16x16x32_bf16 v[110:113], v[136:139], v[176:179], v[110:113]
	v_mfma_f32_16x16x32_bf16 v[106:109], v[144:147], v[176:179], v[106:109]
	v_mfma_f32_16x16x32_bf16 v[94:97], v[136:139], v[184:187], v[94:97]
	v_mfma_f32_16x16x32_bf16 v[90:93], v[144:147], v[184:187], v[90:93]
	v_mfma_f32_16x16x32_bf16 v[78:81], v[136:139], v[192:195], v[78:81]
	v_mfma_f32_16x16x32_bf16 v[74:77], v[144:147], v[192:195], v[74:77]
	v_mfma_f32_16x16x32_bf16 v[126:129], v[140:143], v[172:175], v[126:129]
	v_mfma_f32_16x16x32_bf16 v[122:125], v[148:151], v[172:175], v[122:125]
	v_mfma_f32_16x16x32_bf16 v[110:113], v[140:143], v[180:183], v[110:113]
	v_mfma_f32_16x16x32_bf16 v[106:109], v[148:151], v[180:183], v[106:109]
	v_mfma_f32_16x16x32_bf16 v[94:97], v[140:143], v[188:191], v[94:97]
	v_mfma_f32_16x16x32_bf16 v[90:93], v[148:151], v[188:191], v[90:93]
	v_mfma_f32_16x16x32_bf16 v[78:81], v[140:143], v[198:201], v[78:81]
	v_mfma_f32_16x16x32_bf16 v[74:77], v[148:151], v[198:201], v[74:77]
	s_setprio 0
	s_setprio 1
	v_mfma_f32_16x16x32_bf16 v[118:121], v[152:155], v[168:171], v[118:121]
	v_mfma_f32_16x16x32_bf16 v[114:117], v[160:163], v[168:171], v[114:117]
	v_mfma_f32_16x16x32_bf16 v[102:105], v[152:155], v[176:179], v[102:105]
	v_mfma_f32_16x16x32_bf16 v[98:101], v[160:163], v[176:179], v[98:101]
	v_mfma_f32_16x16x32_bf16 v[86:89], v[152:155], v[184:187], v[86:89]
	v_mfma_f32_16x16x32_bf16 v[82:85], v[160:163], v[184:187], v[82:85]
	v_mfma_f32_16x16x32_bf16 v[70:73], v[152:155], v[192:195], v[70:73]
	v_mfma_f32_16x16x32_bf16 v[66:69], v[160:163], v[192:195], v[66:69]
	v_mfma_f32_16x16x32_bf16 v[118:121], v[156:159], v[172:175], v[118:121]
	v_mfma_f32_16x16x32_bf16 v[114:117], v[164:167], v[172:175], v[114:117]
	v_mfma_f32_16x16x32_bf16 v[102:105], v[156:159], v[180:183], v[102:105]
	v_mfma_f32_16x16x32_bf16 v[98:101], v[164:167], v[180:183], v[98:101]
	v_mfma_f32_16x16x32_bf16 v[86:89], v[156:159], v[188:191], v[86:89]
	v_mfma_f32_16x16x32_bf16 v[82:85], v[164:167], v[188:191], v[82:85]
	v_mfma_f32_16x16x32_bf16 v[70:73], v[156:159], v[198:201], v[70:73]
	v_mfma_f32_16x16x32_bf16 v[66:69], v[164:167], v[198:201], v[66:69]
	s_setprio 0
	s_barrier
	ds_read_b128 v[168:171], v135 offset:49152
	ds_read_b128 v[172:175], v135 offset:50176
	ds_read_b128 v[176:179], v135 offset:51200
	ds_read_b128 v[180:183], v135 offset:52224
	ds_read_b128 v[184:187], v135 offset:53248
	ds_read_b128 v[188:191], v135 offset:54272
	ds_read_b128 v[192:195], v135 offset:55296
	ds_read_b128 v[198:201], v135 offset:56320
	s_add_i32 s4, s85, s26
	s_add_u32 s100, s58, s38
	s_addc_u32 s101, s59, s39
	s_mov_b32 m0, s4
	s_nop 0
	global_load_lds_dwordx4 v132, s[100:101]
	s_add_i32 m0, s4, 0x2000
	s_add_u32 s4, s58, 0xb0080
	s_addc_u32 s5, s59, 0
	s_add_i32 s58, s86, s26
	global_load_lds_dwordx4 v133, s[100:101]
	s_mov_b32 m0, s58
	s_nop 0
	global_load_lds_dwordx4 v132, s[4:5]
	s_add_i32 m0, s58, 0x2000
	s_nop 0
	global_load_lds_dwordx4 v133, s[4:5]
	s_mov_b32 m0, s75
	s_add_u32 s100, s46, s38
	s_addc_u32 s101, s47, s39
	v_mov_b32_e32 v0, v131
	global_load_lds_dwordx4 v130, s[100:101]
	s_mov_b32 m0, s78
	s_nop 0
	global_load_lds_dwordx4 v131, s[100:101]
	s_waitcnt vmcnt(8)
	s_waitcnt lgkmcnt(0)
	s_barrier
	s_setprio 1
	s_waitcnt lgkmcnt(0)
	v_mfma_f32_16x16x32_bf16 v[62:65], v[136:139], v[168:171], v[62:65]
	v_mfma_f32_16x16x32_bf16 v[58:61], v[144:147], v[168:171], v[58:61]
	v_mfma_f32_16x16x32_bf16 v[46:49], v[136:139], v[176:179], v[46:49]
	v_mfma_f32_16x16x32_bf16 v[42:45], v[144:147], v[176:179], v[42:45]
	v_mfma_f32_16x16x32_bf16 v[30:33], v[136:139], v[184:187], v[30:33]
	v_mfma_f32_16x16x32_bf16 v[26:29], v[144:147], v[184:187], v[26:29]
	v_mfma_f32_16x16x32_bf16 v[14:17], v[136:139], v[192:195], v[14:17]
	v_mfma_f32_16x16x32_bf16 v[10:13], v[144:147], v[192:195], v[10:13]
	v_mfma_f32_16x16x32_bf16 v[62:65], v[140:143], v[172:175], v[62:65]
	v_mfma_f32_16x16x32_bf16 v[58:61], v[148:151], v[172:175], v[58:61]
	v_mfma_f32_16x16x32_bf16 v[46:49], v[140:143], v[180:183], v[46:49]
	v_mfma_f32_16x16x32_bf16 v[42:45], v[148:151], v[180:183], v[42:45]
	v_mfma_f32_16x16x32_bf16 v[30:33], v[140:143], v[188:191], v[30:33]
	v_mfma_f32_16x16x32_bf16 v[26:29], v[148:151], v[188:191], v[26:29]
	v_mfma_f32_16x16x32_bf16 v[14:17], v[140:143], v[198:201], v[14:17]
	v_mfma_f32_16x16x32_bf16 v[10:13], v[148:151], v[198:201], v[10:13]
	s_setprio 0
	s_setprio 1
	v_mfma_f32_16x16x32_bf16 v[54:57], v[152:155], v[168:171], v[54:57]
	v_mfma_f32_16x16x32_bf16 v[50:53], v[160:163], v[168:171], v[50:53]
	v_mfma_f32_16x16x32_bf16 v[38:41], v[152:155], v[176:179], v[38:41]
	v_mfma_f32_16x16x32_bf16 v[34:37], v[160:163], v[176:179], v[34:37]
	v_mfma_f32_16x16x32_bf16 v[22:25], v[152:155], v[184:187], v[22:25]
	v_mfma_f32_16x16x32_bf16 v[18:21], v[160:163], v[184:187], v[18:21]
	v_mfma_f32_16x16x32_bf16 v[6:9], v[152:155], v[192:195], v[6:9]
	v_mfma_f32_16x16x32_bf16 v[2:5], v[160:163], v[192:195], v[2:5]
	v_mfma_f32_16x16x32_bf16 v[54:57], v[156:159], v[172:175], v[54:57]
	v_mfma_f32_16x16x32_bf16 v[50:53], v[164:167], v[172:175], v[50:53]
	v_mfma_f32_16x16x32_bf16 v[38:41], v[156:159], v[180:183], v[38:41]
	v_mfma_f32_16x16x32_bf16 v[34:37], v[164:167], v[180:183], v[34:37]
	v_mfma_f32_16x16x32_bf16 v[22:25], v[156:159], v[188:191], v[22:25]
	v_mfma_f32_16x16x32_bf16 v[18:21], v[164:167], v[188:191], v[18:21]
	v_mfma_f32_16x16x32_bf16 v[6:9], v[156:159], v[198:201], v[6:9]
	v_mfma_f32_16x16x32_bf16 v[2:5], v[164:167], v[198:201], v[2:5]
	s_setprio 0
	s_barrier
	s_add_i32 s84, s84, 2
	s_add_u32 s50, s50, 0x100
	s_addc_u32 s51, s51, 0
	s_cmp_gt_u32 s84, 41
	s_cbranch_scc0 .LBB0_821
.LBB0_824:
	s_lshl_b32 s4, s25, 8
	s_add_u32 s48, s12, 0x6300000
	s_addc_u32 s49, s13, 0
	s_add_i32 s4, s4, s74
	s_lshl_b32 s5, s41, 5
	s_lshl_b32 s46, s61, 2
	v_add_u32_e32 v160, s4, v196
	s_lshl_b32 s4, s61, 8
	s_or_b32 s4, s4, s5
	v_lshl_add_u32 v178, v197, 3, s4
	v_ashrrev_i32_e32 v179, 31, v178
	v_lshl_add_u64 v[130:131], v[178:179], 1, s[12:13]
	s_mov_b64 s[4:5], 0x6400000
	v_ashrrev_i32_e32 v161, 31, v160
	v_lshl_add_u64 v[180:181], v[130:131], 0, s[4:5]
	v_lshlrev_b64 v[130:131], 11, v[160:161]
	v_lshl_add_u64 v[130:131], v[180:181], 0, v[130:131]
	global_load_dwordx4 v[162:165], v[130:131], off sc1
	global_load_dwordx4 v[166:169], v[130:131], off offset:256 sc1
	v_add_u32_e32 v158, 16, v160
	v_ashrrev_i32_e32 v159, 31, v158
	v_lshlrev_b64 v[130:131], 11, v[158:159]
	v_add_u32_e32 v156, 32, v160
	v_lshl_add_u64 v[130:131], v[180:181], 0, v[130:131]
	v_ashrrev_i32_e32 v157, 31, v156
	global_load_dwordx4 v[150:153], v[130:131], off sc1
	global_load_dwordx4 v[146:149], v[130:131], off offset:256 sc1
	v_lshlrev_b64 v[130:131], 11, v[156:157]
	v_add_u32_e32 v154, 48, v160
	v_lshl_add_u64 v[130:131], v[180:181], 0, v[130:131]
	v_ashrrev_i32_e32 v155, 31, v154
	global_load_dwordx4 v[142:145], v[130:131], off sc1
	global_load_dwordx4 v[134:137], v[130:131], off offset:256 sc1
	v_lshlrev_b64 v[130:131], 11, v[154:155]
	v_lshl_add_u64 v[130:131], v[180:181], 0, v[130:131]
	global_load_dwordx4 v[138:141], v[130:131], off sc1
	s_nop 0
	global_load_dwordx4 v[130:133], v[130:131], off offset:256 sc1
	v_cmp_eq_u32_e32 vcc, 0, v197
	s_cmpk_lt_u32 s24, 0x100
	s_cbranch_scc0 .Lepi_lead_r1
	s_barrier
.Lepi_lead_r1:
	s_waitcnt vmcnt(0)
	v_lshlrev_b32_e32 v170, 16, v162
	v_and_b32_e32 v171, 0xffff0000, v162
	v_lshlrev_b32_e32 v162, 16, v163
	v_and_b32_e32 v163, 0xffff0000, v163
	v_pk_fma_f32 v[128:129], v[128:129], 0.5, v[162:163] op_sel_hi:[1,0,1]
	v_pk_fma_f32 v[126:127], v[126:127], 0.5, v[170:171] op_sel_hi:[1,0,1]
	v_lshlrev_b32_e32 v172, 16, v164
	v_and_b32_e32 v173, 0xffff0000, v164
	v_mul_f32_e32 v0, v127, v127
	v_mul_f32_e32 v162, v129, v129
	v_pk_fma_f32 v[122:123], v[122:123], 0.5, v[172:173] op_sel_hi:[1,0,1]
	v_fmac_f32_e32 v0, v126, v126
	v_fmac_f32_e32 v162, v128, v128
	v_lshlrev_b32_e32 v164, 16, v165
	v_and_b32_e32 v165, 0xffff0000, v165
	v_add_f32_e32 v0, v0, v162
	v_mul_f32_e32 v162, v123, v123
	v_pk_fma_f32 v[124:125], v[124:125], 0.5, v[164:165] op_sel_hi:[1,0,1]
	v_fmac_f32_e32 v162, v122, v122
	v_add_f32_e32 v0, v162, v0
	v_mul_f32_e32 v162, v125, v125
	v_fmac_f32_e32 v162, v124, v124
	v_add_f32_e32 v0, v162, v0
	v_lshlrev_b32_e32 v162, 16, v166
	v_and_b32_e32 v163, 0xffff0000, v166
	v_lshlrev_b32_e32 v164, 16, v167
	v_and_b32_e32 v165, 0xffff0000, v167
	v_pk_fma_f32 v[120:121], v[120:121], 0.5, v[164:165] op_sel_hi:[1,0,1]
	v_pk_fma_f32 v[118:119], v[118:119], 0.5, v[162:163] op_sel_hi:[1,0,1]
	v_lshlrev_b32_e32 v166, 16, v168
	v_and_b32_e32 v167, 0xffff0000, v168
	v_mul_f32_e32 v162, v119, v119
	v_mul_f32_e32 v163, v121, v121
	v_pk_fma_f32 v[114:115], v[114:115], 0.5, v[166:167] op_sel_hi:[1,0,1]
	v_fmac_f32_e32 v162, v118, v118
	v_fmac_f32_e32 v163, v120, v120
	v_lshlrev_b32_e32 v168, 16, v169
	v_and_b32_e32 v169, 0xffff0000, v169
	v_add_f32_e32 v162, v162, v163
	v_mul_f32_e32 v163, v115, v115
	v_pk_fma_f32 v[116:117], v[116:117], 0.5, v[168:169] op_sel_hi:[1,0,1]
	v_fmac_f32_e32 v163, v114, v114
	v_add_f32_e32 v162, v163, v162
	v_mul_f32_e32 v163, v117, v117
	v_fmac_f32_e32 v163, v116, v116
	v_add_f32_e32 v162, v163, v162
	v_add_f32_e32 v0, v0, v162
	ds_swizzle_b32 v162, v0 offset:swizzle(SWAP,16)
	v_lshlrev_b64 v[164:165], 6, v[160:161]
	v_lshl_add_u64 v[194:195], s[48:49], 0, v[164:165]
	s_waitcnt lgkmcnt(0)
	v_add_f32_e32 v0, v0, v162
	v_mov_b32_e32 v162, v0
	s_nop 1
	v_permlane32_swap_b32_e32 v0, v162
	s_and_saveexec_b64 s[24:25], vcc
	s_mov_b64 s[84:85], s[92:93]
	s_cbranch_execz .LBB0_826
	s_lshl_b32 s26, s46, 2
	v_lshl_add_u64 v[164:165], v[194:195], 0, s[26:27]
	s_lshl_b32 s26, s41, 2
	v_lshl_add_u64 v[164:165], v[164:165], 0, s[26:27]
	v_add_f32_e32 v0, v0, v162
	global_store_dword v[164:165], v0, off

.LBB0_869:
	s_add_u32 s4, s10, s2
	s_addc_u32 s5, s11, s3
	s_add_u32 s22, s4, 0x100
	s_addc_u32 s23, s5, 0
	s_add_u32 s46, s58, s2
	s_addc_u32 s47, s59, s3
	s_add_i32 s69, 0, 0x10000
	s_cmp_eq_u32 s68, 40
	s_cselect_b32 s23, s11, s23
	s_cselect_b32 s22, s10, s22
	v_add_u32_e32 v0, s69, v126
	s_cselect_b32 s47, s17, s47
	s_cselect_b32 s46, s16, s46
	s_add_i32 s70, 0, 0x14000
	ds_read_b128 v[128:131], v0
	ds_read_b128 v[142:145], v0 offset:1024
	ds_read_b128 v[146:149], v0 offset:2048
	ds_read_b128 v[150:153], v0 offset:3072
	ds_read_b128 v[154:157], v0 offset:16384
	ds_read_b128 v[160:163], v0 offset:17408
	ds_read_b128 v[164:167], v0 offset:18432
	ds_read_b128 v[168:171], v0 offset:19456
	ds_read_b128 v[172:175], v127
	ds_read_b128 v[176:179], v127 offset:1024
	ds_read_b128 v[180:183], v127 offset:2048
	ds_read_b128 v[184:187], v127 offset:3072
	ds_read_b128 v[188:191], v127 offset:4096
	ds_read_b128 v[192:195], v127 offset:5120
	ds_read_b128 v[196:199], v127 offset:6144
	ds_read_b128 v[200:203], v127 offset:7168
	s_add_i32 m0, s41, 0xc000
	s_add_u32 s100, s4, s62
	s_addc_u32 s101, s5, s63
	global_load_lds_dwordx4 v122, s[100:101]
	s_add_i32 m0, s41, 0xe000
	s_nop 0
	global_load_lds_dwordx4 v123, s[100:101]
	s_waitcnt vmcnt(8)
	s_waitcnt lgkmcnt(0)
	s_barrier
	s_setprio 1
	s_waitcnt lgkmcnt(0)
	v_mfma_f32_16x16x32_bf16 v[138:141], v[128:131], v[172:175], v[138:141]
	v_mfma_f32_16x16x32_bf16 v[132:135], v[146:149], v[172:175], v[134:137]
	v_mfma_f32_16x16x32_bf16 v[110:113], v[128:131], v[180:183], v[110:113]
	v_mfma_f32_16x16x32_bf16 v[106:109], v[146:149], v[180:183], v[106:109]
	v_mfma_f32_16x16x32_bf16 v[94:97], v[128:131], v[188:191], v[94:97]
	v_mfma_f32_16x16x32_bf16 v[90:93], v[146:149], v[188:191], v[90:93]
	v_mfma_f32_16x16x32_bf16 v[78:81], v[128:131], v[196:199], v[78:81]
	v_mfma_f32_16x16x32_bf16 v[74:77], v[146:149], v[196:199], v[74:77]
	v_mfma_f32_16x16x32_bf16 v[138:141], v[142:145], v[176:179], v[138:141]
	v_mfma_f32_16x16x32_bf16 v[132:135], v[150:153], v[176:179], v[132:135]
	v_mfma_f32_16x16x32_bf16 v[110:113], v[142:145], v[184:187], v[110:113]
	v_mfma_f32_16x16x32_bf16 v[106:109], v[150:153], v[184:187], v[106:109]
	v_mfma_f32_16x16x32_bf16 v[94:97], v[142:145], v[192:195], v[94:97]
	v_mfma_f32_16x16x32_bf16 v[90:93], v[150:153], v[192:195], v[90:93]
	v_mfma_f32_16x16x32_bf16 v[78:81], v[142:145], v[200:203], v[78:81]
	v_mfma_f32_16x16x32_bf16 v[74:77], v[150:153], v[200:203], v[74:77]
	s_setprio 0
	s_setprio 1
	v_mfma_f32_16x16x32_bf16 v[118:121], v[154:157], v[172:175], v[118:121]
	v_mfma_f32_16x16x32_bf16 v[114:117], v[164:167], v[172:175], v[114:117]
	v_mfma_f32_16x16x32_bf16 v[102:105], v[154:157], v[180:183], v[102:105]
	v_mfma_f32_16x16x32_bf16 v[98:101], v[164:167], v[180:183], v[98:101]
	v_mfma_f32_16x16x32_bf16 v[86:89], v[154:157], v[188:191], v[86:89]
	v_mfma_f32_16x16x32_bf16 v[82:85], v[164:167], v[188:191], v[82:85]
	v_mfma_f32_16x16x32_bf16 v[70:73], v[154:157], v[196:199], v[70:73]
	v_mfma_f32_16x16x32_bf16 v[66:69], v[164:167], v[196:199], v[66:69]
	v_mfma_f32_16x16x32_bf16 v[118:121], v[160:163], v[176:179], v[118:121]
	v_mfma_f32_16x16x32_bf16 v[114:117], v[168:171], v[176:179], v[114:117]
	v_mfma_f32_16x16x32_bf16 v[102:105], v[160:163], v[184:187], v[102:105]
	v_mfma_f32_16x16x32_bf16 v[98:101], v[168:171], v[184:187], v[98:101]
	v_mfma_f32_16x16x32_bf16 v[86:89], v[160:163], v[192:195], v[86:89]
	v_mfma_f32_16x16x32_bf16 v[82:85], v[168:171], v[192:195], v[82:85]
	v_mfma_f32_16x16x32_bf16 v[70:73], v[160:163], v[200:203], v[70:73]
	v_mfma_f32_16x16x32_bf16 v[66:69], v[168:171], v[200:203], v[66:69]
	s_setprio 0
	s_barrier
	s_add_i32 s4, s69, s26
	ds_read_b128 v[172:175], v127 offset:16384
	ds_read_b128 v[176:179], v127 offset:17408
	ds_read_b128 v[180:183], v127 offset:18432
	ds_read_b128 v[184:187], v127 offset:19456
	ds_read_b128 v[188:191], v127 offset:20480
	ds_read_b128 v[192:195], v127 offset:21504
	ds_read_b128 v[196:199], v127 offset:22528
	ds_read_b128 v[200:203], v127 offset:23552
	s_mov_b32 m0, s4
	s_nop 0
	global_load_lds_dwordx4 v124, s[46:47]
	s_add_i32 m0, s4, 0x2000
	s_add_u32 s4, s46, 0xb0000
	global_load_lds_dwordx4 v125, s[46:47]
	s_addc_u32 s5, s47, 0
	s_add_i32 s69, s70, s26
	s_mov_b32 m0, s69
	s_nop 0
	global_load_lds_dwordx4 v124, s[4:5]
	s_add_i32 m0, s69, 0x2000
	s_nop 0
	global_load_lds_dwordx4 v125, s[4:5]
	s_mov_b32 m0, s41
	s_nop 0
	global_load_lds_dwordx4 v122, s[22:23]
	s_mov_b32 m0, s48
	s_nop 0
	global_load_lds_dwordx4 v123, s[22:23]
	s_waitcnt vmcnt(8)
	s_waitcnt lgkmcnt(0)
	s_barrier
	s_setprio 1
	s_waitcnt lgkmcnt(0)
	v_mfma_f32_16x16x32_bf16 v[62:65], v[128:131], v[172:175], v[62:65]
	v_mfma_f32_16x16x32_bf16 v[58:61], v[146:149], v[172:175], v[58:61]
	v_mfma_f32_16x16x32_bf16 v[46:49], v[128:131], v[180:183], v[46:49]
	v_mfma_f32_16x16x32_bf16 v[42:45], v[146:149], v[180:183], v[42:45]
	v_mfma_f32_16x16x32_bf16 v[30:33], v[128:131], v[188:191], v[30:33]
	v_mfma_f32_16x16x32_bf16 v[26:29], v[146:149], v[188:191], v[26:29]
	v_mfma_f32_16x16x32_bf16 v[14:17], v[128:131], v[196:199], v[14:17]
	v_mfma_f32_16x16x32_bf16 v[10:13], v[146:149], v[196:199], v[10:13]
	v_mfma_f32_16x16x32_bf16 v[62:65], v[142:145], v[176:179], v[62:65]
	v_mfma_f32_16x16x32_bf16 v[58:61], v[150:153], v[176:179], v[58:61]
	v_mfma_f32_16x16x32_bf16 v[46:49], v[142:145], v[184:187], v[46:49]
	v_mfma_f32_16x16x32_bf16 v[42:45], v[150:153], v[184:187], v[42:45]
	v_mfma_f32_16x16x32_bf16 v[30:33], v[142:145], v[192:195], v[30:33]
	v_mfma_f32_16x16x32_bf16 v[26:29], v[150:153], v[192:195], v[26:29]
	v_mfma_f32_16x16x32_bf16 v[14:17], v[142:145], v[200:203], v[14:17]
	v_mfma_f32_16x16x32_bf16 v[10:13], v[150:153], v[200:203], v[10:13]
	s_setprio 0
	s_setprio 1
	v_mfma_f32_16x16x32_bf16 v[54:57], v[154:157], v[172:175], v[54:57]
	v_mfma_f32_16x16x32_bf16 v[50:53], v[164:167], v[172:175], v[50:53]
	v_mfma_f32_16x16x32_bf16 v[38:41], v[154:157], v[180:183], v[38:41]
	v_mfma_f32_16x16x32_bf16 v[34:37], v[164:167], v[180:183], v[34:37]
	v_mfma_f32_16x16x32_bf16 v[22:25], v[154:157], v[188:191], v[22:25]
	v_mfma_f32_16x16x32_bf16 v[18:21], v[164:167], v[188:191], v[18:21]
	v_mfma_f32_16x16x32_bf16 v[6:9], v[154:157], v[196:199], v[6:9]
	v_mfma_f32_16x16x32_bf16 v[2:5], v[164:167], v[196:199], v[2:5]
	v_mfma_f32_16x16x32_bf16 v[54:57], v[160:163], v[176:179], v[54:57]
	v_mfma_f32_16x16x32_bf16 v[50:53], v[168:171], v[176:179], v[50:53]
	v_mfma_f32_16x16x32_bf16 v[38:41], v[160:163], v[184:187], v[38:41]
	v_mfma_f32_16x16x32_bf16 v[34:37], v[168:171], v[184:187], v[34:37]
	v_mfma_f32_16x16x32_bf16 v[22:25], v[160:163], v[192:195], v[22:25]
	v_mfma_f32_16x16x32_bf16 v[18:21], v[168:171], v[192:195], v[18:21]
	v_mfma_f32_16x16x32_bf16 v[6:9], v[160:163], v[200:203], v[6:9]
	v_mfma_f32_16x16x32_bf16 v[2:5], v[168:171], v[200:203], v[2:5]
	s_setprio 0
	s_barrier
	s_add_i32 s69, 0, 0x18000
	s_add_i32 s70, 0, 0x1c000
	ds_read_b128 v[128:131], v0 offset:32768
	ds_read_b128 v[142:145], v0 offset:33792
	ds_read_b128 v[146:149], v0 offset:34816
	ds_read_b128 v[150:153], v0 offset:35840
	ds_read_b128 v[154:157], v0 offset:49152
	ds_read_b128 v[160:163], v0 offset:50176
	ds_read_b128 v[164:167], v0 offset:51200
	ds_read_b128 v[168:171], v0 offset:52224
	s_add_u32 s4, s22, 0xb0000
	s_mov_b32 m0, s49
	ds_read_b128 v[172:175], v127 offset:32768
	ds_read_b128 v[176:179], v127 offset:33792
	ds_read_b128 v[180:183], v127 offset:34816
	ds_read_b128 v[184:187], v127 offset:35840
	ds_read_b128 v[188:191], v127 offset:36864
	ds_read_b128 v[192:195], v127 offset:37888
	ds_read_b128 v[196:199], v127 offset:38912
	ds_read_b128 v[200:203], v127 offset:39936
	s_addc_u32 s5, s23, 0
	s_nop 0
	global_load_lds_dwordx4 v122, s[4:5]
	s_mov_b32 m0, s50
	s_nop 0
	global_load_lds_dwordx4 v123, s[4:5]
	s_waitcnt vmcnt(8)
	s_waitcnt lgkmcnt(0)
	s_barrier
	s_setprio 1
	s_waitcnt lgkmcnt(0)
	v_mfma_f32_16x16x32_bf16 v[136:139], v[128:131], v[172:175], v[138:141]
	v_mfma_f32_16x16x32_bf16 v[132:135], v[146:149], v[172:175], v[132:135]
	v_mfma_f32_16x16x32_bf16 v[110:113], v[128:131], v[180:183], v[110:113]
	v_mfma_f32_16x16x32_bf16 v[106:109], v[146:149], v[180:183], v[106:109]
	v_mfma_f32_16x16x32_bf16 v[94:97], v[128:131], v[188:191], v[94:97]
	v_mfma_f32_16x16x32_bf16 v[90:93], v[146:149], v[188:191], v[90:93]
	v_mfma_f32_16x16x32_bf16 v[78:81], v[128:131], v[196:199], v[78:81]
	v_mfma_f32_16x16x32_bf16 v[74:77], v[146:149], v[196:199], v[74:77]
	v_mfma_f32_16x16x32_bf16 v[138:141], v[142:145], v[176:179], v[136:139]
	v_mfma_f32_16x16x32_bf16 v[134:137], v[150:153], v[176:179], v[132:135]
	v_mfma_f32_16x16x32_bf16 v[110:113], v[142:145], v[184:187], v[110:113]
	v_mfma_f32_16x16x32_bf16 v[106:109], v[150:153], v[184:187], v[106:109]
	v_mfma_f32_16x16x32_bf16 v[94:97], v[142:145], v[192:195], v[94:97]
	v_mfma_f32_16x16x32_bf16 v[90:93], v[150:153], v[192:195], v[90:93]
	v_mfma_f32_16x16x32_bf16 v[78:81], v[142:145], v[200:203], v[78:81]
	v_mfma_f32_16x16x32_bf16 v[74:77], v[150:153], v[200:203], v[74:77]
	s_setprio 0
	s_setprio 1
	v_mfma_f32_16x16x32_bf16 v[118:121], v[154:157], v[172:175], v[118:121]
	v_mfma_f32_16x16x32_bf16 v[114:117], v[164:167], v[172:175], v[114:117]
	v_mfma_f32_16x16x32_bf16 v[102:105], v[154:157], v[180:183], v[102:105]
	v_mfma_f32_16x16x32_bf16 v[98:101], v[164:167], v[180:183], v[98:101]
	v_mfma_f32_16x16x32_bf16 v[86:89], v[154:157], v[188:191], v[86:89]
	v_mfma_f32_16x16x32_bf16 v[82:85], v[164:167], v[188:191], v[82:85]
	v_mfma_f32_16x16x32_bf16 v[70:73], v[154:157], v[196:199], v[70:73]
	v_mfma_f32_16x16x32_bf16 v[66:69], v[164:167], v[196:199], v[66:69]
	v_mfma_f32_16x16x32_bf16 v[118:121], v[160:163], v[176:179], v[118:121]
	v_mfma_f32_16x16x32_bf16 v[114:117], v[168:171], v[176:179], v[114:117]
	v_mfma_f32_16x16x32_bf16 v[102:105], v[160:163], v[184:187], v[102:105]
	v_mfma_f32_16x16x32_bf16 v[98:101], v[168:171], v[184:187], v[98:101]
	v_mfma_f32_16x16x32_bf16 v[86:89], v[160:163], v[192:195], v[86:89]
	v_mfma_f32_16x16x32_bf16 v[82:85], v[168:171], v[192:195], v[82:85]
	v_mfma_f32_16x16x32_bf16 v[70:73], v[160:163], v[200:203], v[70:73]
	v_mfma_f32_16x16x32_bf16 v[66:69], v[168:171], v[200:203], v[66:69]
	s_setprio 0
	s_barrier
	ds_read_b128 v[172:175], v127 offset:49152
	ds_read_b128 v[176:179], v127 offset:50176
	ds_read_b128 v[180:183], v127 offset:51200
	ds_read_b128 v[184:187], v127 offset:52224
	ds_read_b128 v[188:191], v127 offset:53248
	ds_read_b128 v[192:195], v127 offset:54272
	ds_read_b128 v[196:199], v127 offset:55296
	ds_read_b128 v[200:203], v127 offset:56320
	s_add_i32 s4, s69, s26
	s_add_u32 s100, s46, s38
	s_addc_u32 s101, s47, s39
	s_mov_b32 m0, s4
	s_nop 0
	global_load_lds_dwordx4 v124, s[100:101]
	s_add_i32 m0, s4, 0x2000
	s_add_u32 s4, s46, 0xb0080
	s_addc_u32 s5, s47, 0
	s_add_i32 s46, s70, s26
	global_load_lds_dwordx4 v125, s[100:101]
	s_mov_b32 m0, s46
	s_nop 0
	global_load_lds_dwordx4 v124, s[4:5]
	s_add_i32 m0, s46, 0x2000
	s_nop 0
	global_load_lds_dwordx4 v125, s[4:5]
	s_mov_b32 m0, s64
	s_add_u32 s100, s22, s38
	s_addc_u32 s101, s23, s39
	v_mov_b32_e32 v0, v123
	global_load_lds_dwordx4 v122, s[100:101]
	s_mov_b32 m0, s65
	s_nop 0
	global_load_lds_dwordx4 v123, s[100:101]
	s_waitcnt vmcnt(8)
	s_waitcnt lgkmcnt(0)
	s_barrier
	s_setprio 1
	s_waitcnt lgkmcnt(0)
	v_mfma_f32_16x16x32_bf16 v[62:65], v[128:131], v[172:175], v[62:65]
	v_mfma_f32_16x16x32_bf16 v[58:61], v[146:149], v[172:175], v[58:61]
	v_mfma_f32_16x16x32_bf16 v[46:49], v[128:131], v[180:183], v[46:49]
	v_mfma_f32_16x16x32_bf16 v[42:45], v[146:149], v[180:183], v[42:45]
	v_mfma_f32_16x16x32_bf16 v[30:33], v[128:131], v[188:191], v[30:33]
	v_mfma_f32_16x16x32_bf16 v[26:29], v[146:149], v[188:191], v[26:29]
	v_mfma_f32_16x16x32_bf16 v[14:17], v[128:131], v[196:199], v[14:17]
	v_mfma_f32_16x16x32_bf16 v[10:13], v[146:149], v[196:199], v[10:13]
	v_mfma_f32_16x16x32_bf16 v[62:65], v[142:145], v[176:179], v[62:65]
	v_mfma_f32_16x16x32_bf16 v[58:61], v[150:153], v[176:179], v[58:61]
	v_mfma_f32_16x16x32_bf16 v[46:49], v[142:145], v[184:187], v[46:49]
	v_mfma_f32_16x16x32_bf16 v[42:45], v[150:153], v[184:187], v[42:45]
	v_mfma_f32_16x16x32_bf16 v[30:33], v[142:145], v[192:195], v[30:33]
	v_mfma_f32_16x16x32_bf16 v[26:29], v[150:153], v[192:195], v[26:29]
	v_mfma_f32_16x16x32_bf16 v[14:17], v[142:145], v[200:203], v[14:17]
	v_mfma_f32_16x16x32_bf16 v[10:13], v[150:153], v[200:203], v[10:13]
	s_setprio 0
	s_setprio 1
	v_mfma_f32_16x16x32_bf16 v[54:57], v[154:157], v[172:175], v[54:57]
	v_mfma_f32_16x16x32_bf16 v[50:53], v[164:167], v[172:175], v[50:53]
	v_mfma_f32_16x16x32_bf16 v[38:41], v[154:157], v[180:183], v[38:41]
	v_mfma_f32_16x16x32_bf16 v[34:37], v[164:167], v[180:183], v[34:37]
	v_mfma_f32_16x16x32_bf16 v[22:25], v[154:157], v[188:191], v[22:25]
	v_mfma_f32_16x16x32_bf16 v[18:21], v[164:167], v[188:191], v[18:21]
	v_mfma_f32_16x16x32_bf16 v[6:9], v[154:157], v[196:199], v[6:9]
	v_mfma_f32_16x16x32_bf16 v[2:5], v[164:167], v[196:199], v[2:5]
	v_mfma_f32_16x16x32_bf16 v[54:57], v[160:163], v[176:179], v[54:57]
	v_mfma_f32_16x16x32_bf16 v[50:53], v[168:171], v[176:179], v[50:53]
	v_mfma_f32_16x16x32_bf16 v[38:41], v[160:163], v[184:187], v[38:41]
	v_mfma_f32_16x16x32_bf16 v[34:37], v[168:171], v[184:187], v[34:37]
	v_mfma_f32_16x16x32_bf16 v[22:25], v[160:163], v[192:195], v[22:25]
	v_mfma_f32_16x16x32_bf16 v[18:21], v[168:171], v[192:195], v[18:21]
	v_mfma_f32_16x16x32_bf16 v[6:9], v[160:163], v[200:203], v[6:9]
	v_mfma_f32_16x16x32_bf16 v[2:5], v[168:171], v[200:203], v[2:5]
	s_setprio 0
	s_barrier
	s_add_i32 s68, s68, 2
	s_add_u32 s2, s2, 0x100
	s_addc_u32 s3, s3, 0
	s_cmp_gt_u32 s68, 41
	s_cbranch_scc0 .LBB0_869
.LBB0_872:
	s_add_u32 s22, s12, 0x6400000
	s_addc_u32 s23, s13, 0
	s_add_u32 s10, s12, 0x6300000
	s_addc_u32 s11, s13, 0
	s_add_u32 s16, s12, 0xfa00000
	s_addc_u32 s17, s13, 0
	s_add_i32 s3, s24, s51
	s_lshl_b32 s2, s61, 5
	s_nop 0
	v_add_u32_e32 v166, s3, v159
	s_lshl_b32 s3, s60, 8
	s_or_b32 s2, s3, s2
	v_lshl_add_u32 v168, v158, 3, s2
	v_ashrrev_i32_e32 v169, 31, v168
	v_lshlrev_b64 v[180:181], 1, v[168:169]
	v_ashrrev_i32_e32 v167, 31, v166
	v_lshl_add_u64 v[184:185], s[22:23], 0, v[180:181]
	v_lshlrev_b64 v[182:183], 11, v[166:167]
	v_lshl_add_u64 v[122:123], v[184:185], 0, v[182:183]
	global_load_dwordx4 v[176:179], v[122:123], off sc1
	global_load_dwordx4 v[154:157], v[122:123], off offset:256 sc1
	v_add_u32_e32 v164, 16, v166
	v_ashrrev_i32_e32 v165, 31, v164
	v_add_u32_e32 v162, 32, v166
	v_lshlrev_b64 v[172:173], 11, v[164:165]
	v_ashrrev_i32_e32 v163, 31, v162
	v_add_u32_e32 v160, 48, v166
	v_lshl_add_u64 v[122:123], v[184:185], 0, v[172:173]
	v_lshlrev_b64 v[170:171], 11, v[162:163]
	v_ashrrev_i32_e32 v161, 31, v160
	global_load_dwordx4 v[150:153], v[122:123], off sc1
	global_load_dwordx4 v[146:149], v[122:123], off offset:256 sc1
	v_lshl_add_u64 v[122:123], v[184:185], 0, v[170:171]
	v_lshlrev_b64 v[174:175], 11, v[160:161]
	global_load_dwordx4 v[142:145], v[122:123], off sc1
	global_load_dwordx4 v[130:133], v[122:123], off offset:256 sc1
	v_lshl_add_u64 v[122:123], v[184:185], 0, v[174:175]
	global_load_dwordx4 v[126:129], v[122:123], off sc1
	s_nop 0
	global_load_dwordx4 v[122:125], v[122:123], off offset:256 sc1
	v_cmp_eq_u32_e64 s[2:3], 0, v158
	s_cmpk_lt_u32 s25, 0x100
	s_cbranch_scc0 .Lepi_lead_r2
	s_barrier
.Lepi_lead_r2:
	s_waitcnt vmcnt(0)
	v_lshlrev_b32_e32 v186, 16, v176
	v_and_b32_e32 v187, 0xffff0000, v176
	v_lshlrev_b32_e32 v176, 16, v177
	v_and_b32_e32 v177, 0xffff0000, v177
	v_pk_fma_f32 v[140:141], v[140:141], 0.5, v[176:177] op_sel_hi:[1,0,1]
	v_lshl_add_u64 v[176:177], s[22:23], 0, v[182:183]
	v_lshlrev_b32_e32 v188, 16, v178
	v_and_b32_e32 v189, 0xffff0000, v178
	v_lshlrev_b32_e32 v178, 16, v179
	v_and_b32_e32 v179, 0xffff0000, v179
	v_pk_fma_f32 v[138:139], v[138:139], 0.5, v[186:187] op_sel_hi:[1,0,1]
	v_lshl_add_u64 v[180:181], v[176:177], 0, v[180:181]
	v_cvt_pk_bf16_f32 v176, v138, v139
	v_pk_fma_f32 v[136:137], v[136:137], 0.5, v[178:179] op_sel_hi:[1,0,1]
	v_pk_fma_f32 v[134:135], v[134:135], 0.5, v[188:189] op_sel_hi:[1,0,1]
	v_cvt_pk_bf16_f32 v177, v140, v141
	v_mul_f32_e32 v0, v139, v139
	v_cvt_pk_bf16_f32 v178, v134, v135
	v_cvt_pk_bf16_f32 v179, v136, v137
	global_store_dwordx4 v[180:181], v[176:179], off
	v_fmac_f32_e32 v0, v138, v138
	s_nop 0
	v_mul_f32_e32 v176, v141, v141
	v_fmac_f32_e32 v176, v140, v140
	v_add_f32_e32 v0, v0, v176
	v_mul_f32_e32 v176, v135, v135
	v_fmac_f32_e32 v176, v134, v134
	v_add_f32_e32 v0, v176, v0
	v_mul_f32_e32 v176, v137, v137
	v_fmac_f32_e32 v176, v136, v136
	v_add_f32_e32 v0, v176, v0
	v_max_f32_e64 v176, |v138|, |v139|
	v_max_f32_e64 v177, |v140|, |v141|
	v_max3_f32 v182, v176, 0, v177
	v_max_f32_e64 v176, |v136|, |v137|
	v_max3_f32 v183, |v134|, |v135|, v176
	v_lshlrev_b32_e32 v176, 16, v154
	v_and_b32_e32 v177, 0xffff0000, v154
	v_lshlrev_b32_e32 v154, 16, v155
	v_and_b32_e32 v155, 0xffff0000, v155
	v_lshlrev_b32_e32 v178, 16, v156
	v_and_b32_e32 v179, 0xffff0000, v156
	v_lshlrev_b32_e32 v156, 16, v157
	v_and_b32_e32 v157, 0xffff0000, v157
	v_pk_fma_f32 v[120:121], v[120:121], 0.5, v[154:155] op_sel_hi:[1,0,1]
	v_pk_fma_f32 v[118:119], v[118:119], 0.5, v[176:177] op_sel_hi:[1,0,1]
	v_pk_fma_f32 v[116:117], v[116:117], 0.5, v[156:157] op_sel_hi:[1,0,1]
	v_cvt_pk_bf16_f32 v154, v118, v119
	v_cvt_pk_bf16_f32 v155, v120, v121
	v_pk_fma_f32 v[114:115], v[114:115], 0.5, v[178:179] op_sel_hi:[1,0,1]
	v_lshlrev_b64 v[178:179], 6, v[166:167]
	v_cvt_pk_bf16_f32 v156, v114, v115
	v_cvt_pk_bf16_f32 v157, v116, v117
	global_store_dwordx4 v[180:181], v[154:157], off offset:256
	s_nop 1
	v_mul_f32_e32 v154, v119, v119
	v_mul_f32_e32 v155, v121, v121
	v_fmac_f32_e32 v154, v118, v118
	v_fmac_f32_e32 v155, v120, v120
	v_add_f32_e32 v154, v154, v155
	v_mul_f32_e32 v155, v115, v115
	v_fmac_f32_e32 v155, v114, v114
	v_add_f32_e32 v154, v155, v154
	v_mul_f32_e32 v155, v117, v117
	v_fmac_f32_e32 v155, v116, v116
	v_add_f32_e32 v154, v155, v154
	v_add_f32_e32 v0, v0, v154
	v_max_f32_e64 v154, |v118|, |v119|
	v_max_f32_e64 v156, |v116|, |v117|
	v_max3_f32 v154, v182, v183, v154
	v_max_f32_e64 v155, |v120|, |v121|
	v_max3_f32 v156, |v114|, |v115|, v156
	v_max3_f32 v155, v154, v155, v156
	ds_swizzle_b32 v156, v155 offset:swizzle(SWAP,16)
	ds_swizzle_b32 v154, v0 offset:swizzle(SWAP,16)
	s_waitcnt lgkmcnt(1)
	v_max_f32_e32 v156, v156, v156
	s_waitcnt lgkmcnt(0)
	v_add_f32_e32 v0, v0, v154
	v_max_f32_e32 v155, v155, v156
	v_mov_b32_e32 v154, v0
	v_mov_b32_e32 v156, v155
	s_nop 0
	v_permlane32_swap_b32_e32 v0, v154
	v_permlane32_swap_b32_e32 v155, v156
	s_and_saveexec_b64 s[24:25], s[2:3]
	s_cbranch_execz .LBB0_874
	s_lshl_b32 s4, s60, 2
	v_max_f32_e32 v155, v155, v155
	v_max_f32_e32 v156, v156, v156
	s_ashr_i32 s5, s4, 31
	v_max_f32_e32 v156, v155, v156
	v_add_f32_e32 v0, v0, v154
	v_lshl_add_u64 v[154:155], s[10:11], 0, v[178:179]
	s_lshl_b64 s[4:5], s[4:5], 2
	v_lshl_add_u64 v[154:155], v[154:155], 0, s[4:5]
	s_lshl_b32 s26, s61, 2
	v_lshl_add_u64 v[154:155], v[154:155], 0, s[26:27]
	global_store_dword v[154:155], v0, off
	v_lshl_add_u64 v[154:155], s[16:17], 0, v[178:179]
	v_lshl_add_u64 v[154:155], v[154:155], 0, s[4:5]
	v_lshl_add_u64 v[154:155], v[154:155], 0, s[26:27]
	global_store_dword v[154:155], v156, off

.LBB0_953:
	s_add_u32 s58, s4, s2
	s_addc_u32 s59, s5, s3
	s_add_u32 s14, s58, 0x100
	s_addc_u32 s15, s59, 0
	s_add_u32 s16, s43, s2
	s_addc_u32 s17, s46, s3
	s_add_i32 s51, 0, 0x10000
	s_cmp_eq_u32 s50, 40
	s_cselect_b32 s15, s5, s15
	s_cselect_b32 s14, s4, s14
	v_add_u32_e32 v0, s51, v135
	s_cselect_b32 s17, s7, s17
	s_cselect_b32 s16, s6, s16
	s_add_i32 s60, 0, 0x14000
	ds_read_b128 v[138:141], v0
	ds_read_b128 v[142:145], v0 offset:1024
	ds_read_b128 v[146:149], v0 offset:2048
	ds_read_b128 v[150:153], v0 offset:3072
	ds_read_b128 v[154:157], v0 offset:16384
	ds_read_b128 v[158:161], v0 offset:17408
	ds_read_b128 v[162:165], v0 offset:18432
	ds_read_b128 v[166:169], v0 offset:19456
	ds_read_b128 v[170:173], v136
	ds_read_b128 v[174:177], v136 offset:1024
	ds_read_b128 v[178:181], v136 offset:2048
	ds_read_b128 v[182:185], v136 offset:3072
	ds_read_b128 v[186:189], v136 offset:4096
	ds_read_b128 v[190:193], v136 offset:5120
	ds_read_b128 v[194:197], v136 offset:6144
	ds_read_b128 v[198:201], v136 offset:7168
	s_add_i32 m0, s37, 0xc000
	s_add_u32 s100, s58, s62
	s_addc_u32 s101, s59, s63
	global_load_lds_dwordx4 v130, s[100:101]
	s_add_i32 m0, s37, 0xe000
	s_nop 0
	global_load_lds_dwordx4 v131, s[100:101]
	s_waitcnt vmcnt(8)
	s_waitcnt lgkmcnt(0)
	s_barrier
	s_setprio 1
	s_waitcnt lgkmcnt(0)
	v_mfma_f32_16x16x32_bf16 v[126:129], v[138:141], v[170:173], v[126:129]
	v_mfma_f32_16x16x32_bf16 v[122:125], v[146:149], v[170:173], v[122:125]
	v_mfma_f32_16x16x32_bf16 v[110:113], v[138:141], v[178:181], v[110:113]
	v_mfma_f32_16x16x32_bf16 v[106:109], v[146:149], v[178:181], v[106:109]
	v_mfma_f32_16x16x32_bf16 v[94:97], v[138:141], v[186:189], v[94:97]
	v_mfma_f32_16x16x32_bf16 v[90:93], v[146:149], v[186:189], v[90:93]
	v_mfma_f32_16x16x32_bf16 v[78:81], v[138:141], v[194:197], v[78:81]
	v_mfma_f32_16x16x32_bf16 v[74:77], v[146:149], v[194:197], v[74:77]
	v_mfma_f32_16x16x32_bf16 v[126:129], v[142:145], v[174:177], v[126:129]
	v_mfma_f32_16x16x32_bf16 v[122:125], v[150:153], v[174:177], v[122:125]
	v_mfma_f32_16x16x32_bf16 v[110:113], v[142:145], v[182:185], v[110:113]
	v_mfma_f32_16x16x32_bf16 v[106:109], v[150:153], v[182:185], v[106:109]
	v_mfma_f32_16x16x32_bf16 v[94:97], v[142:145], v[190:193], v[94:97]
	v_mfma_f32_16x16x32_bf16 v[90:93], v[150:153], v[190:193], v[90:93]
	v_mfma_f32_16x16x32_bf16 v[78:81], v[142:145], v[198:201], v[78:81]
	v_mfma_f32_16x16x32_bf16 v[74:77], v[150:153], v[198:201], v[74:77]
	s_setprio 0
	s_setprio 1
	v_mfma_f32_16x16x32_bf16 v[118:121], v[154:157], v[170:173], v[118:121]
	v_mfma_f32_16x16x32_bf16 v[114:117], v[162:165], v[170:173], v[114:117]
	v_mfma_f32_16x16x32_bf16 v[102:105], v[154:157], v[178:181], v[102:105]
	v_mfma_f32_16x16x32_bf16 v[98:101], v[162:165], v[178:181], v[98:101]
	v_mfma_f32_16x16x32_bf16 v[86:89], v[154:157], v[186:189], v[86:89]
	v_mfma_f32_16x16x32_bf16 v[82:85], v[162:165], v[186:189], v[82:85]
	v_mfma_f32_16x16x32_bf16 v[70:73], v[154:157], v[194:197], v[70:73]
	v_mfma_f32_16x16x32_bf16 v[66:69], v[162:165], v[194:197], v[66:69]
	v_mfma_f32_16x16x32_bf16 v[118:121], v[158:161], v[174:177], v[118:121]
	v_mfma_f32_16x16x32_bf16 v[114:117], v[166:169], v[174:177], v[114:117]
	v_mfma_f32_16x16x32_bf16 v[102:105], v[158:161], v[182:185], v[102:105]
	v_mfma_f32_16x16x32_bf16 v[98:101], v[166:169], v[182:185], v[98:101]
	v_mfma_f32_16x16x32_bf16 v[86:89], v[158:161], v[190:193], v[86:89]
	v_mfma_f32_16x16x32_bf16 v[82:85], v[166:169], v[190:193], v[82:85]
	v_mfma_f32_16x16x32_bf16 v[70:73], v[158:161], v[198:201], v[70:73]
	v_mfma_f32_16x16x32_bf16 v[66:69], v[166:169], v[198:201], v[66:69]
	s_setprio 0
	s_barrier
	s_add_i32 s51, s51, s26
	ds_read_b128 v[170:173], v136 offset:16384
	ds_read_b128 v[174:177], v136 offset:17408
	ds_read_b128 v[178:181], v136 offset:18432
	ds_read_b128 v[182:185], v136 offset:19456
	ds_read_b128 v[186:189], v136 offset:20480
	ds_read_b128 v[190:193], v136 offset:21504
	ds_read_b128 v[194:197], v136 offset:22528
	ds_read_b128 v[198:201], v136 offset:23552
	s_mov_b32 m0, s51
	s_nop 0
	global_load_lds_dwordx4 v133, s[16:17]
	s_add_i32 m0, s51, 0x2000
	s_add_u32 s58, s16, 0xb0000
	global_load_lds_dwordx4 v134, s[16:17]
	s_addc_u32 s59, s17, 0
	s_add_i32 s51, s60, s26
	s_mov_b32 m0, s51
	s_nop 0
	global_load_lds_dwordx4 v133, s[58:59]
	s_add_i32 m0, s51, 0x2000
	s_nop 0
	global_load_lds_dwordx4 v134, s[58:59]
	s_mov_b32 m0, s37
	s_nop 0
	global_load_lds_dwordx4 v130, s[14:15]
	s_mov_b32 m0, s40
	s_nop 0
	global_load_lds_dwordx4 v131, s[14:15]
	s_waitcnt vmcnt(8)
	s_waitcnt lgkmcnt(0)
	s_barrier
	s_setprio 1
	s_waitcnt lgkmcnt(0)
	v_mfma_f32_16x16x32_bf16 v[62:65], v[138:141], v[170:173], v[62:65]
	v_mfma_f32_16x16x32_bf16 v[58:61], v[146:149], v[170:173], v[58:61]
	v_mfma_f32_16x16x32_bf16 v[46:49], v[138:141], v[178:181], v[46:49]
	v_mfma_f32_16x16x32_bf16 v[42:45], v[146:149], v[178:181], v[42:45]
	v_mfma_f32_16x16x32_bf16 v[30:33], v[138:141], v[186:189], v[30:33]
	v_mfma_f32_16x16x32_bf16 v[26:29], v[146:149], v[186:189], v[26:29]
	v_mfma_f32_16x16x32_bf16 v[14:17], v[138:141], v[194:197], v[14:17]
	v_mfma_f32_16x16x32_bf16 v[10:13], v[146:149], v[194:197], v[10:13]
	v_mfma_f32_16x16x32_bf16 v[62:65], v[142:145], v[174:177], v[62:65]
	v_mfma_f32_16x16x32_bf16 v[58:61], v[150:153], v[174:177], v[58:61]
	v_mfma_f32_16x16x32_bf16 v[46:49], v[142:145], v[182:185], v[46:49]
	v_mfma_f32_16x16x32_bf16 v[42:45], v[150:153], v[182:185], v[42:45]
	v_mfma_f32_16x16x32_bf16 v[30:33], v[142:145], v[190:193], v[30:33]
	v_mfma_f32_16x16x32_bf16 v[26:29], v[150:153], v[190:193], v[26:29]
	v_mfma_f32_16x16x32_bf16 v[14:17], v[142:145], v[198:201], v[14:17]
	v_mfma_f32_16x16x32_bf16 v[10:13], v[150:153], v[198:201], v[10:13]
	s_setprio 0
	s_setprio 1
	v_mfma_f32_16x16x32_bf16 v[54:57], v[154:157], v[170:173], v[54:57]
	v_mfma_f32_16x16x32_bf16 v[50:53], v[162:165], v[170:173], v[50:53]
	v_mfma_f32_16x16x32_bf16 v[38:41], v[154:157], v[178:181], v[38:41]
	v_mfma_f32_16x16x32_bf16 v[34:37], v[162:165], v[178:181], v[34:37]
	v_mfma_f32_16x16x32_bf16 v[22:25], v[154:157], v[186:189], v[22:25]
	v_mfma_f32_16x16x32_bf16 v[18:21], v[162:165], v[186:189], v[18:21]
	v_mfma_f32_16x16x32_bf16 v[6:9], v[154:157], v[194:197], v[6:9]
	v_mfma_f32_16x16x32_bf16 v[2:5], v[162:165], v[194:197], v[2:5]
	v_mfma_f32_16x16x32_bf16 v[54:57], v[158:161], v[174:177], v[54:57]
	v_mfma_f32_16x16x32_bf16 v[50:53], v[166:169], v[174:177], v[50:53]
	v_mfma_f32_16x16x32_bf16 v[38:41], v[158:161], v[182:185], v[38:41]
	v_mfma_f32_16x16x32_bf16 v[34:37], v[166:169], v[182:185], v[34:37]
	v_mfma_f32_16x16x32_bf16 v[22:25], v[158:161], v[190:193], v[22:25]
	v_mfma_f32_16x16x32_bf16 v[18:21], v[166:169], v[190:193], v[18:21]
	v_mfma_f32_16x16x32_bf16 v[6:9], v[158:161], v[198:201], v[6:9]
	v_mfma_f32_16x16x32_bf16 v[2:5], v[166:169], v[198:201], v[2:5]
	s_setprio 0
	s_barrier
	s_add_i32 s51, 0, 0x18000
	s_add_i32 s60, 0, 0x1c000
	ds_read_b128 v[138:141], v0 offset:32768
	ds_read_b128 v[142:145], v0 offset:33792
	ds_read_b128 v[146:149], v0 offset:34816
	ds_read_b128 v[150:153], v0 offset:35840
	ds_read_b128 v[154:157], v0 offset:49152
	ds_read_b128 v[158:161], v0 offset:50176
	ds_read_b128 v[162:165], v0 offset:51200
	ds_read_b128 v[166:169], v0 offset:52224
	s_add_u32 s58, s14, 0xb0000
	s_mov_b32 m0, s41
	ds_read_b128 v[170:173], v136 offset:32768
	ds_read_b128 v[174:177], v136 offset:33792
	ds_read_b128 v[178:181], v136 offset:34816
	ds_read_b128 v[182:185], v136 offset:35840
	ds_read_b128 v[186:189], v136 offset:36864
	ds_read_b128 v[190:193], v136 offset:37888
	ds_read_b128 v[194:197], v136 offset:38912
	ds_read_b128 v[198:201], v136 offset:39936
	s_addc_u32 s59, s15, 0
	s_nop 0
	global_load_lds_dwordx4 v130, s[58:59]
	s_mov_b32 m0, s42
	s_nop 0
	global_load_lds_dwordx4 v131, s[58:59]
	s_waitcnt vmcnt(8)
	s_waitcnt lgkmcnt(0)
	s_barrier
	s_setprio 1
	s_waitcnt lgkmcnt(0)
	v_mfma_f32_16x16x32_bf16 v[126:129], v[138:141], v[170:173], v[126:129]
	v_mfma_f32_16x16x32_bf16 v[122:125], v[146:149], v[170:173], v[122:125]
	v_mfma_f32_16x16x32_bf16 v[110:113], v[138:141], v[178:181], v[110:113]
	v_mfma_f32_16x16x32_bf16 v[106:109], v[146:149], v[178:181], v[106:109]
	v_mfma_f32_16x16x32_bf16 v[94:97], v[138:141], v[186:189], v[94:97]
	v_mfma_f32_16x16x32_bf16 v[90:93], v[146:149], v[186:189], v[90:93]
	v_mfma_f32_16x16x32_bf16 v[78:81], v[138:141], v[194:197], v[78:81]
	v_mfma_f32_16x16x32_bf16 v[74:77], v[146:149], v[194:197], v[74:77]
	v_mfma_f32_16x16x32_bf16 v[126:129], v[142:145], v[174:177], v[126:129]
	v_mfma_f32_16x16x32_bf16 v[122:125], v[150:153], v[174:177], v[122:125]
	v_mfma_f32_16x16x32_bf16 v[110:113], v[142:145], v[182:185], v[110:113]
	v_mfma_f32_16x16x32_bf16 v[106:109], v[150:153], v[182:185], v[106:109]
	v_mfma_f32_16x16x32_bf16 v[94:97], v[142:145], v[190:193], v[94:97]
	v_mfma_f32_16x16x32_bf16 v[90:93], v[150:153], v[190:193], v[90:93]
	v_mfma_f32_16x16x32_bf16 v[78:81], v[142:145], v[198:201], v[78:81]
	v_mfma_f32_16x16x32_bf16 v[74:77], v[150:153], v[198:201], v[74:77]
	s_setprio 0
	s_setprio 1
	v_mfma_f32_16x16x32_bf16 v[118:121], v[154:157], v[170:173], v[118:121]
	v_mfma_f32_16x16x32_bf16 v[114:117], v[162:165], v[170:173], v[114:117]
	v_mfma_f32_16x16x32_bf16 v[102:105], v[154:157], v[178:181], v[102:105]
	v_mfma_f32_16x16x32_bf16 v[98:101], v[162:165], v[178:181], v[98:101]
	v_mfma_f32_16x16x32_bf16 v[86:89], v[154:157], v[186:189], v[86:89]
	v_mfma_f32_16x16x32_bf16 v[82:85], v[162:165], v[186:189], v[82:85]
	v_mfma_f32_16x16x32_bf16 v[70:73], v[154:157], v[194:197], v[70:73]
	v_mfma_f32_16x16x32_bf16 v[66:69], v[162:165], v[194:197], v[66:69]
	v_mfma_f32_16x16x32_bf16 v[118:121], v[158:161], v[174:177], v[118:121]
	v_mfma_f32_16x16x32_bf16 v[114:117], v[166:169], v[174:177], v[114:117]
	v_mfma_f32_16x16x32_bf16 v[102:105], v[158:161], v[182:185], v[102:105]
	v_mfma_f32_16x16x32_bf16 v[98:101], v[166:169], v[182:185], v[98:101]
	v_mfma_f32_16x16x32_bf16 v[86:89], v[158:161], v[190:193], v[86:89]
	v_mfma_f32_16x16x32_bf16 v[82:85], v[166:169], v[190:193], v[82:85]
	v_mfma_f32_16x16x32_bf16 v[70:73], v[158:161], v[198:201], v[70:73]
	v_mfma_f32_16x16x32_bf16 v[66:69], v[166:169], v[198:201], v[66:69]
	s_setprio 0
	s_barrier
	ds_read_b128 v[170:173], v136 offset:49152
	ds_read_b128 v[174:177], v136 offset:50176
	ds_read_b128 v[178:181], v136 offset:51200
	ds_read_b128 v[182:185], v136 offset:52224
	ds_read_b128 v[186:189], v136 offset:53248
	ds_read_b128 v[190:193], v136 offset:54272
	ds_read_b128 v[194:197], v136 offset:55296
	ds_read_b128 v[198:201], v136 offset:56320
	s_add_i32 s51, s51, s26
	s_add_u32 s100, s16, s38
	s_addc_u32 s101, s17, s39
	s_mov_b32 m0, s51
	s_nop 0
	global_load_lds_dwordx4 v133, s[100:101]
	s_add_i32 m0, s51, 0x2000
	s_nop 0
	s_add_u32 s16, s16, 0xb0080
	s_addc_u32 s17, s17, 0
	s_add_i32 s51, s60, s26
	global_load_lds_dwordx4 v134, s[100:101]
	s_mov_b32 m0, s51
	s_nop 0
	global_load_lds_dwordx4 v133, s[16:17]
	s_add_i32 m0, s51, 0x2000
	s_nop 0
	global_load_lds_dwordx4 v134, s[16:17]
	s_mov_b32 m0, s48
	s_add_u32 s100, s14, s38
	s_addc_u32 s101, s15, s39
	v_mov_b32_e32 v0, v131
	global_load_lds_dwordx4 v130, s[100:101]
	s_mov_b32 m0, s49
	s_nop 0
	global_load_lds_dwordx4 v131, s[100:101]
	s_waitcnt vmcnt(8)
	s_waitcnt lgkmcnt(0)
	s_barrier
	s_setprio 1
	s_waitcnt lgkmcnt(0)
	v_mfma_f32_16x16x32_bf16 v[62:65], v[138:141], v[170:173], v[62:65]
	v_mfma_f32_16x16x32_bf16 v[58:61], v[146:149], v[170:173], v[58:61]
	v_mfma_f32_16x16x32_bf16 v[46:49], v[138:141], v[178:181], v[46:49]
	v_mfma_f32_16x16x32_bf16 v[42:45], v[146:149], v[178:181], v[42:45]
	v_mfma_f32_16x16x32_bf16 v[30:33], v[138:141], v[186:189], v[30:33]
	v_mfma_f32_16x16x32_bf16 v[26:29], v[146:149], v[186:189], v[26:29]
	v_mfma_f32_16x16x32_bf16 v[14:17], v[138:141], v[194:197], v[14:17]
	v_mfma_f32_16x16x32_bf16 v[10:13], v[146:149], v[194:197], v[10:13]
	v_mfma_f32_16x16x32_bf16 v[62:65], v[142:145], v[174:177], v[62:65]
	v_mfma_f32_16x16x32_bf16 v[58:61], v[150:153], v[174:177], v[58:61]
	v_mfma_f32_16x16x32_bf16 v[46:49], v[142:145], v[182:185], v[46:49]
	v_mfma_f32_16x16x32_bf16 v[42:45], v[150:153], v[182:185], v[42:45]
	v_mfma_f32_16x16x32_bf16 v[30:33], v[142:145], v[190:193], v[30:33]
	v_mfma_f32_16x16x32_bf16 v[26:29], v[150:153], v[190:193], v[26:29]
	v_mfma_f32_16x16x32_bf16 v[14:17], v[142:145], v[198:201], v[14:17]
	v_mfma_f32_16x16x32_bf16 v[10:13], v[150:153], v[198:201], v[10:13]
	s_setprio 0
	s_setprio 1
	v_mfma_f32_16x16x32_bf16 v[54:57], v[154:157], v[170:173], v[54:57]
	v_mfma_f32_16x16x32_bf16 v[50:53], v[162:165], v[170:173], v[50:53]
	v_mfma_f32_16x16x32_bf16 v[38:41], v[154:157], v[178:181], v[38:41]
	v_mfma_f32_16x16x32_bf16 v[34:37], v[162:165], v[178:181], v[34:37]
	v_mfma_f32_16x16x32_bf16 v[22:25], v[154:157], v[186:189], v[22:25]
	v_mfma_f32_16x16x32_bf16 v[18:21], v[162:165], v[186:189], v[18:21]
	v_mfma_f32_16x16x32_bf16 v[6:9], v[154:157], v[194:197], v[6:9]
	v_mfma_f32_16x16x32_bf16 v[2:5], v[162:165], v[194:197], v[2:5]
	v_mfma_f32_16x16x32_bf16 v[54:57], v[158:161], v[174:177], v[54:57]
	v_mfma_f32_16x16x32_bf16 v[50:53], v[166:169], v[174:177], v[50:53]
	v_mfma_f32_16x16x32_bf16 v[38:41], v[158:161], v[182:185], v[38:41]
	v_mfma_f32_16x16x32_bf16 v[34:37], v[166:169], v[182:185], v[34:37]
	v_mfma_f32_16x16x32_bf16 v[22:25], v[158:161], v[190:193], v[22:25]
	v_mfma_f32_16x16x32_bf16 v[18:21], v[166:169], v[190:193], v[18:21]
	v_mfma_f32_16x16x32_bf16 v[6:9], v[158:161], v[198:201], v[6:9]
	v_mfma_f32_16x16x32_bf16 v[2:5], v[166:169], v[198:201], v[2:5]
	s_setprio 0
	s_barrier
	s_add_i32 s50, s50, 2
	s_add_u32 s2, s2, 0x100
	s_addc_u32 s3, s3, 0
	s_cmp_gt_u32 s50, 41
	s_cbranch_scc0 .LBB0_953
.LBB0_956:
	s_add_u32 s4, s12, 0x6400000
	s_addc_u32 s5, s13, 0
	s_add_u32 s2, s12, 0x6300000
	s_addc_u32 s3, s13, 0
	s_add_i32 s7, s24, s47
	s_lshl_b32 s6, s23, 5
	s_lshl_b32 s12, s22, 8
	s_or_b32 s6, s12, s6
	v_add_u32_e32 v202, s7, v132
	v_ashrrev_i32_e32 v203, 31, v202
	v_lshl_add_u32 v194, v240, 3, s6
	v_lshlrev_b64 v[186:187], 11, v[202:203]
	s_cmp_eq_u64 s[10:11], 0
	v_ashrrev_i32_e32 v195, 31, v194
	v_cmp_eq_u32_e64 s[6:7], 0, v240
	v_add_u32_e32 v200, 16, v202
	v_add_u32_e32 v198, 32, v202
	v_add_u32_e32 v196, 48, v202
	v_lshl_add_u64 v[206:207], s[4:5], 0, v[186:187]
	s_cbranch_scc1 .LBB0_987
	v_lshl_add_u64 v[188:189], v[194:195], 2, s[10:11]
	v_lshlrev_b64 v[130:131], 12, v[202:203]
	v_lshl_add_u64 v[130:131], v[188:189], 0, v[130:131]
	global_load_dwordx4 v[190:193], v[130:131], off offset:16 sc1 nt
	global_load_dwordx4 v[208:211], v[130:131], off sc1 nt
	global_load_dwordx4 v[178:181], v[130:131], off offset:528 sc1 nt
	global_load_dwordx4 v[182:185], v[130:131], off offset:512 sc1 nt
	v_ashrrev_i32_e32 v201, 31, v200
	v_lshlrev_b64 v[130:131], 12, v[200:201]
	v_lshl_add_u64 v[130:131], v[188:189], 0, v[130:131]
	v_ashrrev_i32_e32 v199, 31, v198
	global_load_dwordx4 v[170:173], v[130:131], off offset:16 sc1 nt
	global_load_dwordx4 v[174:177], v[130:131], off sc1 nt
	global_load_dwordx4 v[162:165], v[130:131], off offset:528 sc1 nt
	global_load_dwordx4 v[166:169], v[130:131], off offset:512 sc1 nt
	v_lshlrev_b64 v[130:131], 12, v[198:199]
	v_lshl_add_u64 v[130:131], v[188:189], 0, v[130:131]
	v_ashrrev_i32_e32 v197, 31, v196
	global_load_dwordx4 v[154:157], v[130:131], off offset:16 sc1 nt
	global_load_dwordx4 v[158:161], v[130:131], off sc1 nt
	global_load_dwordx4 v[142:145], v[130:131], off offset:528 sc1 nt
	global_load_dwordx4 v[150:153], v[130:131], off offset:512 sc1 nt
	v_lshlrev_b64 v[130:131], 12, v[196:197]
	v_lshl_add_u64 v[134:135], v[188:189], 0, v[130:131]
	global_load_dwordx4 v[138:141], v[134:135], off offset:16 sc1 nt
	global_load_dwordx4 v[146:149], v[134:135], off sc1 nt
	global_load_dwordx4 v[130:133], v[134:135], off offset:528 sc1 nt
	s_nop 0
	global_load_dwordx4 v[134:137], v[134:135], off offset:512 sc1 nt
	v_lshl_add_u64 v[214:215], v[194:195], 1, v[206:207]
	s_cmpk_lt_u32 s25, 0x100
	s_cbranch_scc0 .Lepi_lead_r4
	s_barrier
.Lepi_lead_r4:
	s_waitcnt vmcnt(0)
	v_pk_fma_f32 v[212:213], v[122:123], 0.5, v[190:191] op_sel_hi:[1,0,1]
	v_pk_fma_f32 v[204:205], v[128:129], 0.5, v[210:211] op_sel_hi:[1,0,1]
	v_pk_fma_f32 v[208:209], v[126:127], 0.5, v[208:209] op_sel_hi:[1,0,1]
	v_pk_fma_f32 v[210:211], v[124:125], 0.5, v[192:193] op_sel_hi:[1,0,1]
	v_cvt_pk_bf16_f32 v190, v208, v209
	v_cvt_pk_bf16_f32 v191, v204, v205
	v_cvt_pk_bf16_f32 v192, v212, v213
	v_mul_f32_e32 v0, v209, v209
	v_cvt_pk_bf16_f32 v193, v210, v211
	global_store_dwordx4 v[214:215], v[190:193], off
	v_fmac_f32_e32 v0, v208, v208
	v_pk_fma_f32 v[184:185], v[120:121], 0.5, v[184:185] op_sel_hi:[1,0,1]
	v_mul_f32_e32 v190, v205, v205
	v_fmac_f32_e32 v190, v204, v204
	v_add_f32_e32 v0, v0, v190
	v_mul_f32_e32 v190, v213, v213
	v_fmac_f32_e32 v190, v212, v212
	v_add_f32_e32 v0, v190, v0
	v_mul_f32_e32 v190, v211, v211
	v_fmac_f32_e32 v190, v210, v210
	v_pk_fma_f32 v[182:183], v[118:119], 0.5, v[182:183] op_sel_hi:[1,0,1]
	v_pk_fma_f32 v[192:193], v[114:115], 0.5, v[178:179] op_sel_hi:[1,0,1]
	v_cvt_pk_bf16_f32 v178, v182, v183
	v_cvt_pk_bf16_f32 v179, v184, v185
	v_add_f32_e32 v0, v190, v0
	v_pk_fma_f32 v[190:191], v[116:117], 0.5, v[180:181] op_sel_hi:[1,0,1]
	v_cvt_pk_bf16_f32 v180, v192, v193
	s_nop 0
	v_cvt_pk_bf16_f32 v181, v190, v191
	global_store_dwordx4 v[214:215], v[178:181], off offset:256
	s_nop 1
	v_mul_f32_e32 v178, v183, v183
	v_mul_f32_e32 v179, v185, v185
	v_fmac_f32_e32 v178, v182, v182
	v_fmac_f32_e32 v179, v184, v184
	v_add_f32_e32 v178, v178, v179
	v_mul_f32_e32 v179, v193, v193
	v_fmac_f32_e32 v179, v192, v192
	v_add_f32_e32 v178, v179, v178
	v_mul_f32_e32 v179, v191, v191
	v_fmac_f32_e32 v179, v190, v190
	v_add_f32_e32 v178, v179, v178
	v_add_f32_e32 v0, v0, v178
	ds_swizzle_b32 v178, v0 offset:swizzle(SWAP,16)
	s_waitcnt lgkmcnt(0)
	v_add_f32_e32 v0, v0, v178
	v_mov_b32_e32 v178, v0
	s_nop 1
	v_permlane32_swap_b32_e32 v0, v178
	s_and_saveexec_b64 s[10:11], s[6:7]
	s_cbranch_execz .LBB0_959
	v_add_f32_e32 v0, v0, v178
	s_lshl_b32 s12, s22, 2
	v_lshlrev_b64 v[178:179], 6, v[202:203]
	s_ashr_i32 s13, s12, 31
	v_lshl_add_u64 v[178:179], s[2:3], 0, v[178:179]
	v_lshl_add_u64 v[178:179], s[12:13], 2, v[178:179]
	s_lshl_b32 s26, s23, 2
	v_lshl_add_u64 v[178:179], v[178:179], 0, s[26:27]
	global_store_dword v[178:179], v0, off

.LBB0_972:
	v_lshlrev_b64 v[228:229], 1, v[194:195]
	v_lshl_add_u64 v[134:135], s[4:5], 0, v[228:229]
	v_lshl_add_u64 v[130:131], v[134:135], 0, v[186:187]
	global_load_dwordx4 v[190:193], v[130:131], off sc1
	global_load_dwordx4 v[186:189], v[130:131], off offset:256 sc1
	v_ashrrev_i32_e32 v201, 31, v200
	v_lshlrev_b64 v[226:227], 11, v[200:201]
	v_ashrrev_i32_e32 v199, 31, v198
	v_lshl_add_u64 v[130:131], v[134:135], 0, v[226:227]
	v_lshlrev_b64 v[224:225], 11, v[198:199]
	v_ashrrev_i32_e32 v197, 31, v196
	v_add_u32_e32 v218, 0x80, v202
	global_load_dwordx4 v[182:185], v[130:131], off sc1
	global_load_dwordx4 v[178:181], v[130:131], off offset:256 sc1
	v_lshl_add_u64 v[130:131], v[134:135], 0, v[224:225]
	v_lshlrev_b64 v[222:223], 11, v[196:197]
	v_ashrrev_i32_e32 v219, 31, v218
	v_add_u32_e32 v214, 0x90, v202
	global_load_dwordx4 v[174:177], v[130:131], off sc1
	global_load_dwordx4 v[170:173], v[130:131], off offset:256 sc1
	v_lshl_add_u64 v[130:131], v[134:135], 0, v[222:223]
	v_lshlrev_b64 v[220:221], 11, v[218:219]
	v_ashrrev_i32_e32 v215, 31, v214
	v_add_u32_e32 v208, 0xa0, v202
	v_add_u32_e32 v204, 0xb0, v202
	global_load_dwordx4 v[166:169], v[130:131], off sc1
	global_load_dwordx4 v[162:165], v[130:131], off offset:256 sc1
	v_lshl_add_u64 v[130:131], v[134:135], 0, v[220:221]
	v_lshlrev_b64 v[216:217], 11, v[214:215]
	v_ashrrev_i32_e32 v209, 31, v208
	v_ashrrev_i32_e32 v205, 31, v204
	global_load_dwordx4 v[158:161], v[130:131], off sc1
	global_load_dwordx4 v[154:157], v[130:131], off offset:256 sc1
	v_lshl_add_u64 v[130:131], v[134:135], 0, v[216:217]
	v_lshlrev_b64 v[212:213], 11, v[208:209]
	v_lshlrev_b64 v[210:211], 11, v[204:205]
	global_load_dwordx4 v[150:153], v[130:131], off sc1
	global_load_dwordx4 v[146:149], v[130:131], off offset:256 sc1
	v_lshl_add_u64 v[130:131], v[134:135], 0, v[212:213]
	v_lshl_add_u64 v[134:135], v[134:135], 0, v[210:211]
	global_load_dwordx4 v[142:145], v[130:131], off sc1
	s_nop 0
	global_load_dwordx4 v[130:133], v[130:131], off offset:256 sc1
	s_nop 0
	global_load_dwordx4 v[138:141], v[134:135], off sc1
	s_nop 0
	global_load_dwordx4 v[134:137], v[134:135], off offset:256 sc1
	v_lshl_add_u64 v[206:207], v[206:207], 0, v[228:229]
	v_cmp_eq_u32_e64 s[6:7], 0, v240
	s_cmpk_lt_u32 s25, 0x100
	s_cbranch_scc0 .Lepi_lead_r3
	s_barrier
.Lepi_lead_r3:
	s_waitcnt vmcnt(0)
	v_lshlrev_b32_e32 v232, 16, v190
	v_and_b32_e32 v233, 0xffff0000, v190
	v_lshlrev_b32_e32 v190, 16, v191
	v_and_b32_e32 v191, 0xffff0000, v191
	v_lshlrev_b32_e32 v234, 16, v192
	v_and_b32_e32 v235, 0xffff0000, v192
	v_lshlrev_b32_e32 v192, 16, v193
	v_and_b32_e32 v193, 0xffff0000, v193
	v_pk_fma_f32 v[128:129], v[128:129], 0.5, v[190:191] op_sel_hi:[1,0,1]
	v_pk_fma_f32 v[126:127], v[126:127], 0.5, v[232:233] op_sel_hi:[1,0,1]
	v_pk_fma_f32 v[190:191], v[124:125], 0.5, v[192:193] op_sel_hi:[1,0,1]
	v_pk_fma_f32 v[192:193], v[122:123], 0.5, v[234:235] op_sel_hi:[1,0,1]
	v_cvt_pk_bf16_f32 v122, v126, v127
	v_cvt_pk_bf16_f32 v123, v128, v129
	v_mul_f32_e32 v0, v127, v127
	v_cvt_pk_bf16_f32 v124, v192, v193
	v_cvt_pk_bf16_f32 v125, v190, v191
	global_store_dwordx4 v[206:207], v[122:125], off
	v_fmac_f32_e32 v0, v126, v126
	v_lshlrev_b32_e32 v126, 16, v188
	v_mul_f32_e32 v122, v129, v129
	v_fmac_f32_e32 v122, v128, v128
	v_add_f32_e32 v0, v0, v122
	v_mul_f32_e32 v122, v193, v193
	v_fmac_f32_e32 v122, v192, v192
	v_add_f32_e32 v0, v122, v0
	v_mul_f32_e32 v122, v191, v191
	v_fmac_f32_e32 v122, v190, v190
	v_add_f32_e32 v0, v122, v0
	v_lshlrev_b32_e32 v122, 16, v186
	v_and_b32_e32 v123, 0xffff0000, v186
	v_lshlrev_b32_e32 v124, 16, v187
	v_and_b32_e32 v125, 0xffff0000, v187
	v_and_b32_e32 v127, 0xffff0000, v188
	v_lshlrev_b32_e32 v128, 16, v189
	v_and_b32_e32 v129, 0xffff0000, v189
	v_pk_fma_f32 v[120:121], v[120:121], 0.5, v[124:125] op_sel_hi:[1,0,1]
	v_pk_fma_f32 v[118:119], v[118:119], 0.5, v[122:123] op_sel_hi:[1,0,1]
	v_pk_fma_f32 v[124:125], v[114:115], 0.5, v[126:127] op_sel_hi:[1,0,1]
	v_cvt_pk_bf16_f32 v114, v118, v119
	v_cvt_pk_bf16_f32 v115, v120, v121
	v_pk_fma_f32 v[122:123], v[116:117], 0.5, v[128:129] op_sel_hi:[1,0,1]
	v_cvt_pk_bf16_f32 v116, v124, v125
	s_nop 0
	v_cvt_pk_bf16_f32 v117, v122, v123
	global_store_dwordx4 v[206:207], v[114:117], off offset:256
	s_nop 1
	v_mul_f32_e32 v114, v119, v119
	v_mul_f32_e32 v115, v121, v121
	v_fmac_f32_e32 v114, v118, v118
	v_fmac_f32_e32 v115, v120, v120
	v_add_f32_e32 v114, v114, v115
	v_mul_f32_e32 v115, v125, v125
	v_fmac_f32_e32 v115, v124, v124
	v_add_f32_e32 v114, v115, v114
	v_mul_f32_e32 v115, v123, v123
	v_fmac_f32_e32 v115, v122, v122
	v_add_f32_e32 v114, v115, v114
	v_add_f32_e32 v0, v0, v114
	ds_swizzle_b32 v114, v0 offset:swizzle(SWAP,16)
	s_waitcnt lgkmcnt(0)
	v_add_f32_e32 v0, v0, v114
	v_mov_b32_e32 v114, v0
	s_nop 1
	v_permlane32_swap_b32_e32 v0, v114
	s_and_saveexec_b64 s[10:11], s[6:7]
	s_cbranch_execz .LBB0_974
	v_add_f32_e32 v0, v0, v114
	s_lshl_b32 s12, s22, 2
	v_lshlrev_b64 v[114:115], 6, v[202:203]
	s_ashr_i32 s13, s12, 31
	v_lshl_add_u64 v[114:115], s[2:3], 0, v[114:115]
	v_lshl_add_u64 v[114:115], s[12:13], 2, v[114:115]
	s_lshl_b32 s26, s23, 2
	v_lshl_add_u64 v[114:115], v[114:115], 0, s[26:27]
	global_store_dword v[114:115], v0, off

.LBB0_1019:
	s_or_b64 exec, exec, s[12:13]
	s_waitcnt lgkmcnt(0)
	s_barrier
	s_branch .LBB0_1076

.LBB0_1270:
	s_or_b64 exec, exec, s[10:11]
	s_waitcnt vmcnt(0)
	s_waitcnt vmcnt(0)

.LBB0_1544:
	s_or_b64 exec, exec, s[14:15]
	s_waitcnt vmcnt(0)
	s_waitcnt vmcnt(0)

.LBB0_1573:
.LBB0_1575:
	s_add_u32 s6, s4, 0x6400000
	s_addc_u32 s7, s5, 0
	s_add_u32 s2, s4, 0x6300000
	s_addc_u32 s3, s5, 0
	s_lshl_b32 s4, s12, 5
	s_lshl_b32 s5, s13, 8
	s_or_b32 s4, s5, s4
	s_lshl_b32 s8, s13, 2
	v_lshl_add_u32 v2, v240, 3, s4
	v_add_u32_e32 v224, s15, v165
	v_ashrrev_i32_e32 v3, 31, v2
	v_lshlrev_b64 v[226:227], 1, v[2:3]
	v_ashrrev_i32_e32 v225, 31, v224
	v_lshl_add_u64 v[124:125], s[6:7], 0, v[226:227]
	v_lshlrev_b64 v[228:229], 11, v[224:225]
	v_lshl_add_u64 v[116:117], v[124:125], 0, v[228:229]
	global_load_dwordx4 v[192:195], v[116:117], off sc1
	global_load_dwordx4 v[188:191], v[116:117], off offset:256 sc1
	v_add_u32_e32 v220, 16, v224
	v_ashrrev_i32_e32 v221, 31, v220
	v_add_u32_e32 v216, 32, v224
	v_lshlrev_b64 v[222:223], 11, v[220:221]
	v_ashrrev_i32_e32 v217, 31, v216
	v_add_u32_e32 v212, 48, v224
	v_lshl_add_u64 v[116:117], v[124:125], 0, v[222:223]
	v_lshlrev_b64 v[218:219], 11, v[216:217]
	v_ashrrev_i32_e32 v213, 31, v212
	v_add_u32_e32 v208, 0x80, v224
	global_load_dwordx4 v[184:187], v[116:117], off sc1
	global_load_dwordx4 v[180:183], v[116:117], off offset:256 sc1
	v_lshl_add_u64 v[116:117], v[124:125], 0, v[218:219]
	v_lshlrev_b64 v[214:215], 11, v[212:213]
	v_ashrrev_i32_e32 v209, 31, v208
	v_add_u32_e32 v204, 0x90, v224
	global_load_dwordx4 v[176:179], v[116:117], off sc1
	global_load_dwordx4 v[172:175], v[116:117], off offset:256 sc1
	v_lshl_add_u64 v[116:117], v[124:125], 0, v[214:215]
	v_lshlrev_b64 v[210:211], 11, v[208:209]
	v_ashrrev_i32_e32 v205, 31, v204
	v_add_u32_e32 v198, 0xa0, v224
	v_add_u32_e32 v196, 0xb0, v224
	global_load_dwordx4 v[168:171], v[116:117], off sc1
	global_load_dwordx4 v[164:167], v[116:117], off offset:256 sc1
	v_lshl_add_u64 v[116:117], v[124:125], 0, v[210:211]
	v_lshlrev_b64 v[206:207], 11, v[204:205]
	v_ashrrev_i32_e32 v199, 31, v198
	v_ashrrev_i32_e32 v197, 31, v196
	global_load_dwordx4 v[152:155], v[116:117], off sc1
	global_load_dwordx4 v[148:151], v[116:117], off offset:256 sc1
	v_lshl_add_u64 v[116:117], v[124:125], 0, v[206:207]
	v_lshlrev_b64 v[202:203], 11, v[198:199]
	v_lshlrev_b64 v[200:201], 11, v[196:197]
	global_load_dwordx4 v[144:147], v[116:117], off sc1
	global_load_dwordx4 v[140:143], v[116:117], off offset:256 sc1
	v_lshl_add_u64 v[116:117], v[124:125], 0, v[202:203]
	v_lshl_add_u64 v[124:125], v[124:125], 0, v[200:201]
	global_load_dwordx4 v[132:135], v[116:117], off sc1
	s_nop 0
	global_load_dwordx4 v[116:119], v[116:117], off offset:256 sc1
	s_nop 0
	global_load_dwordx4 v[136:139], v[124:125], off sc1
	s_nop 0
	global_load_dwordx4 v[124:127], v[124:125], off offset:256 sc1
	v_cmp_eq_u32_e32 vcc, 0, v240
	s_cmpk_lt_u32 s14, 0x100
	s_cbranch_scc0 .Lepi_lead_r5
	s_barrier
.Lepi_lead_r5:
	s_waitcnt vmcnt(0)
	v_lshlrev_b32_e32 v232, 16, v192
	v_and_b32_e32 v233, 0xffff0000, v192
	v_lshlrev_b32_e32 v192, 16, v193
	v_and_b32_e32 v193, 0xffff0000, v193
	v_lshlrev_b32_e32 v234, 16, v194
	v_and_b32_e32 v235, 0xffff0000, v194
	v_lshlrev_b32_e32 v194, 16, v195
	v_and_b32_e32 v195, 0xffff0000, v195
	v_pk_add_f32 v[162:163], v[162:163], v[192:193]
	v_pk_add_f32 v[192:193], v[158:159], v[194:195]
	v_pk_add_f32 v[194:195], v[156:157], v[234:235]
	v_lshl_add_u64 v[156:157], s[6:7], 0, v[228:229]
	v_pk_add_f32 v[160:161], v[160:161], v[232:233]
	v_lshl_add_u64 v[226:227], v[156:157], 0, v[226:227]
	v_cvt_pk_bf16_f32 v156, v160, v161
	v_cvt_pk_bf16_f32 v157, v162, v163
	v_cvt_pk_bf16_f32 v158, v194, v195
	v_cvt_pk_bf16_f32 v159, v192, v193
	global_store_dwordx4 v[226:227], v[156:159], off
	v_mul_f32_e32 v0, v161, v161
	v_fmac_f32_e32 v0, v160, v160
	v_mul_f32_e32 v156, v163, v163
	v_fmac_f32_e32 v156, v162, v162
	v_add_f32_e32 v0, v0, v156
	v_mul_f32_e32 v156, v195, v195
	v_fmac_f32_e32 v156, v194, v194
	v_add_f32_e32 v0, v156, v0
	v_mul_f32_e32 v156, v193, v193
	v_fmac_f32_e32 v156, v192, v192
	v_add_f32_e32 v0, v156, v0
	v_lshlrev_b32_e32 v156, 16, v188
	v_and_b32_e32 v157, 0xffff0000, v188
	v_lshlrev_b32_e32 v158, 16, v189
	v_and_b32_e32 v159, 0xffff0000, v189
	v_lshlrev_b32_e32 v160, 16, v190
	v_and_b32_e32 v161, 0xffff0000, v190
	v_lshlrev_b32_e32 v162, 16, v191
	v_and_b32_e32 v163, 0xffff0000, v191
	v_pk_add_f32 v[130:131], v[130:131], v[158:159]
	v_pk_add_f32 v[128:129], v[128:129], v[156:157]
	v_pk_add_f32 v[158:159], v[120:121], v[160:161]
	v_cvt_pk_bf16_f32 v120, v128, v129
	v_cvt_pk_bf16_f32 v121, v130, v131
	v_pk_add_f32 v[156:157], v[122:123], v[162:163]
	v_cvt_pk_bf16_f32 v122, v158, v159
	s_nop 0
	v_cvt_pk_bf16_f32 v123, v156, v157
	global_store_dwordx4 v[226:227], v[120:123], off offset:256
	s_nop 1
	v_mul_f32_e32 v120, v129, v129
	v_mul_f32_e32 v121, v131, v131
	v_fmac_f32_e32 v120, v128, v128
	v_fmac_f32_e32 v121, v130, v130
	v_add_f32_e32 v120, v120, v121
	v_mul_f32_e32 v121, v159, v159
	v_fmac_f32_e32 v121, v158, v158
	v_add_f32_e32 v120, v121, v120
	v_mul_f32_e32 v121, v157, v157
	v_fmac_f32_e32 v121, v156, v156
	v_add_f32_e32 v120, v121, v120
	v_add_f32_e32 v0, v0, v120
	ds_swizzle_b32 v120, v0 offset:swizzle(SWAP,16)
	s_waitcnt lgkmcnt(0)
	v_add_f32_e32 v0, v0, v120
	v_mov_b32_e32 v120, v0
	s_nop 1
	v_permlane32_swap_b32_e32 v0, v120
	s_and_saveexec_b64 s[4:5], vcc
	s_cbranch_execz .LBB0_1577
	v_lshlrev_b64 v[122:123], 6, v[224:225]
	v_lshl_add_u64 v[122:123], s[2:3], 0, v[122:123]
	s_lshl_b32 s26, s8, 2
	v_lshl_add_u64 v[122:123], v[122:123], 0, s[26:27]
	s_lshl_b32 s26, s12, 2
	v_lshl_add_u64 v[122:123], v[122:123], 0, s[26:27]
	v_add_f32_e32 v0, v0, v120
	global_store_dword v[122:123], v0, off

.LBB0_1681:
	s_add_u32 s48, s6, s2
	s_addc_u32 s49, s7, s3
	s_add_u32 s10, s48, 0x100
	s_addc_u32 s11, s49, 0
	s_add_u32 s12, s37, s2
	s_addc_u32 s13, s40, s3
	s_add_i32 s47, 0, 0x10000
	s_cmp_eq_u32 s46, 12
	s_cselect_b32 s11, s7, s11
	s_cselect_b32 s10, s6, s10
	v_add_u32_e32 v0, s47, v136
	s_cselect_b32 s13, s9, s13
	s_cselect_b32 s12, s8, s12
	s_add_i32 s50, 0, 0x14000
	ds_read_b128 v[138:141], v0
	ds_read_b128 v[142:145], v0 offset:1024
	ds_read_b128 v[146:149], v0 offset:2048
	ds_read_b128 v[150:153], v0 offset:3072
	ds_read_b128 v[154:157], v0 offset:16384
	ds_read_b128 v[158:161], v0 offset:17408
	ds_read_b128 v[162:165], v0 offset:18432
	ds_read_b128 v[166:169], v0 offset:19456
	ds_read_b128 v[170:173], v137
	ds_read_b128 v[174:177], v137 offset:1024
	ds_read_b128 v[178:181], v137 offset:2048
	ds_read_b128 v[182:185], v137 offset:3072
	ds_read_b128 v[186:189], v137 offset:4096
	ds_read_b128 v[190:193], v137 offset:5120
	ds_read_b128 v[194:197], v137 offset:6144
	ds_read_b128 v[198:201], v137 offset:7168
	s_add_i32 m0, s23, 0xc000
	s_add_u32 s100, s48, s56
	s_addc_u32 s101, s49, s57
	global_load_lds_dwordx4 v130, s[100:101]
	s_add_i32 m0, s23, 0xe000
	s_nop 0
	global_load_lds_dwordx4 v132, s[100:101]
	s_waitcnt vmcnt(8)
	s_waitcnt lgkmcnt(0)
	s_barrier
	s_setprio 1
	s_waitcnt lgkmcnt(0)
	v_mfma_f32_16x16x32_bf16 v[126:129], v[138:141], v[170:173], v[126:129]
	v_mfma_f32_16x16x32_bf16 v[122:125], v[146:149], v[170:173], v[122:125]
	v_mfma_f32_16x16x32_bf16 v[110:113], v[138:141], v[178:181], v[110:113]
	v_mfma_f32_16x16x32_bf16 v[106:109], v[146:149], v[178:181], v[106:109]
	v_mfma_f32_16x16x32_bf16 v[94:97], v[138:141], v[186:189], v[94:97]
	v_mfma_f32_16x16x32_bf16 v[90:93], v[146:149], v[186:189], v[90:93]
	v_mfma_f32_16x16x32_bf16 v[78:81], v[138:141], v[194:197], v[78:81]
	v_mfma_f32_16x16x32_bf16 v[74:77], v[146:149], v[194:197], v[74:77]
	v_mfma_f32_16x16x32_bf16 v[126:129], v[142:145], v[174:177], v[126:129]
	v_mfma_f32_16x16x32_bf16 v[122:125], v[150:153], v[174:177], v[122:125]
	v_mfma_f32_16x16x32_bf16 v[110:113], v[142:145], v[182:185], v[110:113]
	v_mfma_f32_16x16x32_bf16 v[106:109], v[150:153], v[182:185], v[106:109]
	v_mfma_f32_16x16x32_bf16 v[94:97], v[142:145], v[190:193], v[94:97]
	v_mfma_f32_16x16x32_bf16 v[90:93], v[150:153], v[190:193], v[90:93]
	v_mfma_f32_16x16x32_bf16 v[78:81], v[142:145], v[198:201], v[78:81]
	v_mfma_f32_16x16x32_bf16 v[74:77], v[150:153], v[198:201], v[74:77]
	s_setprio 0
	s_setprio 1
	v_mfma_f32_16x16x32_bf16 v[118:121], v[154:157], v[170:173], v[118:121]
	v_mfma_f32_16x16x32_bf16 v[114:117], v[162:165], v[170:173], v[114:117]
	v_mfma_f32_16x16x32_bf16 v[102:105], v[154:157], v[178:181], v[102:105]
	v_mfma_f32_16x16x32_bf16 v[98:101], v[162:165], v[178:181], v[98:101]
	v_mfma_f32_16x16x32_bf16 v[86:89], v[154:157], v[186:189], v[86:89]
	v_mfma_f32_16x16x32_bf16 v[82:85], v[162:165], v[186:189], v[82:85]
	v_mfma_f32_16x16x32_bf16 v[70:73], v[154:157], v[194:197], v[70:73]
	v_mfma_f32_16x16x32_bf16 v[66:69], v[162:165], v[194:197], v[66:69]
	v_mfma_f32_16x16x32_bf16 v[118:121], v[158:161], v[174:177], v[118:121]
	v_mfma_f32_16x16x32_bf16 v[114:117], v[166:169], v[174:177], v[114:117]
	v_mfma_f32_16x16x32_bf16 v[102:105], v[158:161], v[182:185], v[102:105]
	v_mfma_f32_16x16x32_bf16 v[98:101], v[166:169], v[182:185], v[98:101]
	v_mfma_f32_16x16x32_bf16 v[86:89], v[158:161], v[190:193], v[86:89]
	v_mfma_f32_16x16x32_bf16 v[82:85], v[166:169], v[190:193], v[82:85]
	v_mfma_f32_16x16x32_bf16 v[70:73], v[158:161], v[198:201], v[70:73]
	v_mfma_f32_16x16x32_bf16 v[66:69], v[166:169], v[198:201], v[66:69]
	s_setprio 0
	s_barrier
	s_add_i32 s47, s47, s22
	ds_read_b128 v[170:173], v137 offset:16384
	ds_read_b128 v[174:177], v137 offset:17408
	ds_read_b128 v[178:181], v137 offset:18432
	ds_read_b128 v[182:185], v137 offset:19456
	ds_read_b128 v[186:189], v137 offset:20480
	ds_read_b128 v[190:193], v137 offset:21504
	ds_read_b128 v[194:197], v137 offset:22528
	ds_read_b128 v[198:201], v137 offset:23552
	s_mov_b32 m0, s47
	s_nop 0
	global_load_lds_dwordx4 v134, s[12:13]
	s_add_i32 m0, s47, 0x2000
	s_add_u32 s48, s12, 0x40000
	global_load_lds_dwordx4 v135, s[12:13]
	s_addc_u32 s49, s13, 0
	s_add_i32 s47, s50, s22
	s_mov_b32 m0, s47
	s_nop 0
	global_load_lds_dwordx4 v134, s[48:49]
	s_add_i32 m0, s47, 0x2000
	s_nop 0
	global_load_lds_dwordx4 v135, s[48:49]
	s_mov_b32 m0, s23
	s_nop 0
	global_load_lds_dwordx4 v130, s[10:11]
	s_mov_b32 m0, s24
	s_nop 0
	global_load_lds_dwordx4 v132, s[10:11]
	s_waitcnt vmcnt(8)
	s_waitcnt lgkmcnt(0)
	s_barrier
	s_setprio 1
	s_waitcnt lgkmcnt(0)
	v_mfma_f32_16x16x32_bf16 v[62:65], v[138:141], v[170:173], v[62:65]
	v_mfma_f32_16x16x32_bf16 v[58:61], v[146:149], v[170:173], v[58:61]
	v_mfma_f32_16x16x32_bf16 v[46:49], v[138:141], v[178:181], v[46:49]
	v_mfma_f32_16x16x32_bf16 v[42:45], v[146:149], v[178:181], v[42:45]
	v_mfma_f32_16x16x32_bf16 v[30:33], v[138:141], v[186:189], v[30:33]
	v_mfma_f32_16x16x32_bf16 v[26:29], v[146:149], v[186:189], v[26:29]
	v_mfma_f32_16x16x32_bf16 v[14:17], v[138:141], v[194:197], v[14:17]
	v_mfma_f32_16x16x32_bf16 v[10:13], v[146:149], v[194:197], v[10:13]
	v_mfma_f32_16x16x32_bf16 v[62:65], v[142:145], v[174:177], v[62:65]
	v_mfma_f32_16x16x32_bf16 v[58:61], v[150:153], v[174:177], v[58:61]
	v_mfma_f32_16x16x32_bf16 v[46:49], v[142:145], v[182:185], v[46:49]
	v_mfma_f32_16x16x32_bf16 v[42:45], v[150:153], v[182:185], v[42:45]
	v_mfma_f32_16x16x32_bf16 v[30:33], v[142:145], v[190:193], v[30:33]
	v_mfma_f32_16x16x32_bf16 v[26:29], v[150:153], v[190:193], v[26:29]
	v_mfma_f32_16x16x32_bf16 v[14:17], v[142:145], v[198:201], v[14:17]
	v_mfma_f32_16x16x32_bf16 v[10:13], v[150:153], v[198:201], v[10:13]
	s_setprio 0
	s_setprio 1
	v_mfma_f32_16x16x32_bf16 v[54:57], v[154:157], v[170:173], v[54:57]
	v_mfma_f32_16x16x32_bf16 v[50:53], v[162:165], v[170:173], v[50:53]
	v_mfma_f32_16x16x32_bf16 v[38:41], v[154:157], v[178:181], v[38:41]
	v_mfma_f32_16x16x32_bf16 v[34:37], v[162:165], v[178:181], v[34:37]
	v_mfma_f32_16x16x32_bf16 v[22:25], v[154:157], v[186:189], v[22:25]
	v_mfma_f32_16x16x32_bf16 v[18:21], v[162:165], v[186:189], v[18:21]
	v_mfma_f32_16x16x32_bf16 v[6:9], v[154:157], v[194:197], v[6:9]
	v_mfma_f32_16x16x32_bf16 v[2:5], v[162:165], v[194:197], v[2:5]
	v_mfma_f32_16x16x32_bf16 v[54:57], v[158:161], v[174:177], v[54:57]
	v_mfma_f32_16x16x32_bf16 v[50:53], v[166:169], v[174:177], v[50:53]
	v_mfma_f32_16x16x32_bf16 v[38:41], v[158:161], v[182:185], v[38:41]
	v_mfma_f32_16x16x32_bf16 v[34:37], v[166:169], v[182:185], v[34:37]
	v_mfma_f32_16x16x32_bf16 v[22:25], v[158:161], v[190:193], v[22:25]
	v_mfma_f32_16x16x32_bf16 v[18:21], v[166:169], v[190:193], v[18:21]
	v_mfma_f32_16x16x32_bf16 v[6:9], v[158:161], v[198:201], v[6:9]
	v_mfma_f32_16x16x32_bf16 v[2:5], v[166:169], v[198:201], v[2:5]
	s_setprio 0
	s_barrier
	s_add_i32 s47, 0, 0x18000
	s_add_i32 s50, 0, 0x1c000
	ds_read_b128 v[138:141], v0 offset:32768
	ds_read_b128 v[142:145], v0 offset:33792
	ds_read_b128 v[146:149], v0 offset:34816
	ds_read_b128 v[150:153], v0 offset:35840
	ds_read_b128 v[154:157], v0 offset:49152
	ds_read_b128 v[158:161], v0 offset:50176
	ds_read_b128 v[162:165], v0 offset:51200
	ds_read_b128 v[166:169], v0 offset:52224
	s_add_u32 s48, s10, 0x40000
	s_mov_b32 m0, s25
	ds_read_b128 v[170:173], v137 offset:32768
	ds_read_b128 v[174:177], v137 offset:33792
	ds_read_b128 v[178:181], v137 offset:34816
	ds_read_b128 v[182:185], v137 offset:35840
	ds_read_b128 v[186:189], v137 offset:36864
	ds_read_b128 v[190:193], v137 offset:37888
	ds_read_b128 v[194:197], v137 offset:38912
	ds_read_b128 v[198:201], v137 offset:39936
	s_addc_u32 s49, s11, 0
	s_nop 0
	global_load_lds_dwordx4 v130, s[48:49]
	s_mov_b32 m0, s26
	s_nop 0
	global_load_lds_dwordx4 v132, s[48:49]
	s_waitcnt vmcnt(8)
	s_waitcnt lgkmcnt(0)
	s_barrier
	s_setprio 1
	s_waitcnt lgkmcnt(0)
	v_mfma_f32_16x16x32_bf16 v[126:129], v[138:141], v[170:173], v[126:129]
	v_mfma_f32_16x16x32_bf16 v[122:125], v[146:149], v[170:173], v[122:125]
	v_mfma_f32_16x16x32_bf16 v[110:113], v[138:141], v[178:181], v[110:113]
	v_mfma_f32_16x16x32_bf16 v[106:109], v[146:149], v[178:181], v[106:109]
	v_mfma_f32_16x16x32_bf16 v[94:97], v[138:141], v[186:189], v[94:97]
	v_mfma_f32_16x16x32_bf16 v[90:93], v[146:149], v[186:189], v[90:93]
	v_mfma_f32_16x16x32_bf16 v[78:81], v[138:141], v[194:197], v[78:81]
	v_mfma_f32_16x16x32_bf16 v[74:77], v[146:149], v[194:197], v[74:77]
	v_mfma_f32_16x16x32_bf16 v[126:129], v[142:145], v[174:177], v[126:129]
	v_mfma_f32_16x16x32_bf16 v[122:125], v[150:153], v[174:177], v[122:125]
	v_mfma_f32_16x16x32_bf16 v[110:113], v[142:145], v[182:185], v[110:113]
	v_mfma_f32_16x16x32_bf16 v[106:109], v[150:153], v[182:185], v[106:109]
	v_mfma_f32_16x16x32_bf16 v[94:97], v[142:145], v[190:193], v[94:97]
	v_mfma_f32_16x16x32_bf16 v[90:93], v[150:153], v[190:193], v[90:93]
	v_mfma_f32_16x16x32_bf16 v[78:81], v[142:145], v[198:201], v[78:81]
	v_mfma_f32_16x16x32_bf16 v[74:77], v[150:153], v[198:201], v[74:77]
	s_setprio 0
	s_setprio 1
	v_mfma_f32_16x16x32_bf16 v[118:121], v[154:157], v[170:173], v[118:121]
	v_mfma_f32_16x16x32_bf16 v[114:117], v[162:165], v[170:173], v[114:117]
	v_mfma_f32_16x16x32_bf16 v[102:105], v[154:157], v[178:181], v[102:105]
	v_mfma_f32_16x16x32_bf16 v[98:101], v[162:165], v[178:181], v[98:101]
	v_mfma_f32_16x16x32_bf16 v[86:89], v[154:157], v[186:189], v[86:89]
	v_mfma_f32_16x16x32_bf16 v[82:85], v[162:165], v[186:189], v[82:85]
	v_mfma_f32_16x16x32_bf16 v[70:73], v[154:157], v[194:197], v[70:73]
	v_mfma_f32_16x16x32_bf16 v[66:69], v[162:165], v[194:197], v[66:69]
	v_mfma_f32_16x16x32_bf16 v[118:121], v[158:161], v[174:177], v[118:121]
	v_mfma_f32_16x16x32_bf16 v[114:117], v[166:169], v[174:177], v[114:117]
	v_mfma_f32_16x16x32_bf16 v[102:105], v[158:161], v[182:185], v[102:105]
	v_mfma_f32_16x16x32_bf16 v[98:101], v[166:169], v[182:185], v[98:101]
	v_mfma_f32_16x16x32_bf16 v[86:89], v[158:161], v[190:193], v[86:89]
	v_mfma_f32_16x16x32_bf16 v[82:85], v[166:169], v[190:193], v[82:85]
	v_mfma_f32_16x16x32_bf16 v[70:73], v[158:161], v[198:201], v[70:73]
	v_mfma_f32_16x16x32_bf16 v[66:69], v[166:169], v[198:201], v[66:69]
	s_setprio 0
	s_barrier
	ds_read_b128 v[170:173], v137 offset:49152
	ds_read_b128 v[174:177], v137 offset:50176
	ds_read_b128 v[178:181], v137 offset:51200
	ds_read_b128 v[182:185], v137 offset:52224
	ds_read_b128 v[186:189], v137 offset:53248
	ds_read_b128 v[190:193], v137 offset:54272
	ds_read_b128 v[194:197], v137 offset:55296
	ds_read_b128 v[198:201], v137 offset:56320
	s_add_i32 s47, s47, s22
	s_add_u32 s100, s12, s38
	s_addc_u32 s101, s13, s39
	s_mov_b32 m0, s47
	s_nop 0
	global_load_lds_dwordx4 v134, s[100:101]
	s_add_i32 m0, s47, 0x2000
	s_nop 0
	s_add_u32 s12, s12, 0x40080
	s_addc_u32 s13, s13, 0
	s_add_i32 s47, s50, s22
	global_load_lds_dwordx4 v135, s[100:101]
	s_mov_b32 m0, s47
	s_nop 0
	global_load_lds_dwordx4 v134, s[12:13]
	s_add_i32 m0, s47, 0x2000
	s_nop 0
	global_load_lds_dwordx4 v135, s[12:13]
	s_mov_b32 m0, s42
	s_add_u32 s100, s10, s38
	s_addc_u32 s101, s11, s39
	v_mov_b32_e32 v0, v132
	global_load_lds_dwordx4 v130, s[100:101]
	s_mov_b32 m0, s43
	s_nop 0
	global_load_lds_dwordx4 v132, s[100:101]
	s_waitcnt vmcnt(8)
	s_waitcnt lgkmcnt(0)
	s_barrier
	s_setprio 1
	s_waitcnt lgkmcnt(0)
	v_mfma_f32_16x16x32_bf16 v[62:65], v[138:141], v[170:173], v[62:65]
	v_mfma_f32_16x16x32_bf16 v[58:61], v[146:149], v[170:173], v[58:61]
	v_mfma_f32_16x16x32_bf16 v[46:49], v[138:141], v[178:181], v[46:49]
	v_mfma_f32_16x16x32_bf16 v[42:45], v[146:149], v[178:181], v[42:45]
	v_mfma_f32_16x16x32_bf16 v[30:33], v[138:141], v[186:189], v[30:33]
	v_mfma_f32_16x16x32_bf16 v[26:29], v[146:149], v[186:189], v[26:29]
	v_mfma_f32_16x16x32_bf16 v[14:17], v[138:141], v[194:197], v[14:17]
	v_mfma_f32_16x16x32_bf16 v[10:13], v[146:149], v[194:197], v[10:13]
	v_mfma_f32_16x16x32_bf16 v[62:65], v[142:145], v[174:177], v[62:65]
	v_mfma_f32_16x16x32_bf16 v[58:61], v[150:153], v[174:177], v[58:61]
	v_mfma_f32_16x16x32_bf16 v[46:49], v[142:145], v[182:185], v[46:49]
	v_mfma_f32_16x16x32_bf16 v[42:45], v[150:153], v[182:185], v[42:45]
	v_mfma_f32_16x16x32_bf16 v[30:33], v[142:145], v[190:193], v[30:33]
	v_mfma_f32_16x16x32_bf16 v[26:29], v[150:153], v[190:193], v[26:29]
	v_mfma_f32_16x16x32_bf16 v[14:17], v[142:145], v[198:201], v[14:17]
	v_mfma_f32_16x16x32_bf16 v[10:13], v[150:153], v[198:201], v[10:13]
	s_setprio 0
	s_setprio 1
	v_mfma_f32_16x16x32_bf16 v[54:57], v[154:157], v[170:173], v[54:57]
	v_mfma_f32_16x16x32_bf16 v[50:53], v[162:165], v[170:173], v[50:53]
	v_mfma_f32_16x16x32_bf16 v[38:41], v[154:157], v[178:181], v[38:41]
	v_mfma_f32_16x16x32_bf16 v[34:37], v[162:165], v[178:181], v[34:37]
	v_mfma_f32_16x16x32_bf16 v[22:25], v[154:157], v[186:189], v[22:25]
	v_mfma_f32_16x16x32_bf16 v[18:21], v[162:165], v[186:189], v[18:21]
	v_mfma_f32_16x16x32_bf16 v[6:9], v[154:157], v[194:197], v[6:9]
	v_mfma_f32_16x16x32_bf16 v[2:5], v[162:165], v[194:197], v[2:5]
	v_mfma_f32_16x16x32_bf16 v[54:57], v[158:161], v[174:177], v[54:57]
	v_mfma_f32_16x16x32_bf16 v[50:53], v[166:169], v[174:177], v[50:53]
	v_mfma_f32_16x16x32_bf16 v[38:41], v[158:161], v[182:185], v[38:41]
	v_mfma_f32_16x16x32_bf16 v[34:37], v[166:169], v[182:185], v[34:37]
	v_mfma_f32_16x16x32_bf16 v[22:25], v[158:161], v[190:193], v[22:25]
	v_mfma_f32_16x16x32_bf16 v[18:21], v[166:169], v[190:193], v[18:21]
	v_mfma_f32_16x16x32_bf16 v[6:9], v[158:161], v[198:201], v[6:9]
	v_mfma_f32_16x16x32_bf16 v[2:5], v[166:169], v[198:201], v[2:5]
	s_setprio 0
	s_barrier
	s_add_i32 s46, s46, 2
	s_add_u32 s2, s2, 0x100
	s_addc_u32 s3, s3, 0
	s_cmp_gt_u32 s46, 13
	s_cbranch_scc0 .LBB0_1681
.LBB0_1684:
	s_mov_b64 s[2:3], 0x6300000
	v_add_u32_e32 v130, s41, v133
	v_lshl_add_u32 v132, s14, 8, v130
	v_ashrrev_i32_e32 v133, 31, v132
	v_lshlrev_b64 v[132:133], 6, v[132:133]
	v_lshl_add_u64 v[142:143], s[4:5], 0, v[132:133]
	v_lshl_add_u64 v[132:133], v[142:143], 0, s[2:3]
	v_add_co_u32_e32 v142, vcc, 0x6300000, v142
	global_load_dwordx4 v[134:137], v[132:133], off offset:16 sc1
	global_load_dwordx4 v[138:141], v[132:133], off offset:32 sc1
	v_addc_co_u32_e32 v143, vcc, 0, v143, vcc
	global_load_dwordx4 v[142:145], v[142:143], off sc1
	s_nop 0
	global_load_dwordx4 v[146:149], v[132:133], off offset:48 sc1
	s_mov_b32 s2, 0xff61b1e6
	s_cmpk_lt_u32 s17, 0x100
	s_cbranch_scc0 .Lepi_lead_r6
	s_barrier
.Lepi_lead_r6:
	s_waitcnt vmcnt(0)
	v_mov_b32_e32 v154, v134
	v_mov_b32_e32 v151, v138
	v_mov_b32_e32 v153, v140
	v_mov_b32_e32 v134, v136
	v_mov_b32_e32 v150, v142
	v_mov_b32_e32 v138, v143
	v_mov_b32_e32 v152, v144
	v_mov_b32_e32 v140, v145
	v_mov_b32_e32 v155, v146
	v_mov_b32_e32 v146, v135
	v_mov_b32_e32 v135, v148
	v_mov_b32_e32 v148, v137
	v_pk_add_f32 v[136:137], v[150:151], v[138:139]
	v_pk_add_f32 v[138:139], v[152:153], v[140:141]
	v_pk_add_f32 v[140:141], v[154:155], v[146:147]
	v_pk_add_f32 v[134:135], v[134:135], v[148:149]
	v_pk_add_f32 v[136:137], v[136:137], v[138:139]
	v_pk_add_f32 v[134:135], v[140:141], v[134:135]
	s_nop 0
	v_pk_add_f32 v[134:135], v[136:137], v[134:135]
	s_nop 0
	v_add_f32_e32 v0, v134, v135
	v_fmamk_f32 v0, v0, 0x3a800000, v231
	v_rsq_f32_e32 v0, v0
	s_nop 0
	v_pk_mul_f32 v[128:129], v[128:129], v[0:1] op_sel_hi:[1,0]
	v_pk_mul_f32 v[124:125], v[124:125], v[0:1] op_sel_hi:[1,0]
	v_pk_mul_f32 v[126:127], v[126:127], v[0:1] op_sel_hi:[1,0]
	v_pk_mul_f32 v[122:123], v[122:123], v[0:1] op_sel_hi:[1,0]
	v_pk_mul_f32 v[120:121], v[120:121], v[0:1] op_sel_hi:[1,0]
	v_pk_mul_f32 v[118:119], v[118:119], v[0:1] op_sel_hi:[1,0]
	v_pk_mul_f32 v[116:117], v[116:117], v[0:1] op_sel_hi:[1,0]
	v_pk_mul_f32 v[114:115], v[114:115], v[0:1] op_sel_hi:[1,0]
	v_max_f32_e32 v0, v128, v129
	v_max_f32_e32 v134, v124, v125
	v_max_f32_e32 v135, v120, v121
	v_max_f32_e32 v136, v116, v117
	v_max3_f32 v0, v126, v127, v0
	v_max3_f32 v134, v122, v123, v134
	v_max3_f32 v135, v118, v119, v135
	v_max3_f32 v136, v114, v115, v136
	v_max3_f32 v0, v0, s2, v134
	v_max3_f32 v0, v0, v135, v136
	ds_swizzle_b32 v134, v0 offset:swizzle(SWAP,16)
	s_lshl_b32 s2, s16, 2
	s_add_i32 s8, s2, 0
	v_cmp_eq_u32_e64 s[2:3], 0, v131
	s_add_i32 s9, s8, 0x20000
	s_waitcnt lgkmcnt(0)
	v_max_f32_e32 v134, v134, v134
	v_max_f32_e32 v0, v0, v134
	v_mov_b32_e32 v134, v0
	s_nop 1
	v_permlane32_swap_b32_e32 v0, v134
	s_and_saveexec_b64 s[6:7], s[2:3]
	v_max_f32_e32 v0, v0, v0
	v_max_f32_e32 v134, v134, v134
	v_lshl_add_u32 v135, v130, 4, s9
	v_max_f32_e32 v0, v0, v134
	ds_write_b32 v135, v0
	s_or_b64 exec, exec, s[6:7]
	global_load_dwordx4 v[134:137], v[132:133], off offset:1024 sc1
	global_load_dwordx4 v[138:141], v[132:133], off offset:1056 sc1
	global_load_dwordx4 v[142:145], v[132:133], off offset:1040 sc1
	global_load_dwordx4 v[146:149], v[132:133], off offset:1072 sc1
	s_mov_b32 s6, 0xff61b1e6
	s_waitcnt vmcnt(3)
	v_mov_b32_e32 v150, v134
	s_waitcnt vmcnt(2)
	v_mov_b32_e32 v151, v138
	v_mov_b32_e32 v138, v135
	v_mov_b32_e32 v134, v136
	v_mov_b32_e32 v135, v140
	v_mov_b32_e32 v140, v137
	s_waitcnt vmcnt(1)
	v_mov_b32_e32 v136, v142
	s_waitcnt vmcnt(0)
	v_mov_b32_e32 v137, v146
	v_mov_b32_e32 v146, v143
	v_mov_b32_e32 v142, v144
	v_mov_b32_e32 v143, v148
	v_mov_b32_e32 v148, v145
	v_pk_add_f32 v[138:139], v[150:151], v[138:139]
	v_pk_add_f32 v[134:135], v[134:135], v[140:141]
	v_pk_add_f32 v[136:137], v[136:137], v[146:147]
	v_pk_add_f32 v[140:141], v[142:143], v[148:149]
	v_pk_add_f32 v[134:135], v[138:139], v[134:135]
	v_pk_add_f32 v[136:137], v[136:137], v[140:141]
	v_add_u32_e32 v140, 16, v130
	v_pk_add_f32 v[134:135], v[134:135], v[136:137]
	s_nop 0
	v_add_f32_e32 v0, v134, v135
	v_fmamk_f32 v0, v0, 0x3a800000, v231
	v_rsq_f32_e32 v0, v0
	s_nop 0
	v_pk_mul_f32 v[112:113], v[112:113], v[0:1] op_sel_hi:[1,0]
	v_pk_mul_f32 v[108:109], v[108:109], v[0:1] op_sel_hi:[1,0]
	v_pk_mul_f32 v[110:111], v[110:111], v[0:1] op_sel_hi:[1,0]
	v_pk_mul_f32 v[106:107], v[106:107], v[0:1] op_sel_hi:[1,0]
	v_pk_mul_f32 v[104:105], v[104:105], v[0:1] op_sel_hi:[1,0]
	v_pk_mul_f32 v[102:103], v[102:103], v[0:1] op_sel_hi:[1,0]
	v_pk_mul_f32 v[100:101], v[100:101], v[0:1] op_sel_hi:[1,0]
	v_pk_mul_f32 v[98:99], v[98:99], v[0:1] op_sel_hi:[1,0]
	v_max_f32_e32 v0, v112, v113
	v_max_f32_e32 v134, v108, v109
	v_max_f32_e32 v135, v104, v105
	v_max_f32_e32 v136, v100, v101
	v_max3_f32 v0, v110, v111, v0
	v_max3_f32 v134, v106, v107, v134
	v_max3_f32 v135, v102, v103, v135
	v_max3_f32 v136, v98, v99, v136
	v_max3_f32 v0, v0, s6, v134
	v_max3_f32 v0, v0, v135, v136
	ds_swizzle_b32 v134, v0 offset:swizzle(SWAP,16)
	s_waitcnt lgkmcnt(0)
	v_max_f32_e32 v134, v134, v134
	v_max_f32_e32 v0, v0, v134
	v_mov_b32_e32 v134, v0
	s_nop 1
	v_permlane32_swap_b32_e32 v0, v134
	s_and_saveexec_b64 s[6:7], s[2:3]
	v_max_f32_e32 v0, v0, v0
	v_max_f32_e32 v134, v134, v134
	v_lshl_add_u32 v135, v140, 4, s9
	v_max_f32_e32 v0, v0, v134
	ds_write_b32 v135, v0
	s_or_b64 exec, exec, s[6:7]
	global_load_dwordx4 v[134:137], v[132:133], off offset:2048 sc1
	global_load_dwordx4 v[142:145], v[132:133], off offset:2080 sc1
	global_load_dwordx4 v[146:149], v[132:133], off offset:2064 sc1
	global_load_dwordx4 v[150:153], v[132:133], off offset:2096 sc1
	s_mov_b32 s6, 0xff61b1e6
	v_add_u32_e32 v141, 32, v130
	s_waitcnt vmcnt(3)
	v_mov_b32_e32 v138, v134
	s_waitcnt vmcnt(2)
	v_mov_b32_e32 v139, v142
	v_mov_b32_e32 v142, v135
	v_mov_b32_e32 v134, v136
	v_mov_b32_e32 v135, v144
	v_mov_b32_e32 v144, v137
	s_waitcnt vmcnt(1)
	v_mov_b32_e32 v136, v146
	s_waitcnt vmcnt(0)
	v_mov_b32_e32 v137, v150
	v_mov_b32_e32 v150, v147
	v_mov_b32_e32 v146, v148
	v_mov_b32_e32 v147, v152
	v_mov_b32_e32 v152, v149
	v_pk_add_f32 v[138:139], v[138:139], v[142:143]
	v_pk_add_f32 v[134:135], v[134:135], v[144:145]
	v_pk_add_f32 v[136:137], v[136:137], v[150:151]
	v_pk_add_f32 v[142:143], v[146:147], v[152:153]
	v_pk_add_f32 v[134:135], v[138:139], v[134:135]
	v_pk_add_f32 v[136:137], v[136:137], v[142:143]
	s_nop 0
	v_pk_add_f32 v[134:135], v[134:135], v[136:137]
	s_nop 0
	v_add_f32_e32 v0, v134, v135
	v_fmamk_f32 v0, v0, 0x3a800000, v231
	v_rsq_f32_e32 v0, v0
	s_nop 0
	v_pk_mul_f32 v[96:97], v[96:97], v[0:1] op_sel_hi:[1,0]
	v_pk_mul_f32 v[92:93], v[92:93], v[0:1] op_sel_hi:[1,0]
	v_pk_mul_f32 v[94:95], v[94:95], v[0:1] op_sel_hi:[1,0]
	v_pk_mul_f32 v[90:91], v[90:91], v[0:1] op_sel_hi:[1,0]
	v_pk_mul_f32 v[88:89], v[88:89], v[0:1] op_sel_hi:[1,0]
	v_pk_mul_f32 v[86:87], v[86:87], v[0:1] op_sel_hi:[1,0]
	v_pk_mul_f32 v[84:85], v[84:85], v[0:1] op_sel_hi:[1,0]
	v_pk_mul_f32 v[82:83], v[82:83], v[0:1] op_sel_hi:[1,0]
	v_max_f32_e32 v0, v96, v97
	v_max_f32_e32 v134, v92, v93
	v_max_f32_e32 v135, v88, v89
	v_max_f32_e32 v136, v84, v85
	v_max3_f32 v0, v94, v95, v0
	v_max3_f32 v134, v90, v91, v134
	v_max3_f32 v135, v86, v87, v135
	v_max3_f32 v136, v82, v83, v136
	v_max3_f32 v0, v0, s6, v134
	v_max3_f32 v0, v0, v135, v136
	ds_swizzle_b32 v134, v0 offset:swizzle(SWAP,16)
	s_waitcnt lgkmcnt(0)
	v_max_f32_e32 v134, v134, v134
	v_max_f32_e32 v0, v0, v134
	v_mov_b32_e32 v134, v0
	s_nop 1
	v_permlane32_swap_b32_e32 v0, v134
	s_and_saveexec_b64 s[6:7], s[2:3]
	v_max_f32_e32 v0, v0, v0
	v_max_f32_e32 v134, v134, v134
	v_lshl_add_u32 v135, v141, 4, s9
	v_max_f32_e32 v0, v0, v134
	ds_write_b32 v135, v0
	s_or_b64 exec, exec, s[6:7]
	global_load_dwordx4 v[134:137], v[132:133], off offset:3072 sc1
	global_load_dwordx4 v[142:145], v[132:133], off offset:3104 sc1
	global_load_dwordx4 v[146:149], v[132:133], off offset:3088 sc1
	global_load_dwordx4 v[150:153], v[132:133], off offset:3120 sc1
	s_mov_b32 s6, 0xff61b1e6
	s_waitcnt vmcnt(3)
	v_mov_b32_e32 v138, v134
	s_waitcnt vmcnt(2)
	v_mov_b32_e32 v139, v142
	v_mov_b32_e32 v142, v135
	v_mov_b32_e32 v134, v136
	v_mov_b32_e32 v135, v144
	v_mov_b32_e32 v144, v137
	s_waitcnt vmcnt(1)
	v_mov_b32_e32 v136, v146
	s_waitcnt vmcnt(0)
	v_mov_b32_e32 v137, v150
	v_mov_b32_e32 v150, v147
	v_mov_b32_e32 v146, v148
	v_mov_b32_e32 v147, v152
	v_mov_b32_e32 v152, v149
	v_pk_add_f32 v[138:139], v[138:139], v[142:143]
	v_pk_add_f32 v[134:135], v[134:135], v[144:145]
	v_pk_add_f32 v[136:137], v[136:137], v[150:151]
	v_pk_add_f32 v[142:143], v[146:147], v[152:153]
	v_pk_add_f32 v[134:135], v[138:139], v[134:135]
	v_pk_add_f32 v[136:137], v[136:137], v[142:143]
	v_add_u32_e32 v142, 48, v130
	v_pk_add_f32 v[134:135], v[134:135], v[136:137]
	s_nop 0
	v_add_f32_e32 v0, v134, v135
	v_fmamk_f32 v0, v0, 0x3a800000, v231
	v_rsq_f32_e32 v0, v0
	s_nop 0
	v_pk_mul_f32 v[80:81], v[80:81], v[0:1] op_sel_hi:[1,0]
	v_pk_mul_f32 v[76:77], v[76:77], v[0:1] op_sel_hi:[1,0]
	v_pk_mul_f32 v[78:79], v[78:79], v[0:1] op_sel_hi:[1,0]
	v_pk_mul_f32 v[74:75], v[74:75], v[0:1] op_sel_hi:[1,0]
	v_pk_mul_f32 v[72:73], v[72:73], v[0:1] op_sel_hi:[1,0]
	v_pk_mul_f32 v[70:71], v[70:71], v[0:1] op_sel_hi:[1,0]
	v_pk_mul_f32 v[68:69], v[68:69], v[0:1] op_sel_hi:[1,0]
	v_pk_mul_f32 v[66:67], v[66:67], v[0:1] op_sel_hi:[1,0]
	v_max_f32_e32 v0, v80, v81
	v_max_f32_e32 v134, v76, v77
	v_max_f32_e32 v135, v72, v73
	v_max_f32_e32 v136, v68, v69
	v_max3_f32 v0, v78, v79, v0
	v_max3_f32 v134, v74, v75, v134
	v_max3_f32 v135, v70, v71, v135
	v_max3_f32 v136, v66, v67, v136
	v_max3_f32 v0, v0, s6, v134
	v_max3_f32 v0, v0, v135, v136
	ds_swizzle_b32 v134, v0 offset:swizzle(SWAP,16)
	s_waitcnt lgkmcnt(0)
	v_max_f32_e32 v134, v134, v134
	v_max_f32_e32 v0, v0, v134
	v_mov_b32_e32 v134, v0
	s_nop 1
	v_permlane32_swap_b32_e32 v0, v134
	s_and_saveexec_b64 s[6:7], s[2:3]
	v_max_f32_e32 v0, v0, v0
	v_max_f32_e32 v134, v134, v134
	v_lshl_add_u32 v135, v142, 4, s9
	v_max_f32_e32 v0, v0, v134
	ds_write_b32 v135, v0
	s_or_b64 exec, exec, s[6:7]
	v_add_co_u32_e32 v134, vcc, 0x2000, v132
	s_mov_b64 s[6:7], 0x2000
	s_nop 0
	v_addc_co_u32_e32 v135, vcc, 0, v133, vcc
	v_lshl_add_u64 v[138:139], v[132:133], 0, s[6:7]
	global_load_dwordx4 v[134:137], v[134:135], off sc1
	s_nop 0
	global_load_dwordx4 v[144:147], v[138:139], off offset:16 sc1
	global_load_dwordx4 v[148:151], v[138:139], off offset:48 sc1
	global_load_dwordx4 v[152:155], v[138:139], off offset:32 sc1
	s_mov_b32 s6, 0xff61b1e6
	v_add_u32_e32 v0, 0x80, v130
	s_waitcnt vmcnt(3)
	v_mov_b32_e32 v138, v134
	s_waitcnt vmcnt(0)
	v_mov_b32_e32 v139, v152
	v_mov_b32_e32 v152, v135
	v_pk_add_f32 v[134:135], v[138:139], v[152:153]
	v_mov_b32_e32 v138, v136
	v_mov_b32_e32 v139, v154
	v_mov_b32_e32 v154, v137
	v_pk_add_f32 v[136:137], v[138:139], v[154:155]
	v_mov_b32_e32 v138, v146
	v_pk_add_f32 v[134:135], v[134:135], v[136:137]
	v_mov_b32_e32 v136, v144
	v_mov_b32_e32 v137, v148
	v_mov_b32_e32 v148, v145
	v_mov_b32_e32 v139, v150
	v_mov_b32_e32 v150, v147
	v_pk_add_f32 v[136:137], v[136:137], v[148:149]
	v_pk_add_f32 v[138:139], v[138:139], v[150:151]
	s_nop 0
	v_pk_add_f32 v[136:137], v[136:137], v[138:139]
	s_nop 0
	v_pk_add_f32 v[134:135], v[134:135], v[136:137]
	s_nop 0
	v_add_f32_e32 v134, v134, v135
	v_fmamk_f32 v134, v134, 0x3a800000, v231
	v_rsq_f32_e32 v134, v134
	s_nop 0
	v_pk_mul_f32 v[64:65], v[64:65], v[134:135] op_sel_hi:[1,0]
	v_pk_mul_f32 v[62:63], v[62:63], v[134:135] op_sel_hi:[1,0]
	v_max_f32_e32 v135, v64, v65
	v_max3_f32 v135, v62, v63, v135
	v_pk_mul_f32 v[60:61], v[60:61], v[134:135] op_sel_hi:[1,0]
	v_pk_mul_f32 v[58:59], v[58:59], v[134:135] op_sel_hi:[1,0]
	v_max_f32_e32 v136, v60, v61
	v_max3_f32 v136, v58, v59, v136
	v_max3_f32 v135, v135, s6, v136
	v_pk_mul_f32 v[56:57], v[56:57], v[134:135] op_sel_hi:[1,0]
	v_pk_mul_f32 v[52:53], v[52:53], v[134:135] op_sel_hi:[1,0]
	v_pk_mul_f32 v[54:55], v[54:55], v[134:135] op_sel_hi:[1,0]
	v_max_f32_e32 v136, v56, v57
	v_pk_mul_f32 v[50:51], v[50:51], v[134:135] op_sel_hi:[1,0]
	v_max_f32_e32 v134, v52, v53
	v_max3_f32 v136, v54, v55, v136
	v_max3_f32 v134, v50, v51, v134
	v_max3_f32 v134, v135, v136, v134
	ds_swizzle_b32 v135, v134 offset:swizzle(SWAP,16)
	s_waitcnt lgkmcnt(0)
	v_max_f32_e32 v135, v135, v135
	v_max_f32_e32 v134, v134, v135
	v_mov_b32_e32 v135, v134
	s_nop 1
	v_permlane32_swap_b32_e32 v134, v135
	s_and_saveexec_b64 s[6:7], s[2:3]
	v_max_f32_e32 v134, v134, v134
	v_max_f32_e32 v135, v135, v135
	v_lshl_add_u32 v136, v0, 4, s9
	v_max_f32_e32 v134, v134, v135
	ds_write_b32 v136, v134
	s_or_b64 exec, exec, s[6:7]
	v_add_co_u32_e32 v134, vcc, 0x2000, v132
	s_mov_b64 s[6:7], 0x2400
	s_nop 0
	v_addc_co_u32_e32 v135, vcc, 0, v133, vcc
	v_lshl_add_u64 v[138:139], v[132:133], 0, s[6:7]
	global_load_dwordx4 v[134:137], v[134:135], off offset:1024 sc1
	s_nop 0
	global_load_dwordx4 v[144:147], v[138:139], off offset:16 sc1
	global_load_dwordx4 v[148:151], v[138:139], off offset:48 sc1
	global_load_dwordx4 v[152:155], v[138:139], off offset:32 sc1
	s_mov_b32 s6, 0xff61b1e6
	v_add_u32_e32 v143, 0x90, v130
	s_waitcnt vmcnt(3)
	v_mov_b32_e32 v138, v134
	s_waitcnt vmcnt(0)
	v_mov_b32_e32 v139, v152
	v_mov_b32_e32 v152, v135
	v_pk_add_f32 v[134:135], v[138:139], v[152:153]
	v_mov_b32_e32 v138, v136
	v_mov_b32_e32 v139, v154
	v_mov_b32_e32 v154, v137
	v_pk_add_f32 v[136:137], v[138:139], v[154:155]
	v_mov_b32_e32 v138, v146
	v_pk_add_f32 v[134:135], v[134:135], v[136:137]
	v_mov_b32_e32 v136, v144
	v_mov_b32_e32 v137, v148
	v_mov_b32_e32 v148, v145
	v_mov_b32_e32 v139, v150
	v_mov_b32_e32 v150, v147
	v_pk_add_f32 v[136:137], v[136:137], v[148:149]
	v_pk_add_f32 v[138:139], v[138:139], v[150:151]
	s_nop 0
	v_pk_add_f32 v[136:137], v[136:137], v[138:139]
	s_nop 0
	v_pk_add_f32 v[134:135], v[134:135], v[136:137]
	s_nop 0
	v_add_f32_e32 v134, v134, v135
	v_fmamk_f32 v134, v134, 0x3a800000, v231
	v_rsq_f32_e32 v134, v134
	s_nop 0
	v_pk_mul_f32 v[48:49], v[48:49], v[134:135] op_sel_hi:[1,0]
	v_pk_mul_f32 v[46:47], v[46:47], v[134:135] op_sel_hi:[1,0]
	v_max_f32_e32 v135, v48, v49
	v_max3_f32 v135, v46, v47, v135
	v_pk_mul_f32 v[44:45], v[44:45], v[134:135] op_sel_hi:[1,0]
	v_pk_mul_f32 v[42:43], v[42:43], v[134:135] op_sel_hi:[1,0]
	v_max_f32_e32 v136, v44, v45
	v_max3_f32 v136, v42, v43, v136
	v_max3_f32 v135, v135, s6, v136
	v_pk_mul_f32 v[40:41], v[40:41], v[134:135] op_sel_hi:[1,0]
	v_pk_mul_f32 v[36:37], v[36:37], v[134:135] op_sel_hi:[1,0]
	v_pk_mul_f32 v[38:39], v[38:39], v[134:135] op_sel_hi:[1,0]
	v_max_f32_e32 v136, v40, v41
	v_pk_mul_f32 v[34:35], v[34:35], v[134:135] op_sel_hi:[1,0]
	v_max_f32_e32 v134, v36, v37
	v_max3_f32 v136, v38, v39, v136
	v_max3_f32 v134, v34, v35, v134
	v_max3_f32 v134, v135, v136, v134
	ds_swizzle_b32 v135, v134 offset:swizzle(SWAP,16)
	s_waitcnt lgkmcnt(0)
	v_max_f32_e32 v135, v135, v135
	v_max_f32_e32 v134, v134, v135
	v_mov_b32_e32 v135, v134
	s_nop 1
	v_permlane32_swap_b32_e32 v134, v135
	s_and_saveexec_b64 s[6:7], s[2:3]
	v_max_f32_e32 v134, v134, v134
	v_max_f32_e32 v135, v135, v135
	v_lshl_add_u32 v136, v143, 4, s9
	v_max_f32_e32 v134, v134, v135
	ds_write_b32 v136, v134
	s_or_b64 exec, exec, s[6:7]
	v_add_co_u32_e32 v134, vcc, 0x2000, v132
	s_mov_b64 s[6:7], 0x2800
	s_nop 0
	v_addc_co_u32_e32 v135, vcc, 0, v133, vcc
	v_lshl_add_u64 v[138:139], v[132:133], 0, s[6:7]
	global_load_dwordx4 v[134:137], v[134:135], off offset:2048 sc1
	s_nop 0
	global_load_dwordx4 v[144:147], v[138:139], off offset:16 sc1
	global_load_dwordx4 v[148:151], v[138:139], off offset:48 sc1
	global_load_dwordx4 v[152:155], v[138:139], off offset:32 sc1
	s_mov_b32 s6, 0xff61b1e6
	s_waitcnt vmcnt(3)
	v_mov_b32_e32 v138, v134
	s_waitcnt vmcnt(0)
	v_mov_b32_e32 v139, v152
	v_mov_b32_e32 v152, v135
	v_pk_add_f32 v[134:135], v[138:139], v[152:153]
	v_mov_b32_e32 v138, v136
	v_mov_b32_e32 v139, v154
	v_mov_b32_e32 v154, v137
	v_pk_add_f32 v[136:137], v[138:139], v[154:155]
	v_mov_b32_e32 v138, v146
	v_pk_add_f32 v[134:135], v[134:135], v[136:137]
	v_mov_b32_e32 v136, v144
	v_mov_b32_e32 v137, v148
	v_mov_b32_e32 v148, v145
	v_mov_b32_e32 v139, v150
	v_mov_b32_e32 v150, v147
	v_pk_add_f32 v[136:137], v[136:137], v[148:149]
	v_pk_add_f32 v[138:139], v[138:139], v[150:151]
	v_add_u32_e32 v144, 0xa0, v130
	v_pk_add_f32 v[136:137], v[136:137], v[138:139]
	s_nop 0
	v_pk_add_f32 v[134:135], v[134:135], v[136:137]
	s_nop 0
	v_add_f32_e32 v134, v134, v135
	v_fmamk_f32 v134, v134, 0x3a800000, v231
	v_rsq_f32_e32 v134, v134
	s_nop 0
	v_pk_mul_f32 v[32:33], v[32:33], v[134:135] op_sel_hi:[1,0]
	v_pk_mul_f32 v[30:31], v[30:31], v[134:135] op_sel_hi:[1,0]
	v_max_f32_e32 v135, v32, v33
	v_max3_f32 v135, v30, v31, v135
	v_pk_mul_f32 v[28:29], v[28:29], v[134:135] op_sel_hi:[1,0]
	v_pk_mul_f32 v[26:27], v[26:27], v[134:135] op_sel_hi:[1,0]
	v_max_f32_e32 v136, v28, v29
	v_max3_f32 v136, v26, v27, v136
	v_max3_f32 v135, v135, s6, v136
	v_pk_mul_f32 v[24:25], v[24:25], v[134:135] op_sel_hi:[1,0]
	v_pk_mul_f32 v[20:21], v[20:21], v[134:135] op_sel_hi:[1,0]
	v_pk_mul_f32 v[22:23], v[22:23], v[134:135] op_sel_hi:[1,0]
	v_max_f32_e32 v136, v24, v25
	v_pk_mul_f32 v[18:19], v[18:19], v[134:135] op_sel_hi:[1,0]
	v_max_f32_e32 v134, v20, v21
	v_max3_f32 v136, v22, v23, v136
	v_max3_f32 v134, v18, v19, v134
	v_max3_f32 v134, v135, v136, v134
	ds_swizzle_b32 v135, v134 offset:swizzle(SWAP,16)
	s_waitcnt lgkmcnt(0)
	v_max_f32_e32 v135, v135, v135
	v_max_f32_e32 v134, v134, v135
	v_mov_b32_e32 v135, v134
	s_nop 1
	v_permlane32_swap_b32_e32 v134, v135
	s_and_saveexec_b64 s[6:7], s[2:3]
	v_max_f32_e32 v134, v134, v134
	v_max_f32_e32 v135, v135, v135
	v_lshl_add_u32 v136, v144, 4, s9
	v_max_f32_e32 v134, v134, v135
	ds_write_b32 v136, v134
	s_or_b64 exec, exec, s[6:7]
	s_mov_b64 s[6:7], 0x2c00
	v_lshl_add_u64 v[150:151], v[132:133], 0, s[6:7]
	v_add_co_u32_e32 v132, vcc, 0x2000, v132
	s_mov_b32 s6, 0xff61b1e6
	s_nop 0
	v_addc_co_u32_e32 v133, vcc, 0, v133, vcc
	global_load_dwordx4 v[132:135], v[132:133], off offset:3072 sc1
	s_nop 0
	global_load_dwordx4 v[136:139], v[150:151], off offset:16 sc1
	global_load_dwordx4 v[146:149], v[150:151], off offset:48 sc1
	s_nop 0
	global_load_dwordx4 v[150:153], v[150:151], off offset:32 sc1
	v_add_u32_e32 v145, 0xb0, v130
	s_waitcnt vmcnt(3)
	v_mov_b32_e32 v154, v132
	s_waitcnt vmcnt(0)
	v_mov_b32_e32 v155, v150
	v_mov_b32_e32 v150, v133
	v_pk_add_f32 v[132:133], v[154:155], v[150:151]
	v_mov_b32_e32 v150, v134
	v_mov_b32_e32 v151, v152
	v_mov_b32_e32 v152, v135
	v_pk_add_f32 v[134:135], v[150:151], v[152:153]
	s_nop 0
	v_pk_add_f32 v[132:133], v[132:133], v[134:135]
	v_mov_b32_e32 v134, v136
	v_mov_b32_e32 v135, v146
	v_mov_b32_e32 v146, v137
	v_mov_b32_e32 v136, v138
	v_mov_b32_e32 v137, v148
	v_mov_b32_e32 v148, v139
	v_pk_add_f32 v[134:135], v[134:135], v[146:147]
	v_pk_add_f32 v[136:137], v[136:137], v[148:149]
	s_nop 0
	v_pk_add_f32 v[134:135], v[134:135], v[136:137]
	s_nop 0
	v_pk_add_f32 v[132:133], v[132:133], v[134:135]
	s_nop 0
	v_add_f32_e32 v132, v132, v133
	v_fmamk_f32 v132, v132, 0x3a800000, v231
	v_rsq_f32_e32 v134, v132
	s_nop 0
	v_pk_mul_f32 v[16:17], v[16:17], v[134:135] op_sel_hi:[1,0]
	v_pk_mul_f32 v[14:15], v[14:15], v[134:135] op_sel_hi:[1,0]
	v_max_f32_e32 v132, v16, v17
	v_max3_f32 v135, v14, v15, v132
	v_pk_mul_f32 v[132:133], v[12:13], v[134:135] op_sel_hi:[1,0]
	v_pk_mul_f32 v[12:13], v[10:11], v[134:135] op_sel_hi:[1,0]
	v_max_f32_e32 v10, v132, v133
	v_max3_f32 v10, v12, v13, v10
	v_pk_mul_f32 v[136:137], v[8:9], v[134:135] op_sel_hi:[1,0]
	v_pk_mul_f32 v[138:139], v[4:5], v[134:135] op_sel_hi:[1,0]
	v_max3_f32 v10, v135, s6, v10
	v_pk_mul_f32 v[8:9], v[6:7], v[134:135] op_sel_hi:[1,0]
	v_max_f32_e32 v6, v136, v137
	v_pk_mul_f32 v[134:135], v[2:3], v[134:135] op_sel_hi:[1,0]
	v_max_f32_e32 v2, v138, v139
	v_max3_f32 v6, v8, v9, v6
	v_max3_f32 v2, v134, v135, v2
	v_max3_f32 v2, v10, v6, v2
	ds_swizzle_b32 v3, v2 offset:swizzle(SWAP,16)
	s_waitcnt lgkmcnt(0)
	v_max_f32_e32 v3, v3, v3
	v_max_f32_e32 v2, v2, v3
	v_mov_b32_e32 v3, v2
	s_nop 1
	v_permlane32_swap_b32_e32 v2, v3
	s_and_saveexec_b64 s[6:7], s[2:3]
	v_max_f32_e32 v2, v2, v2
	v_max_f32_e32 v3, v3, v3
	v_lshl_add_u32 v4, v145, 4, s9
	v_max_f32_e32 v2, v2, v3
	ds_write_b32 v4, v2
	s_or_b64 exec, exec, s[6:7]
	v_lshl_add_u32 v2, v130, 4, 0
	s_waitcnt lgkmcnt(0)
	s_barrier
	v_add_u32_e32 v2, 0x20000, v2
	ds_read_b128 v[4:7], v2
	s_add_i32 s8, s8, 0x21000
	s_waitcnt lgkmcnt(0)
	v_max_f32_e32 v3, v7, v7
	v_max_f32_e32 v6, v6, v6
	v_max_f32_e32 v3, v6, v3
	v_max3_f32 v3, v4, v5, v3
	v_sub_f32_e32 v4, v129, v3
	v_sub_f32_e32 v5, v128, v3
	v_sub_f32_e32 v6, v127, v3
	v_sub_f32_e32 v7, v126, v3
	v_exp_f32_e32 v126, v7
	v_exp_f32_e32 v127, v6
	v_exp_f32_e32 v128, v5
	v_exp_f32_e32 v129, v4
	v_sub_f32_e32 v6, v125, v3
	v_sub_f32_e32 v7, v124, v3
	v_sub_f32_e32 v10, v123, v3
	v_sub_f32_e32 v11, v122, v3
	v_exp_f32_e32 v122, v11
	v_exp_f32_e32 v123, v10
	v_exp_f32_e32 v124, v7
	v_exp_f32_e32 v125, v6
	v_sub_f32_e32 v7, v121, v3
	v_sub_f32_e32 v10, v120, v3
	v_sub_f32_e32 v11, v119, v3
	v_sub_f32_e32 v118, v118, v3
	v_exp_f32_e32 v118, v118
	v_exp_f32_e32 v119, v11
	v_exp_f32_e32 v120, v10
	v_exp_f32_e32 v121, v7
	v_add_f32_e32 v4, v126, v127
	v_add_f32_e32 v5, v128, v129
	v_sub_f32_e32 v7, v117, v3
	v_sub_f32_e32 v10, v116, v3
	v_sub_f32_e32 v11, v115, v3
	v_sub_f32_e32 v3, v114, v3
	v_add_f32_e32 v4, v4, v5
	v_add_f32_e32 v5, v122, v123
	v_add_f32_e32 v6, v124, v125
	v_exp_f32_e32 v114, v3
	v_exp_f32_e32 v115, v11
	v_exp_f32_e32 v116, v10
	v_exp_f32_e32 v117, v7
	v_add_f32_e32 v4, 0, v4
	v_add_f32_e32 v5, v5, v6
	v_add_f32_e32 v4, v5, v4
	v_add_f32_e32 v5, v118, v119
	v_add_f32_e32 v6, v120, v121
	v_add_f32_e32 v3, v5, v6
	v_add_f32_e32 v3, v3, v4
	v_add_f32_e32 v4, v114, v115
	v_add_f32_e32 v5, v116, v117
	v_add_f32_e32 v4, v4, v5
	v_add_f32_e32 v3, v4, v3
	ds_swizzle_b32 v4, v3 offset:swizzle(SWAP,16)
	v_lshlrev_b32_e32 v5, 2, v130
	v_lshl_add_u32 v146, v5, 2, s8
	s_waitcnt lgkmcnt(0)
	v_add_f32_e32 v3, v3, v4
	v_mov_b32_e32 v4, v3
	s_nop 1
	v_permlane32_swap_b32_e32 v3, v4
	s_and_saveexec_b64 s[6:7], s[2:3]
	v_add_f32_e32 v3, v3, v4
	ds_write_b32 v146, v3
	s_or_b64 exec, exec, s[6:7]
	ds_read_b128 v[4:7], v2 offset:256
	s_waitcnt lgkmcnt(0)
	v_max_f32_e32 v3, v7, v7
	v_max_f32_e32 v6, v6, v6
	v_max_f32_e32 v3, v6, v3
	v_max3_f32 v3, v4, v5, v3
	v_sub_f32_e32 v4, v113, v3
	v_sub_f32_e32 v5, v112, v3
	v_sub_f32_e32 v6, v111, v3
	v_sub_f32_e32 v7, v110, v3
	v_exp_f32_e32 v110, v7
	v_exp_f32_e32 v111, v6
	v_exp_f32_e32 v112, v5
	v_exp_f32_e32 v113, v4
	v_sub_f32_e32 v6, v109, v3
	v_sub_f32_e32 v7, v108, v3
	v_sub_f32_e32 v10, v107, v3
	v_sub_f32_e32 v11, v106, v3
	v_exp_f32_e32 v106, v11
	v_exp_f32_e32 v107, v10
	v_exp_f32_e32 v108, v7
	v_exp_f32_e32 v109, v6
	v_sub_f32_e32 v7, v105, v3
	v_sub_f32_e32 v10, v104, v3
	v_sub_f32_e32 v11, v103, v3
	v_sub_f32_e32 v102, v102, v3
	v_exp_f32_e32 v102, v102
	v_exp_f32_e32 v103, v11
	v_exp_f32_e32 v104, v10
	v_exp_f32_e32 v105, v7
	v_add_f32_e32 v4, v110, v111
	v_add_f32_e32 v5, v112, v113
	v_sub_f32_e32 v7, v101, v3
	v_sub_f32_e32 v10, v100, v3
	v_sub_f32_e32 v11, v99, v3
	v_sub_f32_e32 v3, v98, v3
	v_add_f32_e32 v4, v4, v5
	v_add_f32_e32 v5, v106, v107
	v_add_f32_e32 v6, v108, v109
	v_exp_f32_e32 v98, v3
	v_exp_f32_e32 v99, v11
	v_exp_f32_e32 v100, v10
	v_exp_f32_e32 v101, v7
	v_add_f32_e32 v4, 0, v4
	v_add_f32_e32 v5, v5, v6
	v_add_f32_e32 v4, v5, v4
	v_add_f32_e32 v5, v102, v103
	v_add_f32_e32 v6, v104, v105
	v_add_f32_e32 v3, v5, v6
	v_add_f32_e32 v3, v3, v4
	v_add_f32_e32 v4, v98, v99
	v_add_f32_e32 v5, v100, v101
	v_add_f32_e32 v4, v4, v5
	v_add_f32_e32 v3, v4, v3
	ds_swizzle_b32 v4, v3 offset:swizzle(SWAP,16)
	s_waitcnt lgkmcnt(0)
	v_add_f32_e32 v3, v3, v4
	v_mov_b32_e32 v4, v3
	s_nop 1
	v_permlane32_swap_b32_e32 v3, v4
	s_and_saveexec_b64 s[6:7], s[2:3]
	v_add_f32_e32 v3, v3, v4
	ds_write_b32 v146, v3 offset:256
	s_or_b64 exec, exec, s[6:7]
	v_mad_u64_u32 v[4:5], s[6:7], v130, 3, v[0:1]
	v_lshl_add_u32 v3, v4, 2, 0
	v_add_u32_e32 v3, 0x20000, v3
	ds_read_b128 v[4:7], v3
	s_waitcnt lgkmcnt(0)
	v_max_f32_e32 v3, v7, v7
	v_max_f32_e32 v6, v6, v6
	v_max_f32_e32 v3, v6, v3
	v_max3_f32 v3, v4, v5, v3
	v_sub_f32_e32 v4, v97, v3
	v_sub_f32_e32 v5, v96, v3
	v_sub_f32_e32 v6, v95, v3
	v_sub_f32_e32 v7, v94, v3
	v_exp_f32_e32 v94, v7
	v_exp_f32_e32 v95, v6
	v_exp_f32_e32 v96, v5
	v_exp_f32_e32 v97, v4
	v_sub_f32_e32 v6, v93, v3
	v_sub_f32_e32 v7, v92, v3
	v_sub_f32_e32 v10, v91, v3
	v_sub_f32_e32 v11, v90, v3
	v_exp_f32_e32 v90, v11
	v_exp_f32_e32 v91, v10
	v_exp_f32_e32 v92, v7
	v_exp_f32_e32 v93, v6
	v_sub_f32_e32 v7, v89, v3
	v_sub_f32_e32 v10, v88, v3
	v_sub_f32_e32 v11, v87, v3
	v_sub_f32_e32 v86, v86, v3
	v_exp_f32_e32 v86, v86
	v_exp_f32_e32 v87, v11
	v_exp_f32_e32 v88, v10
	v_exp_f32_e32 v89, v7
	v_add_f32_e32 v4, v94, v95
	v_add_f32_e32 v5, v96, v97
	v_sub_f32_e32 v7, v85, v3
	v_sub_f32_e32 v10, v84, v3
	v_sub_f32_e32 v11, v83, v3
	v_sub_f32_e32 v3, v82, v3
	v_add_f32_e32 v4, v4, v5
	v_add_f32_e32 v5, v90, v91
	v_add_f32_e32 v6, v92, v93
	v_exp_f32_e32 v82, v3
	v_exp_f32_e32 v83, v11
	v_exp_f32_e32 v84, v10
	v_exp_f32_e32 v85, v7
	v_add_f32_e32 v4, 0, v4
	v_add_f32_e32 v5, v5, v6
	v_add_f32_e32 v4, v5, v4
	v_add_f32_e32 v5, v86, v87
	v_add_f32_e32 v6, v88, v89
	v_add_f32_e32 v3, v5, v6
	v_add_f32_e32 v3, v3, v4
	v_add_f32_e32 v4, v82, v83
	v_add_f32_e32 v5, v84, v85
	v_add_f32_e32 v4, v4, v5
	v_add_f32_e32 v3, v4, v3
	ds_swizzle_b32 v4, v3 offset:swizzle(SWAP,16)
	s_waitcnt lgkmcnt(0)
	v_add_f32_e32 v3, v3, v4
	v_mov_b32_e32 v4, v3
	s_nop 1
	v_permlane32_swap_b32_e32 v3, v4
	s_and_saveexec_b64 s[6:7], s[2:3]
	v_add_f32_e32 v3, v3, v4
	ds_write_b32 v146, v3 offset:512
	s_or_b64 exec, exec, s[6:7]
	ds_read_b128 v[4:7], v2 offset:768
	s_waitcnt lgkmcnt(0)
	v_max_f32_e32 v3, v7, v7
	v_max_f32_e32 v6, v6, v6
	v_max_f32_e32 v3, v6, v3
	v_max3_f32 v3, v4, v5, v3
	v_sub_f32_e32 v4, v81, v3
	v_sub_f32_e32 v5, v80, v3
	v_sub_f32_e32 v6, v79, v3
	v_sub_f32_e32 v7, v78, v3
	v_exp_f32_e32 v78, v7
	v_exp_f32_e32 v79, v6
	v_exp_f32_e32 v80, v5
	v_exp_f32_e32 v81, v4
	v_sub_f32_e32 v6, v77, v3
	v_sub_f32_e32 v7, v76, v3
	v_sub_f32_e32 v10, v75, v3
	v_sub_f32_e32 v11, v74, v3
	v_exp_f32_e32 v74, v11
	v_exp_f32_e32 v75, v10
	v_exp_f32_e32 v76, v7
	v_exp_f32_e32 v77, v6
	v_sub_f32_e32 v7, v73, v3
	v_sub_f32_e32 v10, v72, v3
	v_sub_f32_e32 v11, v71, v3
	v_sub_f32_e32 v70, v70, v3
	v_exp_f32_e32 v70, v70
	v_exp_f32_e32 v71, v11
	v_exp_f32_e32 v72, v10
	v_exp_f32_e32 v73, v7
	v_add_f32_e32 v4, v78, v79
	v_add_f32_e32 v5, v80, v81
	v_sub_f32_e32 v7, v69, v3
	v_sub_f32_e32 v10, v68, v3
	v_sub_f32_e32 v11, v67, v3
	v_sub_f32_e32 v3, v66, v3
	v_add_f32_e32 v4, v4, v5
	v_add_f32_e32 v5, v74, v75
	v_add_f32_e32 v6, v76, v77
	v_exp_f32_e32 v66, v3
	v_exp_f32_e32 v67, v11
	v_exp_f32_e32 v68, v10
	v_exp_f32_e32 v69, v7
	v_add_f32_e32 v4, 0, v4
	v_add_f32_e32 v5, v5, v6
	v_add_f32_e32 v4, v5, v4
	v_add_f32_e32 v5, v70, v71
	v_add_f32_e32 v6, v72, v73
	v_add_f32_e32 v3, v5, v6
	v_add_f32_e32 v3, v3, v4
	v_add_f32_e32 v4, v66, v67
	v_add_f32_e32 v5, v68, v69
	v_add_f32_e32 v4, v4, v5
	v_add_f32_e32 v3, v4, v3
	ds_swizzle_b32 v4, v3 offset:swizzle(SWAP,16)
	s_waitcnt lgkmcnt(0)
	v_add_f32_e32 v3, v3, v4
	v_mov_b32_e32 v4, v3
	s_nop 1
	v_permlane32_swap_b32_e32 v3, v4
	s_and_saveexec_b64 s[6:7], s[2:3]
	v_add_f32_e32 v3, v3, v4
	ds_write_b32 v146, v3 offset:768
	s_or_b64 exec, exec, s[6:7]
	ds_read_b128 v[4:7], v2 offset:2048
	s_waitcnt lgkmcnt(0)
	v_max_f32_e32 v3, v7, v7
	v_max_f32_e32 v6, v6, v6
	v_max_f32_e32 v3, v6, v3
	v_max3_f32 v3, v4, v5, v3
	v_sub_f32_e32 v4, v65, v3
	v_sub_f32_e32 v5, v64, v3
	v_sub_f32_e32 v6, v63, v3
	v_sub_f32_e32 v7, v62, v3
	v_exp_f32_e32 v62, v7
	v_exp_f32_e32 v63, v6
	v_exp_f32_e32 v64, v5
	v_exp_f32_e32 v65, v4
	v_sub_f32_e32 v6, v61, v3
	v_sub_f32_e32 v7, v60, v3
	v_sub_f32_e32 v10, v59, v3
	v_sub_f32_e32 v11, v58, v3
	v_exp_f32_e32 v58, v11
	v_exp_f32_e32 v59, v10
	v_exp_f32_e32 v60, v7
	v_exp_f32_e32 v61, v6
	v_sub_f32_e32 v7, v57, v3
	v_sub_f32_e32 v56, v56, v3
	v_sub_f32_e32 v11, v55, v3
	v_sub_f32_e32 v10, v54, v3
	v_exp_f32_e32 v10, v10
	v_exp_f32_e32 v11, v11
	v_exp_f32_e32 v54, v56
	v_exp_f32_e32 v55, v7
	v_add_f32_e32 v4, v62, v63
	v_add_f32_e32 v5, v64, v65
	v_sub_f32_e32 v7, v53, v3
	v_sub_f32_e32 v52, v52, v3
	v_sub_f32_e32 v51, v51, v3
	v_sub_f32_e32 v3, v50, v3
	v_add_f32_e32 v4, v4, v5
	v_add_f32_e32 v5, v58, v59
	v_add_f32_e32 v6, v60, v61
	v_exp_f32_e32 v50, v3
	v_exp_f32_e32 v51, v51
	v_exp_f32_e32 v52, v52
	v_exp_f32_e32 v53, v7
	v_add_f32_e32 v4, 0, v4
	v_add_f32_e32 v5, v5, v6
	v_add_f32_e32 v4, v5, v4
	v_add_f32_e32 v5, v10, v11
	v_add_f32_e32 v6, v54, v55
	v_add_f32_e32 v3, v5, v6
	v_add_f32_e32 v3, v3, v4
	v_add_f32_e32 v4, v50, v51
	v_add_f32_e32 v5, v52, v53
	v_add_f32_e32 v4, v4, v5
	v_add_f32_e32 v3, v4, v3
	ds_swizzle_b32 v4, v3 offset:swizzle(SWAP,16)
	s_waitcnt lgkmcnt(0)
	v_add_f32_e32 v3, v3, v4
	v_mov_b32_e32 v4, v3
	s_nop 1
	v_permlane32_swap_b32_e32 v3, v4
	s_and_saveexec_b64 s[6:7], s[2:3]
	v_add_f32_e32 v3, v3, v4
	ds_write_b32 v146, v3 offset:2048
	s_or_b64 exec, exec, s[6:7]
	ds_read_b128 v[4:7], v2 offset:2304
	s_waitcnt lgkmcnt(0)
	v_max_f32_e32 v3, v7, v7
	v_max_f32_e32 v6, v6, v6
	v_max_f32_e32 v3, v6, v3
	v_max3_f32 v3, v4, v5, v3
	v_sub_f32_e32 v4, v49, v3
	v_sub_f32_e32 v5, v48, v3
	v_sub_f32_e32 v6, v47, v3
	v_sub_f32_e32 v7, v46, v3
	v_exp_f32_e32 v46, v7
	v_exp_f32_e32 v47, v6
	v_exp_f32_e32 v48, v5
	v_exp_f32_e32 v49, v4
	v_sub_f32_e32 v6, v45, v3
	v_sub_f32_e32 v7, v44, v3
	v_sub_f32_e32 v43, v43, v3
	v_sub_f32_e32 v42, v42, v3
	v_exp_f32_e32 v42, v42
	v_exp_f32_e32 v43, v43
	v_exp_f32_e32 v56, v7
	v_exp_f32_e32 v57, v6
	v_sub_f32_e32 v41, v41, v3
	v_sub_f32_e32 v40, v40, v3
	v_sub_f32_e32 v7, v39, v3
	v_sub_f32_e32 v6, v38, v3
	v_exp_f32_e32 v6, v6
	v_exp_f32_e32 v7, v7
	v_exp_f32_e32 v38, v40
	v_exp_f32_e32 v39, v41
	v_add_f32_e32 v4, v46, v47
	v_add_f32_e32 v5, v48, v49
	v_sub_f32_e32 v37, v37, v3
	v_sub_f32_e32 v36, v36, v3
	v_sub_f32_e32 v35, v35, v3
	v_sub_f32_e32 v3, v34, v3
	v_add_f32_e32 v4, v4, v5
	v_add_f32_e32 v5, v42, v43
	v_add_f32_e32 v44, v56, v57
	v_exp_f32_e32 v34, v3
	v_exp_f32_e32 v35, v35
	v_exp_f32_e32 v36, v36
	v_exp_f32_e32 v37, v37
	v_add_f32_e32 v4, 0, v4
	v_add_f32_e32 v5, v5, v44
	v_add_f32_e32 v4, v5, v4
	v_add_f32_e32 v5, v6, v7
	v_add_f32_e32 v40, v38, v39
	v_add_f32_e32 v3, v5, v40
	v_add_f32_e32 v3, v3, v4
	v_add_f32_e32 v4, v34, v35
	v_add_f32_e32 v5, v36, v37
	v_add_f32_e32 v4, v4, v5
	v_add_f32_e32 v3, v4, v3
	ds_swizzle_b32 v4, v3 offset:swizzle(SWAP,16)
	s_waitcnt lgkmcnt(0)
	v_add_f32_e32 v3, v3, v4
	v_mov_b32_e32 v4, v3
	s_nop 1
	v_permlane32_swap_b32_e32 v3, v4
	s_and_saveexec_b64 s[6:7], s[2:3]
	v_add_f32_e32 v3, v3, v4
	ds_write_b32 v146, v3 offset:2304
	s_or_b64 exec, exec, s[6:7]
	ds_read_b128 v[148:151], v2 offset:2560
	s_waitcnt lgkmcnt(0)
	v_max_f32_e32 v3, v151, v151
	v_max_f32_e32 v4, v150, v150
	v_max_f32_e32 v3, v4, v3
	v_max3_f32 v3, v148, v149, v3
	v_sub_f32_e32 v4, v33, v3
	v_sub_f32_e32 v5, v32, v3
	v_sub_f32_e32 v31, v31, v3
	v_sub_f32_e32 v30, v30, v3
	v_exp_f32_e32 v30, v30
	v_exp_f32_e32 v31, v31
	v_exp_f32_e32 v32, v5
	v_exp_f32_e32 v33, v4
	v_sub_f32_e32 v40, v29, v3
	v_sub_f32_e32 v41, v28, v3
	v_sub_f32_e32 v27, v27, v3
	v_sub_f32_e32 v26, v26, v3
	v_exp_f32_e32 v28, v26
	v_exp_f32_e32 v29, v27
	v_exp_f32_e32 v44, v41
	v_exp_f32_e32 v45, v40
	v_add_f32_e32 v4, v30, v31
	v_add_f32_e32 v5, v32, v33
	v_add_f32_e32 v4, v4, v5
	v_add_f32_e32 v26, 0, v4
	v_add_f32_e32 v27, v28, v29
	v_add_f32_e32 v40, v44, v45
	v_sub_f32_e32 v25, v25, v3
	v_sub_f32_e32 v24, v24, v3
	v_sub_f32_e32 v5, v23, v3
	v_sub_f32_e32 v4, v22, v3
	v_exp_f32_e32 v4, v4
	v_exp_f32_e32 v5, v5
	v_exp_f32_e32 v22, v24
	v_exp_f32_e32 v23, v25
	v_add_f32_e32 v24, v27, v40
	v_sub_f32_e32 v21, v21, v3
	v_sub_f32_e32 v20, v20, v3
	v_sub_f32_e32 v19, v19, v3
	v_sub_f32_e32 v3, v18, v3
	v_add_f32_e32 v24, v24, v26
	v_exp_f32_e32 v18, v3
	v_exp_f32_e32 v19, v19
	v_exp_f32_e32 v26, v20
	v_exp_f32_e32 v27, v21
	v_add_f32_e32 v25, v4, v5
	v_add_f32_e32 v40, v22, v23
	v_add_f32_e32 v3, v25, v40
	v_add_f32_e32 v20, v18, v19
	v_add_f32_e32 v21, v26, v27
	v_add_f32_e32 v3, v3, v24
	v_add_f32_e32 v20, v20, v21
	v_add_f32_e32 v3, v20, v3
	ds_swizzle_b32 v20, v3 offset:swizzle(SWAP,16)
	s_waitcnt lgkmcnt(0)
	v_add_f32_e32 v3, v3, v20
	v_mov_b32_e32 v20, v3
	s_nop 1
	v_permlane32_swap_b32_e32 v3, v20
	s_and_saveexec_b64 s[6:7], s[2:3]
	v_add_f32_e32 v3, v3, v20
	ds_write_b32 v146, v3 offset:2560
	s_or_b64 exec, exec, s[6:7]
	ds_read_b128 v[148:151], v2 offset:2816
	s_waitcnt lgkmcnt(0)
	v_max_f32_e32 v2, v151, v151
	v_max_f32_e32 v3, v150, v150
	v_max_f32_e32 v2, v3, v2
	v_max3_f32 v147, v148, v149, v2
	v_sub_f32_e32 v2, v17, v147
	v_sub_f32_e32 v3, v16, v147
	v_sub_f32_e32 v15, v15, v147
	v_sub_f32_e32 v14, v14, v147
	v_exp_f32_e32 v14, v14
	v_exp_f32_e32 v15, v15
	v_exp_f32_e32 v20, v3
	v_exp_f32_e32 v21, v2
	v_sub_f32_e32 v16, v133, v147
	v_sub_f32_e32 v17, v132, v147
	v_sub_f32_e32 v13, v13, v147
	v_sub_f32_e32 v12, v12, v147
	v_exp_f32_e32 v24, v12
	v_exp_f32_e32 v25, v13
	v_exp_f32_e32 v40, v17
	v_exp_f32_e32 v41, v16
	v_add_f32_e32 v2, v14, v15
	v_add_f32_e32 v3, v20, v21
	v_add_f32_e32 v2, v2, v3
	v_add_f32_e32 v12, 0, v2
	v_add_f32_e32 v13, v24, v25
	v_add_f32_e32 v16, v40, v41
	v_sub_f32_e32 v17, v137, v147
	v_sub_f32_e32 v132, v136, v147
	v_sub_f32_e32 v3, v9, v147
	v_sub_f32_e32 v2, v8, v147
	v_exp_f32_e32 v2, v2
	v_exp_f32_e32 v3, v3
	v_exp_f32_e32 v8, v132
	v_exp_f32_e32 v9, v17
	v_add_f32_e32 v13, v13, v16
	v_add_f32_e32 v132, v13, v12
	v_sub_f32_e32 v17, v139, v147
	v_sub_f32_e32 v16, v138, v147
	v_sub_f32_e32 v13, v135, v147
	v_sub_f32_e32 v12, v134, v147
	v_exp_f32_e32 v12, v12
	v_exp_f32_e32 v13, v13
	v_exp_f32_e32 v16, v16
	v_exp_f32_e32 v17, v17
	v_add_f32_e32 v133, v2, v3
	v_add_f32_e32 v136, v8, v9
	v_add_f32_e32 v133, v133, v136
	v_add_f32_e32 v132, v133, v132
	v_add_f32_e32 v133, v12, v13
	v_add_f32_e32 v134, v16, v17
	v_add_f32_e32 v133, v133, v134
	v_add_f32_e32 v132, v133, v132
	ds_swizzle_b32 v133, v132 offset:swizzle(SWAP,16)
	s_waitcnt lgkmcnt(0)
	v_add_f32_e32 v132, v132, v133
	v_mov_b32_e32 v133, v132
	s_nop 1
	v_permlane32_swap_b32_e32 v132, v133
	s_and_saveexec_b64 s[6:7], s[2:3]
	v_add_f32_e32 v132, v132, v133
	ds_write_b32 v146, v132 offset:2816
	s_or_b64 exec, exec, s[6:7]
	s_lshl_b32 s2, s16, 5
	s_or_b32 s3, s15, s2
	s_mul_i32 s6, s14, 0x180000
	s_mul_hi_i32 s2, s14, 0x180000
	s_add_u32 s4, s4, s6
	s_addc_u32 s5, s5, s2
	s_add_i32 s2, 0, 0x21000
	s_waitcnt lgkmcnt(0)
	s_barrier
	v_lshl_add_u32 v132, v130, 4, s2
	ds_read_b128 v[132:135], v132
	v_lshl_add_u32 v136, v131, 3, s3
	v_ashrrev_i32_e32 v131, 31, v130
	v_lshlrev_b64 v[130:131], 11, v[130:131]
	v_lshl_add_u64 v[130:131], s[4:5], 0, v[130:131]
	s_waitcnt lgkmcnt(0)
	v_mov_b32_e32 v138, v133
	v_mov_b32_e32 v139, v134
	v_mov_b32_e32 v133, v135
	v_pk_add_f32 v[132:133], v[138:139], v[132:133]
	v_ashrrev_i32_e32 v137, 31, v136
	v_add_f32_e32 v132, v132, v133
	v_rcp_f32_e32 v132, v132
	v_lshl_add_u64 v[130:131], v[136:137], 1, v[130:131]
	s_mov_b32 s3, 0x9800000
	s_mov_b64 s[4:5], 0x9800000
	v_pk_mul_f32 v[126:127], v[126:127], v[132:133] op_sel_hi:[1,0]
	v_pk_mul_f32 v[134:135], v[124:125], v[132:133] op_sel_hi:[1,0]
	v_pk_mul_f32 v[124:125], v[122:123], v[132:133] op_sel_hi:[1,0]
	v_cvt_pk_bf16_f32 v122, v126, v127
	v_add_co_u32_e32 v126, vcc, s3, v130
	v_pk_mul_f32 v[128:129], v[128:129], v[132:133] op_sel_hi:[1,0]
	s_nop 0
	v_addc_co_u32_e32 v127, vcc, 0, v131, vcc
	v_cvt_pk_bf16_f32 v123, v128, v129
	v_pk_mul_f32 v[118:119], v[118:119], v[132:133] op_sel_hi:[1,0]
	v_cvt_pk_bf16_f32 v124, v124, v125
	v_cvt_pk_bf16_f32 v125, v134, v135
	global_store_dwordx4 v[126:127], v[122:125], off
	v_pk_mul_f32 v[120:121], v[120:121], v[132:133] op_sel_hi:[1,0]
	s_mov_b32 s3, 0x9808000
	v_pk_mul_f32 v[122:123], v[116:117], v[132:133] op_sel_hi:[1,0]
	v_pk_mul_f32 v[116:117], v[114:115], v[132:133] op_sel_hi:[1,0]
	v_cvt_pk_bf16_f32 v114, v118, v119
	v_lshl_add_u32 v118, v140, 4, s2
	v_cvt_pk_bf16_f32 v115, v120, v121
	v_cvt_pk_bf16_f32 v116, v116, v117
	v_cvt_pk_bf16_f32 v117, v122, v123
	ds_read_b128 v[118:121], v118
	v_lshl_add_u32 v0, v0, 4, s2
	s_waitcnt lgkmcnt(0)
	v_mov_b32_e32 v122, v119
	v_mov_b32_e32 v123, v120
	v_mov_b32_e32 v119, v121
	v_pk_add_f32 v[118:119], v[122:123], v[118:119]
	v_lshl_add_u64 v[120:121], v[130:131], 0, s[4:5]
	v_add_f32_e32 v118, v118, v119
	v_rcp_f32_e32 v118, v118
	global_store_dwordx4 v[120:121], v[114:117], off offset:256
	v_pk_mul_f32 v[110:111], v[110:111], v[118:119] op_sel_hi:[1,0]
	s_nop 0
	v_pk_mul_f32 v[114:115], v[108:109], v[118:119] op_sel_hi:[1,0]
	v_pk_mul_f32 v[108:109], v[106:107], v[118:119] op_sel_hi:[1,0]
	v_cvt_pk_bf16_f32 v106, v110, v111
	v_add_co_u32_e32 v110, vcc, s3, v130
	v_pk_mul_f32 v[112:113], v[112:113], v[118:119] op_sel_hi:[1,0]
	s_nop 0
	v_addc_co_u32_e32 v111, vcc, 0, v131, vcc
	v_cvt_pk_bf16_f32 v107, v112, v113
	v_pk_mul_f32 v[102:103], v[102:103], v[118:119] op_sel_hi:[1,0]
	v_cvt_pk_bf16_f32 v108, v108, v109
	v_cvt_pk_bf16_f32 v109, v114, v115
	global_store_dwordx4 v[110:111], v[106:109], off
	v_pk_mul_f32 v[104:105], v[104:105], v[118:119] op_sel_hi:[1,0]
	s_mov_b32 s3, 0x9810000
	v_pk_mul_f32 v[106:107], v[100:101], v[118:119] op_sel_hi:[1,0]
	v_pk_mul_f32 v[100:101], v[98:99], v[118:119] op_sel_hi:[1,0]
	v_cvt_pk_bf16_f32 v98, v102, v103
	v_lshl_add_u32 v102, v141, 4, s2
	v_cvt_pk_bf16_f32 v99, v104, v105
	v_cvt_pk_bf16_f32 v100, v100, v101
	v_cvt_pk_bf16_f32 v101, v106, v107
	ds_read_b128 v[102:105], v102
	global_store_dwordx4 v[110:111], v[98:101], off offset:256
	s_waitcnt lgkmcnt(0)
	v_mov_b32_e32 v106, v103
	v_mov_b32_e32 v107, v104
	v_mov_b32_e32 v103, v105
	v_pk_add_f32 v[102:103], v[106:107], v[102:103]
	s_nop 0
	v_add_f32_e32 v102, v102, v103
	v_rcp_f32_e32 v102, v102
	s_nop 0
	v_pk_mul_f32 v[94:95], v[94:95], v[102:103] op_sel_hi:[1,0]
	v_pk_mul_f32 v[98:99], v[92:93], v[102:103] op_sel_hi:[1,0]
	v_pk_mul_f32 v[92:93], v[90:91], v[102:103] op_sel_hi:[1,0]
	v_cvt_pk_bf16_f32 v90, v94, v95
	v_add_co_u32_e32 v94, vcc, s3, v130
	v_pk_mul_f32 v[96:97], v[96:97], v[102:103] op_sel_hi:[1,0]
	s_nop 0
	v_addc_co_u32_e32 v95, vcc, 0, v131, vcc
	v_cvt_pk_bf16_f32 v91, v96, v97
	v_pk_mul_f32 v[86:87], v[86:87], v[102:103] op_sel_hi:[1,0]
	v_cvt_pk_bf16_f32 v92, v92, v93
	v_cvt_pk_bf16_f32 v93, v98, v99
	global_store_dwordx4 v[94:95], v[90:93], off
	v_pk_mul_f32 v[88:89], v[88:89], v[102:103] op_sel_hi:[1,0]
	s_mov_b32 s3, 0x9818000
	v_pk_mul_f32 v[90:91], v[84:85], v[102:103] op_sel_hi:[1,0]
	v_pk_mul_f32 v[84:85], v[82:83], v[102:103] op_sel_hi:[1,0]
	v_cvt_pk_bf16_f32 v82, v86, v87
	v_lshl_add_u32 v86, v142, 4, s2
	v_cvt_pk_bf16_f32 v83, v88, v89
	v_cvt_pk_bf16_f32 v84, v84, v85
	v_cvt_pk_bf16_f32 v85, v90, v91
	ds_read_b128 v[86:89], v86
	global_store_dwordx4 v[94:95], v[82:85], off offset:256
	s_waitcnt lgkmcnt(0)
	v_mov_b32_e32 v90, v87
	v_mov_b32_e32 v91, v88
	v_mov_b32_e32 v87, v89
	v_pk_add_f32 v[86:87], v[90:91], v[86:87]
	s_nop 0
	v_add_f32_e32 v86, v86, v87
	v_rcp_f32_e32 v86, v86
	s_nop 0
	v_pk_mul_f32 v[78:79], v[78:79], v[86:87] op_sel_hi:[1,0]
	v_pk_mul_f32 v[82:83], v[76:77], v[86:87] op_sel_hi:[1,0]
	v_pk_mul_f32 v[76:77], v[74:75], v[86:87] op_sel_hi:[1,0]
	v_cvt_pk_bf16_f32 v74, v78, v79
	v_add_co_u32_e32 v78, vcc, s3, v130
	v_pk_mul_f32 v[80:81], v[80:81], v[86:87] op_sel_hi:[1,0]
	s_nop 0
	v_addc_co_u32_e32 v79, vcc, 0, v131, vcc
	v_cvt_pk_bf16_f32 v75, v80, v81
	v_cvt_pk_bf16_f32 v76, v76, v77
	v_cvt_pk_bf16_f32 v77, v82, v83
	global_store_dwordx4 v[78:79], v[74:77], off
	v_pk_mul_f32 v[72:73], v[72:73], v[86:87] op_sel_hi:[1,0]
	v_pk_mul_f32 v[70:71], v[70:71], v[86:87] op_sel_hi:[1,0]
	v_pk_mul_f32 v[74:75], v[68:69], v[86:87] op_sel_hi:[1,0]
	v_pk_mul_f32 v[68:69], v[66:67], v[86:87] op_sel_hi:[1,0]
	v_cvt_pk_bf16_f32 v66, v70, v71
	v_cvt_pk_bf16_f32 v67, v72, v73
	s_mov_b32 s3, 0x9840000
	v_cvt_pk_bf16_f32 v68, v68, v69
	v_cvt_pk_bf16_f32 v69, v74, v75
	ds_read_b128 v[70:73], v0
	global_store_dwordx4 v[78:79], v[66:69], off offset:256
	s_waitcnt lgkmcnt(0)
	v_mov_b32_e32 v74, v71
	v_mov_b32_e32 v75, v72
	v_mov_b32_e32 v71, v73
	v_pk_add_f32 v[70:71], v[74:75], v[70:71]
	s_nop 0
	v_add_f32_e32 v0, v70, v71
	v_rcp_f32_e32 v0, v0
	s_nop 0
	v_pk_mul_f32 v[62:63], v[62:63], v[0:1] op_sel_hi:[1,0]
	v_pk_mul_f32 v[66:67], v[60:61], v[0:1] op_sel_hi:[1,0]
	v_pk_mul_f32 v[60:61], v[58:59], v[0:1] op_sel_hi:[1,0]
	v_cvt_pk_bf16_f32 v58, v62, v63
	v_add_co_u32_e32 v62, vcc, s3, v130
	v_pk_mul_f32 v[64:65], v[64:65], v[0:1] op_sel_hi:[1,0]
	s_nop 0
	v_addc_co_u32_e32 v63, vcc, 0, v131, vcc
	v_cvt_pk_bf16_f32 v59, v64, v65
	v_cvt_pk_bf16_f32 v60, v60, v61
	v_cvt_pk_bf16_f32 v61, v66, v67
	global_store_dwordx4 v[62:63], v[58:61], off
	v_pk_mul_f32 v[54:55], v[54:55], v[0:1] op_sel_hi:[1,0]
	v_pk_mul_f32 v[10:11], v[10:11], v[0:1] op_sel_hi:[1,0]
	v_pk_mul_f32 v[58:59], v[52:53], v[0:1] op_sel_hi:[1,0]
	v_pk_mul_f32 v[52:53], v[50:51], v[0:1] op_sel_hi:[1,0]
	v_lshl_add_u32 v0, v143, 4, s2
	v_cvt_pk_bf16_f32 v50, v10, v11
	v_cvt_pk_bf16_f32 v51, v54, v55
	v_cvt_pk_bf16_f32 v52, v52, v53
	v_cvt_pk_bf16_f32 v53, v58, v59
	ds_read_b128 v[58:61], v0
	s_mov_b32 s3, 0x9848000
	global_store_dwordx4 v[62:63], v[50:53], off offset:256
	s_waitcnt lgkmcnt(0)
	v_mov_b32_e32 v10, v59
	v_mov_b32_e32 v11, v60
	v_mov_b32_e32 v59, v61
	v_pk_add_f32 v[10:11], v[10:11], v[58:59]
	s_nop 0
	v_add_f32_e32 v0, v10, v11
	v_rcp_f32_e32 v0, v0
	s_nop 0
	v_pk_mul_f32 v[10:11], v[48:49], v[0:1] op_sel_hi:[1,0]
	v_pk_mul_f32 v[46:47], v[46:47], v[0:1] op_sel_hi:[1,0]
	v_pk_mul_f32 v[42:43], v[42:43], v[0:1] op_sel_hi:[1,0]
	v_cvt_pk_bf16_f32 v46, v46, v47
	v_cvt_pk_bf16_f32 v47, v10, v11
	v_add_co_u32_e32 v10, vcc, s3, v130
	v_pk_mul_f32 v[50:51], v[56:57], v[0:1] op_sel_hi:[1,0]
	v_cvt_pk_bf16_f32 v48, v42, v43
	s_nop 0
	v_addc_co_u32_e32 v11, vcc, 0, v131, vcc
	v_cvt_pk_bf16_f32 v49, v50, v51
	v_pk_mul_f32 v[38:39], v[38:39], v[0:1] op_sel_hi:[1,0]
	v_pk_mul_f32 v[6:7], v[6:7], v[0:1] op_sel_hi:[1,0]
	v_pk_mul_f32 v[42:43], v[36:37], v[0:1] op_sel_hi:[1,0]
	v_pk_mul_f32 v[36:37], v[34:35], v[0:1] op_sel_hi:[1,0]
	v_lshl_add_u32 v0, v144, 4, s2
	global_store_dwordx4 v[10:11], v[46:49], off
	v_cvt_pk_bf16_f32 v34, v6, v7
	v_cvt_pk_bf16_f32 v35, v38, v39
	v_cvt_pk_bf16_f32 v36, v36, v37
	v_cvt_pk_bf16_f32 v37, v42, v43
	ds_read_b128 v[46:49], v0
	global_store_dwordx4 v[10:11], v[34:37], off offset:256
	s_mov_b32 s3, 0x9850000
	s_waitcnt lgkmcnt(0)
	v_mov_b32_e32 v6, v47
	v_mov_b32_e32 v7, v48
	v_mov_b32_e32 v47, v49
	v_pk_add_f32 v[6:7], v[6:7], v[46:47]
	s_nop 0
	v_add_f32_e32 v0, v6, v7
	v_rcp_f32_e32 v0, v0
	s_nop 0
	v_pk_mul_f32 v[10:11], v[30:31], v[0:1] op_sel_hi:[1,0]
	v_pk_mul_f32 v[6:7], v[32:33], v[0:1] op_sel_hi:[1,0]
	v_pk_mul_f32 v[30:31], v[28:29], v[0:1] op_sel_hi:[1,0]
	v_cvt_pk_bf16_f32 v28, v10, v11
	v_add_co_u32_e32 v10, vcc, s3, v130
	v_pk_mul_f32 v[32:33], v[44:45], v[0:1] op_sel_hi:[1,0]
	v_cvt_pk_bf16_f32 v29, v6, v7
	s_nop 0
	v_addc_co_u32_e32 v11, vcc, 0, v131, vcc
	v_pk_mul_f32 v[6:7], v[22:23], v[0:1] op_sel_hi:[1,0]
	v_pk_mul_f32 v[4:5], v[4:5], v[0:1] op_sel_hi:[1,0]
	v_pk_mul_f32 v[22:23], v[26:27], v[0:1] op_sel_hi:[1,0]
	v_pk_mul_f32 v[18:19], v[18:19], v[0:1] op_sel_hi:[1,0]
	v_lshl_add_u32 v0, v145, 4, s2
	v_cvt_pk_bf16_f32 v30, v30, v31
	v_cvt_pk_bf16_f32 v31, v32, v33
	global_store_dwordx4 v[10:11], v[28:31], off
	v_cvt_pk_bf16_f32 v4, v4, v5
	v_cvt_pk_bf16_f32 v5, v6, v7
	v_cvt_pk_bf16_f32 v6, v18, v19
	v_cvt_pk_bf16_f32 v7, v22, v23
	ds_read_b128 v[26:29], v0
	global_store_dwordx4 v[10:11], v[4:7], off offset:256
	s_mov_b32 s2, 0x9858000
	s_waitcnt lgkmcnt(0)
	v_mov_b32_e32 v18, v27
	v_mov_b32_e32 v19, v28
	v_mov_b32_e32 v27, v29
	v_pk_add_f32 v[18:19], v[18:19], v[26:27]
	s_nop 0
	v_add_f32_e32 v0, v18, v19
	v_rcp_f32_e32 v0, v0
	s_nop 0
	v_pk_mul_f32 v[6:7], v[20:21], v[0:1] op_sel_hi:[1,0]
	v_pk_mul_f32 v[4:5], v[14:15], v[0:1] op_sel_hi:[1,0]
	v_pk_mul_f32 v[10:11], v[40:41], v[0:1] op_sel_hi:[1,0]
	v_pk_mul_f32 v[14:15], v[24:25], v[0:1] op_sel_hi:[1,0]
	v_cvt_pk_bf16_f32 v4, v4, v5
	v_cvt_pk_bf16_f32 v5, v6, v7
	v_pk_mul_f32 v[2:3], v[2:3], v[0:1] op_sel_hi:[1,0]
	v_cvt_pk_bf16_f32 v6, v14, v15
	v_cvt_pk_bf16_f32 v7, v10, v11
	v_add_co_u32_e32 v10, vcc, s2, v130
	s_nop 1
	v_addc_co_u32_e32 v11, vcc, 0, v131, vcc
	global_store_dwordx4 v[10:11], v[4:7], off
	v_cvt_pk_bf16_f32 v2, v2, v3
	s_nop 1
	v_pk_mul_f32 v[4:5], v[8:9], v[0:1] op_sel_hi:[1,0]
	v_pk_mul_f32 v[6:7], v[16:17], v[0:1] op_sel_hi:[1,0]
	v_pk_mul_f32 v[8:9], v[12:13], v[0:1] op_sel_hi:[1,0]
	v_cvt_pk_bf16_f32 v3, v4, v5
	s_nop 0
	v_cvt_pk_bf16_f32 v4, v8, v9
	v_cvt_pk_bf16_f32 v5, v6, v7
	global_store_dwordx4 v[10:11], v[2:5], off offset:256

.LBB0_1743:
	s_or_b64 exec, exec, s[14:15]
	s_waitcnt lgkmcnt(0)
	s_barrier
	s_branch .LBB0_1800

.LBB0_1807:
	s_add_u32 s68, s4, s14
	s_addc_u32 s69, s5, s15
	s_add_u32 s16, s68, 0x100
	s_addc_u32 s17, s69, 0
	s_add_u32 s22, s50, s14
	s_addc_u32 s23, s51, s15
	s_add_i32 s67, 0, 0x10000
	s_cmp_eq_u32 s66, 12
	s_cselect_b32 s17, s5, s17
	s_cselect_b32 s16, s4, s16
	v_add_u32_e32 v0, s67, v126
	s_cselect_b32 s23, s13, s23
	s_cselect_b32 s22, s12, s22
	s_add_i32 s70, 0, 0x14000
	ds_read_b128 v[128:131], v0
	ds_read_b128 v[142:145], v0 offset:1024
	ds_read_b128 v[146:149], v0 offset:2048
	ds_read_b128 v[150:153], v0 offset:3072
	ds_read_b128 v[154:157], v0 offset:16384
	ds_read_b128 v[160:163], v0 offset:17408
	ds_read_b128 v[164:167], v0 offset:18432
	ds_read_b128 v[168:171], v0 offset:19456
	ds_read_b128 v[172:175], v127
	ds_read_b128 v[176:179], v127 offset:1024
	ds_read_b128 v[180:183], v127 offset:2048
	ds_read_b128 v[184:187], v127 offset:3072
	ds_read_b128 v[188:191], v127 offset:4096
	ds_read_b128 v[192:195], v127 offset:5120
	ds_read_b128 v[196:199], v127 offset:6144
	ds_read_b128 v[200:203], v127 offset:7168
	s_add_i32 m0, s43, 0xc000
	s_add_u32 s100, s68, s56
	s_addc_u32 s101, s69, s57
	global_load_lds_dwordx4 v122, s[100:101]
	s_add_i32 m0, s43, 0xe000
	s_nop 0
	global_load_lds_dwordx4 v123, s[100:101]
	s_waitcnt vmcnt(8)
	s_waitcnt lgkmcnt(0)
	s_barrier
	s_setprio 1
	s_waitcnt lgkmcnt(0)
	v_mfma_f32_16x16x32_bf16 v[138:141], v[128:131], v[172:175], v[138:141]
	v_mfma_f32_16x16x32_bf16 v[132:135], v[146:149], v[172:175], v[134:137]
	v_mfma_f32_16x16x32_bf16 v[110:113], v[128:131], v[180:183], v[110:113]
	v_mfma_f32_16x16x32_bf16 v[106:109], v[146:149], v[180:183], v[106:109]
	v_mfma_f32_16x16x32_bf16 v[94:97], v[128:131], v[188:191], v[94:97]
	v_mfma_f32_16x16x32_bf16 v[90:93], v[146:149], v[188:191], v[90:93]
	v_mfma_f32_16x16x32_bf16 v[78:81], v[128:131], v[196:199], v[78:81]
	v_mfma_f32_16x16x32_bf16 v[74:77], v[146:149], v[196:199], v[74:77]
	v_mfma_f32_16x16x32_bf16 v[138:141], v[142:145], v[176:179], v[138:141]
	v_mfma_f32_16x16x32_bf16 v[132:135], v[150:153], v[176:179], v[132:135]
	v_mfma_f32_16x16x32_bf16 v[110:113], v[142:145], v[184:187], v[110:113]
	v_mfma_f32_16x16x32_bf16 v[106:109], v[150:153], v[184:187], v[106:109]
	v_mfma_f32_16x16x32_bf16 v[94:97], v[142:145], v[192:195], v[94:97]
	v_mfma_f32_16x16x32_bf16 v[90:93], v[150:153], v[192:195], v[90:93]
	v_mfma_f32_16x16x32_bf16 v[78:81], v[142:145], v[200:203], v[78:81]
	v_mfma_f32_16x16x32_bf16 v[74:77], v[150:153], v[200:203], v[74:77]
	s_setprio 0
	s_setprio 1
	v_mfma_f32_16x16x32_bf16 v[118:121], v[154:157], v[172:175], v[118:121]
	v_mfma_f32_16x16x32_bf16 v[114:117], v[164:167], v[172:175], v[114:117]
	v_mfma_f32_16x16x32_bf16 v[102:105], v[154:157], v[180:183], v[102:105]
	v_mfma_f32_16x16x32_bf16 v[98:101], v[164:167], v[180:183], v[98:101]
	v_mfma_f32_16x16x32_bf16 v[86:89], v[154:157], v[188:191], v[86:89]
	v_mfma_f32_16x16x32_bf16 v[82:85], v[164:167], v[188:191], v[82:85]
	v_mfma_f32_16x16x32_bf16 v[70:73], v[154:157], v[196:199], v[70:73]
	v_mfma_f32_16x16x32_bf16 v[66:69], v[164:167], v[196:199], v[66:69]
	v_mfma_f32_16x16x32_bf16 v[118:121], v[160:163], v[176:179], v[118:121]
	v_mfma_f32_16x16x32_bf16 v[114:117], v[168:171], v[176:179], v[114:117]
	v_mfma_f32_16x16x32_bf16 v[102:105], v[160:163], v[184:187], v[102:105]
	v_mfma_f32_16x16x32_bf16 v[98:101], v[168:171], v[184:187], v[98:101]
	v_mfma_f32_16x16x32_bf16 v[86:89], v[160:163], v[192:195], v[86:89]
	v_mfma_f32_16x16x32_bf16 v[82:85], v[168:171], v[192:195], v[82:85]
	v_mfma_f32_16x16x32_bf16 v[70:73], v[160:163], v[200:203], v[70:73]
	v_mfma_f32_16x16x32_bf16 v[66:69], v[168:171], v[200:203], v[66:69]
	s_setprio 0
	s_barrier
	s_add_i32 s67, s67, s42
	ds_read_b128 v[172:175], v127 offset:16384
	ds_read_b128 v[176:179], v127 offset:17408
	ds_read_b128 v[180:183], v127 offset:18432
	ds_read_b128 v[184:187], v127 offset:19456
	ds_read_b128 v[188:191], v127 offset:20480
	ds_read_b128 v[192:195], v127 offset:21504
	ds_read_b128 v[196:199], v127 offset:22528
	ds_read_b128 v[200:203], v127 offset:23552
	s_mov_b32 m0, s67
	s_nop 0
	global_load_lds_dwordx4 v124, s[22:23]
	s_add_i32 m0, s67, 0x2000
	s_add_u32 s68, s22, 0x40000
	global_load_lds_dwordx4 v125, s[22:23]
	s_addc_u32 s69, s23, 0
	s_add_i32 s67, s70, s42
	s_mov_b32 m0, s67
	s_nop 0
	global_load_lds_dwordx4 v124, s[68:69]
	s_add_i32 m0, s67, 0x2000
	s_nop 0
	global_load_lds_dwordx4 v125, s[68:69]
	s_mov_b32 m0, s43
	s_nop 0
	global_load_lds_dwordx4 v122, s[16:17]
	s_mov_b32 m0, s46
	s_nop 0
	global_load_lds_dwordx4 v123, s[16:17]
	s_waitcnt vmcnt(8)
	s_waitcnt lgkmcnt(0)
	s_barrier
	s_setprio 1
	s_waitcnt lgkmcnt(0)
	v_mfma_f32_16x16x32_bf16 v[62:65], v[128:131], v[172:175], v[62:65]
	v_mfma_f32_16x16x32_bf16 v[58:61], v[146:149], v[172:175], v[58:61]
	v_mfma_f32_16x16x32_bf16 v[46:49], v[128:131], v[180:183], v[46:49]
	v_mfma_f32_16x16x32_bf16 v[42:45], v[146:149], v[180:183], v[42:45]
	v_mfma_f32_16x16x32_bf16 v[30:33], v[128:131], v[188:191], v[30:33]
	v_mfma_f32_16x16x32_bf16 v[26:29], v[146:149], v[188:191], v[26:29]
	v_mfma_f32_16x16x32_bf16 v[14:17], v[128:131], v[196:199], v[14:17]
	v_mfma_f32_16x16x32_bf16 v[10:13], v[146:149], v[196:199], v[10:13]
	v_mfma_f32_16x16x32_bf16 v[62:65], v[142:145], v[176:179], v[62:65]
	v_mfma_f32_16x16x32_bf16 v[58:61], v[150:153], v[176:179], v[58:61]
	v_mfma_f32_16x16x32_bf16 v[46:49], v[142:145], v[184:187], v[46:49]
	v_mfma_f32_16x16x32_bf16 v[42:45], v[150:153], v[184:187], v[42:45]
	v_mfma_f32_16x16x32_bf16 v[30:33], v[142:145], v[192:195], v[30:33]
	v_mfma_f32_16x16x32_bf16 v[26:29], v[150:153], v[192:195], v[26:29]
	v_mfma_f32_16x16x32_bf16 v[14:17], v[142:145], v[200:203], v[14:17]
	v_mfma_f32_16x16x32_bf16 v[10:13], v[150:153], v[200:203], v[10:13]
	s_setprio 0
	s_setprio 1
	v_mfma_f32_16x16x32_bf16 v[54:57], v[154:157], v[172:175], v[54:57]
	v_mfma_f32_16x16x32_bf16 v[50:53], v[164:167], v[172:175], v[50:53]
	v_mfma_f32_16x16x32_bf16 v[38:41], v[154:157], v[180:183], v[38:41]
	v_mfma_f32_16x16x32_bf16 v[34:37], v[164:167], v[180:183], v[34:37]
	v_mfma_f32_16x16x32_bf16 v[22:25], v[154:157], v[188:191], v[22:25]
	v_mfma_f32_16x16x32_bf16 v[18:21], v[164:167], v[188:191], v[18:21]
	v_mfma_f32_16x16x32_bf16 v[6:9], v[154:157], v[196:199], v[6:9]
	v_mfma_f32_16x16x32_bf16 v[2:5], v[164:167], v[196:199], v[2:5]
	v_mfma_f32_16x16x32_bf16 v[54:57], v[160:163], v[176:179], v[54:57]
	v_mfma_f32_16x16x32_bf16 v[50:53], v[168:171], v[176:179], v[50:53]
	v_mfma_f32_16x16x32_bf16 v[38:41], v[160:163], v[184:187], v[38:41]
	v_mfma_f32_16x16x32_bf16 v[34:37], v[168:171], v[184:187], v[34:37]
	v_mfma_f32_16x16x32_bf16 v[22:25], v[160:163], v[192:195], v[22:25]
	v_mfma_f32_16x16x32_bf16 v[18:21], v[168:171], v[192:195], v[18:21]
	v_mfma_f32_16x16x32_bf16 v[6:9], v[160:163], v[200:203], v[6:9]
	v_mfma_f32_16x16x32_bf16 v[2:5], v[168:171], v[200:203], v[2:5]
	s_setprio 0
	s_barrier
	s_add_i32 s67, 0, 0x18000
	s_add_i32 s70, 0, 0x1c000
	ds_read_b128 v[128:131], v0 offset:32768
	ds_read_b128 v[142:145], v0 offset:33792
	ds_read_b128 v[146:149], v0 offset:34816
	ds_read_b128 v[150:153], v0 offset:35840
	ds_read_b128 v[154:157], v0 offset:49152
	ds_read_b128 v[160:163], v0 offset:50176
	ds_read_b128 v[164:167], v0 offset:51200
	ds_read_b128 v[168:171], v0 offset:52224
	s_add_u32 s68, s16, 0x40000
	s_mov_b32 m0, s47
	ds_read_b128 v[172:175], v127 offset:32768
	ds_read_b128 v[176:179], v127 offset:33792
	ds_read_b128 v[180:183], v127 offset:34816
	ds_read_b128 v[184:187], v127 offset:35840
	ds_read_b128 v[188:191], v127 offset:36864
	ds_read_b128 v[192:195], v127 offset:37888
	ds_read_b128 v[196:199], v127 offset:38912
	ds_read_b128 v[200:203], v127 offset:39936
	s_addc_u32 s69, s17, 0
	s_nop 0
	global_load_lds_dwordx4 v122, s[68:69]
	s_mov_b32 m0, s48
	s_nop 0
	global_load_lds_dwordx4 v123, s[68:69]
	s_waitcnt vmcnt(8)
	s_waitcnt lgkmcnt(0)
	s_barrier
	s_setprio 1
	s_waitcnt lgkmcnt(0)
	v_mfma_f32_16x16x32_bf16 v[136:139], v[128:131], v[172:175], v[138:141]
	v_mfma_f32_16x16x32_bf16 v[132:135], v[146:149], v[172:175], v[132:135]
	v_mfma_f32_16x16x32_bf16 v[110:113], v[128:131], v[180:183], v[110:113]
	v_mfma_f32_16x16x32_bf16 v[106:109], v[146:149], v[180:183], v[106:109]
	v_mfma_f32_16x16x32_bf16 v[94:97], v[128:131], v[188:191], v[94:97]
	v_mfma_f32_16x16x32_bf16 v[90:93], v[146:149], v[188:191], v[90:93]
	v_mfma_f32_16x16x32_bf16 v[78:81], v[128:131], v[196:199], v[78:81]
	v_mfma_f32_16x16x32_bf16 v[74:77], v[146:149], v[196:199], v[74:77]
	v_mfma_f32_16x16x32_bf16 v[138:141], v[142:145], v[176:179], v[136:139]
	v_mfma_f32_16x16x32_bf16 v[134:137], v[150:153], v[176:179], v[132:135]
	v_mfma_f32_16x16x32_bf16 v[110:113], v[142:145], v[184:187], v[110:113]
	v_mfma_f32_16x16x32_bf16 v[106:109], v[150:153], v[184:187], v[106:109]
	v_mfma_f32_16x16x32_bf16 v[94:97], v[142:145], v[192:195], v[94:97]
	v_mfma_f32_16x16x32_bf16 v[90:93], v[150:153], v[192:195], v[90:93]
	v_mfma_f32_16x16x32_bf16 v[78:81], v[142:145], v[200:203], v[78:81]
	v_mfma_f32_16x16x32_bf16 v[74:77], v[150:153], v[200:203], v[74:77]
	s_setprio 0
	s_setprio 1
	v_mfma_f32_16x16x32_bf16 v[118:121], v[154:157], v[172:175], v[118:121]
	v_mfma_f32_16x16x32_bf16 v[114:117], v[164:167], v[172:175], v[114:117]
	v_mfma_f32_16x16x32_bf16 v[102:105], v[154:157], v[180:183], v[102:105]
	v_mfma_f32_16x16x32_bf16 v[98:101], v[164:167], v[180:183], v[98:101]
	v_mfma_f32_16x16x32_bf16 v[86:89], v[154:157], v[188:191], v[86:89]
	v_mfma_f32_16x16x32_bf16 v[82:85], v[164:167], v[188:191], v[82:85]
	v_mfma_f32_16x16x32_bf16 v[70:73], v[154:157], v[196:199], v[70:73]
	v_mfma_f32_16x16x32_bf16 v[66:69], v[164:167], v[196:199], v[66:69]
	v_mfma_f32_16x16x32_bf16 v[118:121], v[160:163], v[176:179], v[118:121]
	v_mfma_f32_16x16x32_bf16 v[114:117], v[168:171], v[176:179], v[114:117]
	v_mfma_f32_16x16x32_bf16 v[102:105], v[160:163], v[184:187], v[102:105]
	v_mfma_f32_16x16x32_bf16 v[98:101], v[168:171], v[184:187], v[98:101]
	v_mfma_f32_16x16x32_bf16 v[86:89], v[160:163], v[192:195], v[86:89]
	v_mfma_f32_16x16x32_bf16 v[82:85], v[168:171], v[192:195], v[82:85]
	v_mfma_f32_16x16x32_bf16 v[70:73], v[160:163], v[200:203], v[70:73]
	v_mfma_f32_16x16x32_bf16 v[66:69], v[168:171], v[200:203], v[66:69]
	s_setprio 0
	s_barrier
	ds_read_b128 v[172:175], v127 offset:49152
	ds_read_b128 v[176:179], v127 offset:50176
	ds_read_b128 v[180:183], v127 offset:51200
	ds_read_b128 v[184:187], v127 offset:52224
	ds_read_b128 v[188:191], v127 offset:53248
	ds_read_b128 v[192:195], v127 offset:54272
	ds_read_b128 v[196:199], v127 offset:55296
	ds_read_b128 v[200:203], v127 offset:56320
	s_add_i32 s67, s67, s42
	s_add_u32 s100, s22, s38
	s_addc_u32 s101, s23, s39
	s_mov_b32 m0, s67
	s_nop 0
	global_load_lds_dwordx4 v124, s[100:101]
	s_add_i32 m0, s67, 0x2000
	s_nop 0
	s_add_u32 s22, s22, 0x40080
	s_addc_u32 s23, s23, 0
	s_add_i32 s67, s70, s42
	global_load_lds_dwordx4 v125, s[100:101]
	s_mov_b32 m0, s67
	s_nop 0
	global_load_lds_dwordx4 v124, s[22:23]
	s_add_i32 m0, s67, 0x2000
	s_nop 0
	global_load_lds_dwordx4 v125, s[22:23]
	s_mov_b32 m0, s64
	s_add_u32 s100, s16, s38
	s_addc_u32 s101, s17, s39
	v_mov_b32_e32 v0, v123
	global_load_lds_dwordx4 v122, s[100:101]
	s_mov_b32 m0, s65
	s_nop 0
	global_load_lds_dwordx4 v123, s[100:101]
	s_waitcnt vmcnt(8)
	s_waitcnt lgkmcnt(0)
	s_barrier
	s_setprio 1
	s_waitcnt lgkmcnt(0)
	v_mfma_f32_16x16x32_bf16 v[62:65], v[128:131], v[172:175], v[62:65]
	v_mfma_f32_16x16x32_bf16 v[58:61], v[146:149], v[172:175], v[58:61]
	v_mfma_f32_16x16x32_bf16 v[46:49], v[128:131], v[180:183], v[46:49]
	v_mfma_f32_16x16x32_bf16 v[42:45], v[146:149], v[180:183], v[42:45]
	v_mfma_f32_16x16x32_bf16 v[30:33], v[128:131], v[188:191], v[30:33]
	v_mfma_f32_16x16x32_bf16 v[26:29], v[146:149], v[188:191], v[26:29]
	v_mfma_f32_16x16x32_bf16 v[14:17], v[128:131], v[196:199], v[14:17]
	v_mfma_f32_16x16x32_bf16 v[10:13], v[146:149], v[196:199], v[10:13]
	v_mfma_f32_16x16x32_bf16 v[62:65], v[142:145], v[176:179], v[62:65]
	v_mfma_f32_16x16x32_bf16 v[58:61], v[150:153], v[176:179], v[58:61]
	v_mfma_f32_16x16x32_bf16 v[46:49], v[142:145], v[184:187], v[46:49]
	v_mfma_f32_16x16x32_bf16 v[42:45], v[150:153], v[184:187], v[42:45]
	v_mfma_f32_16x16x32_bf16 v[30:33], v[142:145], v[192:195], v[30:33]
	v_mfma_f32_16x16x32_bf16 v[26:29], v[150:153], v[192:195], v[26:29]
	v_mfma_f32_16x16x32_bf16 v[14:17], v[142:145], v[200:203], v[14:17]
	v_mfma_f32_16x16x32_bf16 v[10:13], v[150:153], v[200:203], v[10:13]
	s_setprio 0
	s_setprio 1
	v_mfma_f32_16x16x32_bf16 v[54:57], v[154:157], v[172:175], v[54:57]
	v_mfma_f32_16x16x32_bf16 v[50:53], v[164:167], v[172:175], v[50:53]
	v_mfma_f32_16x16x32_bf16 v[38:41], v[154:157], v[180:183], v[38:41]
	v_mfma_f32_16x16x32_bf16 v[34:37], v[164:167], v[180:183], v[34:37]
	v_mfma_f32_16x16x32_bf16 v[22:25], v[154:157], v[188:191], v[22:25]
	v_mfma_f32_16x16x32_bf16 v[18:21], v[164:167], v[188:191], v[18:21]
	v_mfma_f32_16x16x32_bf16 v[6:9], v[154:157], v[196:199], v[6:9]
	v_mfma_f32_16x16x32_bf16 v[2:5], v[164:167], v[196:199], v[2:5]
	v_mfma_f32_16x16x32_bf16 v[54:57], v[160:163], v[176:179], v[54:57]
	v_mfma_f32_16x16x32_bf16 v[50:53], v[168:171], v[176:179], v[50:53]
	v_mfma_f32_16x16x32_bf16 v[38:41], v[160:163], v[184:187], v[38:41]
	v_mfma_f32_16x16x32_bf16 v[34:37], v[168:171], v[184:187], v[34:37]
	v_mfma_f32_16x16x32_bf16 v[22:25], v[160:163], v[192:195], v[22:25]
	v_mfma_f32_16x16x32_bf16 v[18:21], v[168:171], v[192:195], v[18:21]
	v_mfma_f32_16x16x32_bf16 v[6:9], v[160:163], v[200:203], v[6:9]
	v_mfma_f32_16x16x32_bf16 v[2:5], v[168:171], v[200:203], v[2:5]
	s_setprio 0
	s_barrier
	s_add_i32 s66, s66, 2
	s_add_u32 s14, s14, 0x100
	s_addc_u32 s15, s15, 0
	s_cmp_gt_u32 s66, 13
	s_cbranch_scc0 .LBB0_1807
.LBB0_1810:
	s_add_u32 s16, s8, 0x6400000
	s_addc_u32 s17, s9, 0
	s_add_u32 s12, s8, 0x6300000
	s_addc_u32 s13, s9, 0
	s_add_u32 s14, s8, 0xfa00000
	s_addc_u32 s15, s9, 0
	s_add_i32 s5, s25, s49
	s_lshl_b32 s4, s61, 5
	s_nop 0
	v_add_u32_e32 v166, s5, v159
	s_lshl_b32 s5, s60, 8
	s_or_b32 s4, s5, s4
	v_lshl_add_u32 v168, v158, 3, s4
	v_ashrrev_i32_e32 v169, 31, v168
	v_lshlrev_b64 v[180:181], 1, v[168:169]
	v_ashrrev_i32_e32 v167, 31, v166
	v_lshl_add_u64 v[184:185], s[16:17], 0, v[180:181]
	v_lshlrev_b64 v[182:183], 11, v[166:167]
	v_lshl_add_u64 v[122:123], v[184:185], 0, v[182:183]
	global_load_dwordx4 v[176:179], v[122:123], off sc1
	global_load_dwordx4 v[154:157], v[122:123], off offset:256 sc1
	v_add_u32_e32 v164, 16, v166
	v_ashrrev_i32_e32 v165, 31, v164
	v_add_u32_e32 v162, 32, v166
	v_lshlrev_b64 v[172:173], 11, v[164:165]
	v_ashrrev_i32_e32 v163, 31, v162
	v_add_u32_e32 v160, 48, v166
	v_lshl_add_u64 v[122:123], v[184:185], 0, v[172:173]
	v_lshlrev_b64 v[170:171], 11, v[162:163]
	v_ashrrev_i32_e32 v161, 31, v160
	global_load_dwordx4 v[150:153], v[122:123], off sc1
	global_load_dwordx4 v[146:149], v[122:123], off offset:256 sc1
	v_lshl_add_u64 v[122:123], v[184:185], 0, v[170:171]
	v_lshlrev_b64 v[174:175], 11, v[160:161]
	global_load_dwordx4 v[142:145], v[122:123], off sc1
	global_load_dwordx4 v[130:133], v[122:123], off offset:256 sc1
	v_lshl_add_u64 v[122:123], v[184:185], 0, v[174:175]
	global_load_dwordx4 v[126:129], v[122:123], off sc1
	s_nop 0
	global_load_dwordx4 v[122:125], v[122:123], off offset:256 sc1
	v_cmp_eq_u32_e64 s[4:5], 0, v158
	s_cmpk_lt_u32 s26, 0x100
	s_cbranch_scc0 .Lepi_lead_r7
	s_barrier
.Lepi_lead_r7:
	s_waitcnt vmcnt(0)
	v_lshlrev_b32_e32 v186, 16, v176
	v_and_b32_e32 v187, 0xffff0000, v176
	v_lshlrev_b32_e32 v176, 16, v177
	v_and_b32_e32 v177, 0xffff0000, v177
	v_pk_add_f32 v[140:141], v[140:141], v[176:177]
	v_lshl_add_u64 v[176:177], s[16:17], 0, v[182:183]
	v_lshlrev_b32_e32 v188, 16, v178
	v_and_b32_e32 v189, 0xffff0000, v178
	v_lshlrev_b32_e32 v178, 16, v179
	v_and_b32_e32 v179, 0xffff0000, v179
	v_pk_add_f32 v[138:139], v[138:139], v[186:187]
	v_lshl_add_u64 v[180:181], v[176:177], 0, v[180:181]
	v_cvt_pk_bf16_f32 v176, v138, v139
	v_pk_add_f32 v[136:137], v[136:137], v[178:179]
	v_pk_add_f32 v[134:135], v[134:135], v[188:189]
	v_cvt_pk_bf16_f32 v177, v140, v141
	v_mul_f32_e32 v0, v139, v139
	v_cvt_pk_bf16_f32 v178, v134, v135
	v_cvt_pk_bf16_f32 v179, v136, v137
	global_store_dwordx4 v[180:181], v[176:179], off
	v_fmac_f32_e32 v0, v138, v138
	s_nop 0
	v_mul_f32_e32 v176, v141, v141
	v_fmac_f32_e32 v176, v140, v140
	v_add_f32_e32 v0, v0, v176
	v_mul_f32_e32 v176, v135, v135
	v_fmac_f32_e32 v176, v134, v134
	v_add_f32_e32 v0, v176, v0
	v_mul_f32_e32 v176, v137, v137
	v_fmac_f32_e32 v176, v136, v136
	v_add_f32_e32 v0, v176, v0
	v_max_f32_e64 v176, |v138|, |v139|
	v_max_f32_e64 v177, |v140|, |v141|
	v_max3_f32 v182, v176, 0, v177
	v_max_f32_e64 v176, |v136|, |v137|
	v_max3_f32 v183, |v134|, |v135|, v176
	v_lshlrev_b32_e32 v176, 16, v154
	v_and_b32_e32 v177, 0xffff0000, v154
	v_lshlrev_b32_e32 v154, 16, v155
	v_and_b32_e32 v155, 0xffff0000, v155
	v_lshlrev_b32_e32 v178, 16, v156
	v_and_b32_e32 v179, 0xffff0000, v156
	v_lshlrev_b32_e32 v156, 16, v157
	v_and_b32_e32 v157, 0xffff0000, v157
	v_pk_add_f32 v[120:121], v[120:121], v[154:155]
	v_pk_add_f32 v[118:119], v[118:119], v[176:177]
	v_pk_add_f32 v[116:117], v[116:117], v[156:157]
	v_cvt_pk_bf16_f32 v154, v118, v119
	v_cvt_pk_bf16_f32 v155, v120, v121
	v_pk_add_f32 v[114:115], v[114:115], v[178:179]
	v_lshlrev_b64 v[178:179], 6, v[166:167]
	v_cvt_pk_bf16_f32 v156, v114, v115
	v_cvt_pk_bf16_f32 v157, v116, v117
	global_store_dwordx4 v[180:181], v[154:157], off offset:256
	s_nop 1
	v_mul_f32_e32 v154, v119, v119
	v_mul_f32_e32 v155, v121, v121
	v_fmac_f32_e32 v154, v118, v118
	v_fmac_f32_e32 v155, v120, v120
	v_add_f32_e32 v154, v154, v155
	v_mul_f32_e32 v155, v115, v115
	v_fmac_f32_e32 v155, v114, v114
	v_add_f32_e32 v154, v155, v154
	v_mul_f32_e32 v155, v117, v117
	v_fmac_f32_e32 v155, v116, v116
	v_add_f32_e32 v154, v155, v154
	v_add_f32_e32 v0, v0, v154
	v_max_f32_e64 v154, |v118|, |v119|
	v_max_f32_e64 v156, |v116|, |v117|
	v_max3_f32 v154, v182, v183, v154
	v_max_f32_e64 v155, |v120|, |v121|
	v_max3_f32 v156, |v114|, |v115|, v156
	v_max3_f32 v155, v154, v155, v156
	ds_swizzle_b32 v156, v155 offset:swizzle(SWAP,16)
	ds_swizzle_b32 v154, v0 offset:swizzle(SWAP,16)
	s_waitcnt lgkmcnt(1)
	v_max_f32_e32 v156, v156, v156
	s_waitcnt lgkmcnt(0)
	v_add_f32_e32 v0, v0, v154
	v_max_f32_e32 v155, v155, v156
	v_mov_b32_e32 v154, v0
	v_mov_b32_e32 v156, v155
	s_nop 0
	v_permlane32_swap_b32_e32 v0, v154
	v_permlane32_swap_b32_e32 v155, v156
	s_and_saveexec_b64 s[22:23], s[4:5]
	s_cbranch_execz .LBB0_1812
	s_lshl_b32 s42, s60, 2
	v_max_f32_e32 v155, v155, v155
	v_max_f32_e32 v156, v156, v156
	s_ashr_i32 s43, s42, 31
	v_max_f32_e32 v156, v155, v156
	v_add_f32_e32 v0, v0, v154
	v_lshl_add_u64 v[154:155], s[12:13], 0, v[178:179]
	s_lshl_b64 s[42:43], s[42:43], 2
	v_lshl_add_u64 v[154:155], v[154:155], 0, s[42:43]
	s_lshl_b32 s26, s61, 2
	v_lshl_add_u64 v[154:155], v[154:155], 0, s[26:27]
	global_store_dword v[154:155], v0, off
	v_lshl_add_u64 v[154:155], s[14:15], 0, v[178:179]
	v_lshl_add_u64 v[154:155], v[154:155], 0, s[42:43]
	v_lshl_add_u64 v[154:155], v[154:155], 0, s[26:27]
	global_store_dword v[154:155], v156, off
